# v13 + first 2 MFMAs of each K-loop phase issued before the barrier (register-only ops; fills barrier-transition bubble)
# speedup vs baseline: 1.0052x; 1.0052x over previous
; #define PG8_STAGE(bufoff, gbase, voff) do { _Pragma("unroll") for (int _i = 0; _i < 2; ++_i) \
;         __builtin_amdgcn_global_load_lds((const unsigned*)((const char*)(gbase) + (voff)[_i]), (LAS unsigned*)(lds + (bufoff) + ldsw + _i * 8192), 16, 0, 0); } while (0)
; #define PG8_LDA(dst, b, h) do { _Pragma("unroll") for (int m = 0; m < 4; ++m) _Pragma("unroll") for (int k = 0; k < 2; ++k) dst[m][k] = *(const LAS bf16x8*)(lds + PG8_SA(b, h) + aoff + m * 2048 + k * 1024); } while (0)
; #define PG8_LDB(dst, b, h) do { _Pragma("unroll") for (int n = 0; n < 2; ++n) _Pragma("unroll") for (int k = 0; k < 2; ++k) dst[n][k] = *(const LAS bf16x8*)(lds + PG8_SB(b, h) + boff + n * 2048 + k * 1024); } while (0)
; #define PG8_MMA(ai, bj, At, Bt) do { __builtin_amdgcn_s_setprio(1); _Pragma("unroll") for (int m = 0; m < 4; ++m) _Pragma("unroll") for (int n = 0; n < 2; ++n) _Pragma("unroll") for (int k = 0; k < 2; ++k) \
;         acc[ai][bj][m][n] = __builtin_amdgcn_mfma_f32_16x16x32_bf16(Bt[n][k], At[m][k], acc[ai][bj][m][n], 0, 0, 0); __builtin_amdgcn_s_setprio(0); } while (0)
; #define PG8_WAIT_V(n) asm volatile("s_waitcnt vmcnt(" #n ")" ::: "memory")
; #define PG8_WAIT_L(n) asm volatile("s_waitcnt lgkmcnt(" #n ")" ::: "memory")
; #define PG8_BAR __builtin_amdgcn_s_barrier()
; #define PG8_SCHED __builtin_amdgcn_sched_barrier(0)
; template <class Epi, class Sched>
; __device__ __forceinline__ void gemm_phase(LAS unsigned char* lds, const Gemm g, const Sched& S, const Epi& E) {
;     ...
;         for (int t = 0; t < nt; t += 2) {
;             const bool last = (t == nt - 2);
;             const char* a1 = cA + (size_t)(t + 1) * kstep;
;             const char* a2 = last ? nA : cA + (size_t)(t + 2) * kstep; const char* b2 = last ? nB : cB + (size_t)(t + 2) * kstep;
;             const char* a3 = a2 + kstep; const char* b3 = b2 + kstep;
;             PG8_LDB(B0, 0, 0); PG8_LDB(B1, 0, 1); PG8_SCHED; PG8_LDA(At, 0, 0); PG8_STAGE(PG8_SA(1, 1), a1 + hstepA, voffA);
;             PG8_WAIT_V(8); PG8_WAIT_L(0); PG8_BAR; PG8_MMA(0, 0, At, B0); PG8_MMA(0, 1, At, B1); PG8_BAR; PG8_SCHED;
;             PG8_LDA(At, 0, 1); PG8_STAGE(PG8_SB(0, 0), b2, voffB); PG8_STAGE(PG8_SB(0, 1), b2 + hstepB, voffB); PG8_STAGE(PG8_SA(0, 0), a2, voffA);
.LBB0_3336:
	s_add_u32 s41, s34, s40
	s_addc_u32 s46, s35, 0
	s_add_u32 s44, s41, 0x100
	s_addc_u32 s45, s46, 0
	s_and_b64 s[42:43], s[38:39], exec
	s_cselect_b32 s43, s23, s45
	s_cselect_b32 s42, s71, s44
	s_add_u32 s40, s30, s40
	s_addc_u32 s44, s31, 0
	s_add_u32 s40, s40, 0x100
	s_addc_u32 s44, s44, 0
	s_and_b64 s[38:39], s[38:39], exec
	s_cselect_b32 s45, s21, s44
	s_cselect_b32 s44, s72, s40
	s_add_u32 s48, s41, 0x10080
	ds_read_b128 v[144:147], v141
	ds_read_b128 v[148:151], v141 offset:1024
	ds_read_b128 v[152:155], v141 offset:2048
	ds_read_b128 v[156:159], v141 offset:3072
	ds_read_b128 v[160:163], v142
	ds_read_b128 v[164:167], v142 offset:1024
	ds_read_b128 v[168:171], v142 offset:2048
	ds_read_b128 v[172:175], v142 offset:3072
	s_addc_u32 s49, s46, 0
	s_add_i32 s80, s62, s52
	s_add_i32 m0, s53, 0xc000
	s_add_i32 s83, s53, 0xe000
	s_add_i32 s77, s80, 0x2000
	s_add_u32 s46, s44, 0x40000
	s_addc_u32 s47, s45, 0
	s_add_i32 s79, s63, s52
	s_add_i32 s78, s79, 0x2000
	s_add_i32 s76, 0, 0x18000
	s_add_i32 s75, 0, 0x1c000
	s_add_u32 s40, s42, 0x10000
	s_addc_u32 s41, s43, 0
	s_add_i32 s74, s76, s52
	s_add_i32 s73, s74, 0x2000
	s_add_u32 s38, s44, 0x40080
	s_addc_u32 s39, s45, 0
	s_add_i32 s82, s75, s52
	s_add_i32 s81, s82, 0x2000
	v_lshl_add_u64 v[136:137], s[48:49], 0, v[128:129]
	ds_read_b128 v[176:179], v143
	ds_read_b128 v[180:183], v143 offset:1024
	ds_read_b128 v[184:187], v143 offset:2048
	ds_read_b128 v[188:191], v143 offset:3072
	ds_read_b128 v[196:199], v143 offset:4096
	ds_read_b128 v[200:203], v143 offset:5120
	ds_read_b128 v[204:207], v143 offset:6144
	ds_read_b128 v[208:211], v143 offset:7168
	global_load_lds_dwordx4 v[136:137], off
	v_lshl_add_u64 v[136:137], s[48:49], 0, v[132:133]
	s_mov_b32 m0, s83
	s_nop 0
	global_load_lds_dwordx4 v[136:137], off
	s_nop 0
	s_nop 0
	s_waitcnt vmcnt(8)
	s_waitcnt lgkmcnt(0)
	v_mfma_f32_16x16x32_bf16 v[124:127], v[144:147], v[176:179], v[124:127]
	v_mfma_f32_16x16x32_bf16 v[120:123], v[152:155], v[176:179], v[120:123]
	s_barrier
	s_setprio 1
	s_waitcnt lgkmcnt(0)
	v_mfma_f32_16x16x32_bf16 v[112:115], v[144:147], v[184:187], v[112:115]
	v_mfma_f32_16x16x32_bf16 v[104:107], v[152:155], v[184:187], v[104:107]
	v_mfma_f32_16x16x32_bf16 v[96:99], v[144:147], v[196:199], v[96:99]
	v_mfma_f32_16x16x32_bf16 v[88:91], v[152:155], v[196:199], v[88:91]
	v_mfma_f32_16x16x32_bf16 v[80:83], v[144:147], v[204:207], v[80:83]
	v_mfma_f32_16x16x32_bf16 v[72:75], v[152:155], v[204:207], v[72:75]
	v_mfma_f32_16x16x32_bf16 v[124:127], v[148:151], v[180:183], v[124:127]
	v_mfma_f32_16x16x32_bf16 v[120:123], v[156:159], v[180:183], v[120:123]
	v_mfma_f32_16x16x32_bf16 v[112:115], v[148:151], v[188:191], v[112:115]
	v_mfma_f32_16x16x32_bf16 v[104:107], v[156:159], v[188:191], v[104:107]
	v_mfma_f32_16x16x32_bf16 v[96:99], v[148:151], v[200:203], v[96:99]
	v_mfma_f32_16x16x32_bf16 v[88:91], v[156:159], v[200:203], v[88:91]
	v_mfma_f32_16x16x32_bf16 v[80:83], v[148:151], v[208:211], v[80:83]
	v_mfma_f32_16x16x32_bf16 v[72:75], v[156:159], v[208:211], v[72:75]
	s_setprio 0
	s_setprio 1
	v_mfma_f32_16x16x32_bf16 v[116:119], v[160:163], v[176:179], v[116:119]
	v_mfma_f32_16x16x32_bf16 v[108:111], v[168:171], v[176:179], v[108:111]
	v_mfma_f32_16x16x32_bf16 v[100:103], v[160:163], v[184:187], v[100:103]
	v_mfma_f32_16x16x32_bf16 v[92:95], v[168:171], v[184:187], v[92:95]
	v_mfma_f32_16x16x32_bf16 v[84:87], v[160:163], v[196:199], v[84:87]
	v_mfma_f32_16x16x32_bf16 v[76:79], v[168:171], v[196:199], v[76:79]
	v_mfma_f32_16x16x32_bf16 v[68:71], v[160:163], v[204:207], v[68:71]
	v_mfma_f32_16x16x32_bf16 v[64:67], v[168:171], v[204:207], v[64:67]
	v_mfma_f32_16x16x32_bf16 v[116:119], v[164:167], v[180:183], v[116:119]
	v_mfma_f32_16x16x32_bf16 v[108:111], v[172:175], v[180:183], v[108:111]
	v_mfma_f32_16x16x32_bf16 v[100:103], v[164:167], v[188:191], v[100:103]
	v_mfma_f32_16x16x32_bf16 v[92:95], v[172:175], v[188:191], v[92:95]
	v_mfma_f32_16x16x32_bf16 v[84:87], v[164:167], v[200:203], v[84:87]
	v_mfma_f32_16x16x32_bf16 v[76:79], v[172:175], v[200:203], v[76:79]
	v_mfma_f32_16x16x32_bf16 v[68:71], v[164:167], v[208:211], v[68:71]
	v_mfma_f32_16x16x32_bf16 v[64:67], v[172:175], v[208:211], v[64:67]
	s_setprio 0
	s_barrier
	s_mov_b32 m0, s80
	v_lshl_add_u64 v[136:137], s[44:45], 0, v[130:131]
	ds_read_b128 v[176:179], v143 offset:16384
	ds_read_b128 v[180:183], v143 offset:17408
	ds_read_b128 v[184:187], v143 offset:18432
	ds_read_b128 v[188:191], v143 offset:19456
	ds_read_b128 v[196:199], v143 offset:20480
	ds_read_b128 v[200:203], v143 offset:21504
	ds_read_b128 v[204:207], v143 offset:22528
	ds_read_b128 v[208:211], v143 offset:23552
	global_load_lds_dwordx4 v[136:137], off
	v_lshl_add_u64 v[192:193], s[44:45], 0, v[134:135]
	s_mov_b32 m0, s77
	v_lshl_add_u64 v[212:213], s[46:47], 0, v[130:131]
	global_load_lds_dwordx4 v[192:193], off
	s_mov_b32 m0, s79
	v_lshl_add_u64 v[214:215], s[42:43], 0, v[132:133]
	global_load_lds_dwordx4 v[212:213], off
	v_lshl_add_u64 v[212:213], s[46:47], 0, v[134:135]
	s_mov_b32 m0, s78
	s_nop 0
	global_load_lds_dwordx4 v[212:213], off
	v_lshl_add_u64 v[212:213], s[42:43], 0, v[128:129]
	s_mov_b32 m0, s53
	s_nop 0
	global_load_lds_dwordx4 v[212:213], off
	s_mov_b32 m0, s54
	s_nop 0
	global_load_lds_dwordx4 v[214:215], off
	s_nop 0
	s_nop 0
	s_waitcnt vmcnt(8)
	s_waitcnt lgkmcnt(0)
	v_mfma_f32_16x16x32_bf16 v[60:63], v[144:147], v[176:179], v[60:63]
	v_mfma_f32_16x16x32_bf16 v[56:59], v[152:155], v[176:179], v[56:59]
	s_barrier
; #define PG8_STAGE(bufoff, gbase, voff) do { _Pragma("unroll") for (int _i = 0; _i < 2; ++_i) \
;         __builtin_amdgcn_global_load_lds((const unsigned*)((const char*)(gbase) + (voff)[_i]), (LAS unsigned*)(lds + (bufoff) + ldsw + _i * 8192), 16, 0, 0); } while (0)
; #define PG8_LDA(dst, b, h) do { _Pragma("unroll") for (int m = 0; m < 4; ++m) _Pragma("unroll") for (int k = 0; k < 2; ++k) dst[m][k] = *(const LAS bf16x8*)(lds + PG8_SA(b, h) + aoff + m * 2048 + k * 1024); } while (0)
; #define PG8_LDB(dst, b, h) do { _Pragma("unroll") for (int n = 0; n < 2; ++n) _Pragma("unroll") for (int k = 0; k < 2; ++k) dst[n][k] = *(const LAS bf16x8*)(lds + PG8_SB(b, h) + boff + n * 2048 + k * 1024); } while (0)
; #define PG8_MMA(ai, bj, At, Bt) do { __builtin_amdgcn_s_setprio(1); _Pragma("unroll") for (int m = 0; m < 4; ++m) _Pragma("unroll") for (int n = 0; n < 2; ++n) _Pragma("unroll") for (int k = 0; k < 2; ++k) \
;         acc[ai][bj][m][n] = __builtin_amdgcn_mfma_f32_16x16x32_bf16(Bt[n][k], At[m][k], acc[ai][bj][m][n], 0, 0, 0); __builtin_amdgcn_s_setprio(0); } while (0)
; #define PG8_WAIT_V(n) asm volatile("s_waitcnt vmcnt(" #n ")" ::: "memory")
; #define PG8_WAIT_L(n) asm volatile("s_waitcnt lgkmcnt(" #n ")" ::: "memory")
; #define PG8_BAR __builtin_amdgcn_s_barrier()
; #define PG8_SCHED __builtin_amdgcn_sched_barrier(0)
; template <class Epi, class Sched>
; __device__ __forceinline__ void gemm_phase(LAS unsigned char* lds, const Gemm g, const Sched& S, const Epi& E) {
;     ...
;             PG8_WAIT_V(8); PG8_WAIT_L(0); PG8_BAR; PG8_MMA(1, 0, At, B0); PG8_MMA(1, 1, At, B1); PG8_BAR; PG8_SCHED;
;             PG8_LDB(B0, 1, 0); PG8_LDB(B1, 1, 1); PG8_SCHED; PG8_LDA(At, 1, 0); PG8_STAGE(PG8_SA(0, 1), a2 + hstepA, voffA);
;             PG8_WAIT_V(8); PG8_WAIT_L(0); PG8_BAR; PG8_MMA(0, 0, At, B0); PG8_MMA(0, 1, At, B1); PG8_BAR; PG8_SCHED;
	s_setprio 1
	s_waitcnt lgkmcnt(0)
	v_mfma_f32_16x16x32_bf16 v[48:51], v[144:147], v[184:187], v[48:51]
	v_mfma_f32_16x16x32_bf16 v[40:43], v[152:155], v[184:187], v[40:43]
	v_mfma_f32_16x16x32_bf16 v[32:35], v[144:147], v[196:199], v[32:35]
	v_mfma_f32_16x16x32_bf16 v[24:27], v[152:155], v[196:199], v[24:27]
	v_mfma_f32_16x16x32_bf16 v[16:19], v[144:147], v[204:207], v[16:19]
	v_mfma_f32_16x16x32_bf16 v[8:11], v[152:155], v[204:207], v[8:11]
	v_mfma_f32_16x16x32_bf16 v[60:63], v[148:151], v[180:183], v[60:63]
	v_mfma_f32_16x16x32_bf16 v[56:59], v[156:159], v[180:183], v[56:59]
	v_mfma_f32_16x16x32_bf16 v[48:51], v[148:151], v[188:191], v[48:51]
	v_mfma_f32_16x16x32_bf16 v[40:43], v[156:159], v[188:191], v[40:43]
	v_mfma_f32_16x16x32_bf16 v[32:35], v[148:151], v[200:203], v[32:35]
	v_mfma_f32_16x16x32_bf16 v[24:27], v[156:159], v[200:203], v[24:27]
	v_mfma_f32_16x16x32_bf16 v[16:19], v[148:151], v[208:211], v[16:19]
	v_mfma_f32_16x16x32_bf16 v[8:11], v[156:159], v[208:211], v[8:11]
	s_setprio 0
	s_setprio 1
	v_mfma_f32_16x16x32_bf16 v[52:55], v[160:163], v[176:179], v[52:55]
	v_mfma_f32_16x16x32_bf16 v[44:47], v[168:171], v[176:179], v[44:47]
	v_mfma_f32_16x16x32_bf16 v[36:39], v[160:163], v[184:187], v[36:39]
	v_mfma_f32_16x16x32_bf16 v[28:31], v[168:171], v[184:187], v[28:31]
	v_mfma_f32_16x16x32_bf16 v[20:23], v[160:163], v[196:199], v[20:23]
	v_mfma_f32_16x16x32_bf16 v[12:15], v[168:171], v[196:199], v[12:15]
	v_mfma_f32_16x16x32_bf16 v[4:7], v[160:163], v[204:207], v[4:7]
	v_mfma_f32_16x16x32_bf16 v[0:3], v[168:171], v[204:207], v[0:3]
	v_mfma_f32_16x16x32_bf16 v[52:55], v[164:167], v[180:183], v[52:55]
	v_mfma_f32_16x16x32_bf16 v[44:47], v[172:175], v[180:183], v[44:47]
	v_mfma_f32_16x16x32_bf16 v[36:39], v[164:167], v[188:191], v[36:39]
	v_mfma_f32_16x16x32_bf16 v[28:31], v[172:175], v[188:191], v[28:31]
	v_mfma_f32_16x16x32_bf16 v[20:23], v[164:167], v[200:203], v[20:23]
	v_mfma_f32_16x16x32_bf16 v[12:15], v[172:175], v[200:203], v[12:15]
	v_mfma_f32_16x16x32_bf16 v[4:7], v[164:167], v[208:211], v[4:7]
	v_mfma_f32_16x16x32_bf16 v[0:3], v[172:175], v[208:211], v[0:3]
	s_setprio 0
	s_barrier
	v_add_u32_e32 v156, s76, v140
	v_add_u32_e32 v172, s75, v140
	ds_read_b128 v[144:147], v156
	ds_read_b128 v[148:151], v156 offset:1024
	ds_read_b128 v[152:155], v156 offset:2048
	ds_read_b128 v[156:159], v156 offset:3072
	ds_read_b128 v[160:163], v172
	ds_read_b128 v[164:167], v172 offset:1024
	ds_read_b128 v[168:171], v172 offset:2048
	ds_read_b128 v[172:175], v172 offset:3072
	s_mov_b32 m0, s55
	v_lshl_add_u64 v[216:217], s[40:41], 0, v[128:129]
	ds_read_b128 v[176:179], v143 offset:32768
	ds_read_b128 v[180:183], v143 offset:33792
	ds_read_b128 v[184:187], v143 offset:34816
	ds_read_b128 v[188:191], v143 offset:35840
	ds_read_b128 v[196:199], v143 offset:36864
	ds_read_b128 v[200:203], v143 offset:37888
	ds_read_b128 v[204:207], v143 offset:38912
	ds_read_b128 v[208:211], v143 offset:39936
	global_load_lds_dwordx4 v[216:217], off
	v_lshl_add_u64 v[216:217], s[40:41], 0, v[132:133]
	s_mov_b32 m0, s56
	s_nop 0
	global_load_lds_dwordx4 v[216:217], off
	s_nop 0
	s_nop 0
	s_waitcnt vmcnt(8)
	s_waitcnt lgkmcnt(0)
	v_mfma_f32_16x16x32_bf16 v[124:127], v[144:147], v[176:179], v[124:127]
	v_mfma_f32_16x16x32_bf16 v[120:123], v[152:155], v[176:179], v[120:123]
	s_barrier
	s_setprio 1
	s_waitcnt lgkmcnt(0)
	v_mfma_f32_16x16x32_bf16 v[112:115], v[144:147], v[184:187], v[112:115]
	v_mfma_f32_16x16x32_bf16 v[104:107], v[152:155], v[184:187], v[104:107]
	v_mfma_f32_16x16x32_bf16 v[96:99], v[144:147], v[196:199], v[96:99]
	v_mfma_f32_16x16x32_bf16 v[88:91], v[152:155], v[196:199], v[88:91]
	v_mfma_f32_16x16x32_bf16 v[80:83], v[144:147], v[204:207], v[80:83]
	v_mfma_f32_16x16x32_bf16 v[72:75], v[152:155], v[204:207], v[72:75]
	v_mfma_f32_16x16x32_bf16 v[124:127], v[148:151], v[180:183], v[124:127]
	v_mfma_f32_16x16x32_bf16 v[120:123], v[156:159], v[180:183], v[120:123]
	v_mfma_f32_16x16x32_bf16 v[112:115], v[148:151], v[188:191], v[112:115]
	v_mfma_f32_16x16x32_bf16 v[104:107], v[156:159], v[188:191], v[104:107]
	v_mfma_f32_16x16x32_bf16 v[96:99], v[148:151], v[200:203], v[96:99]
	v_mfma_f32_16x16x32_bf16 v[88:91], v[156:159], v[200:203], v[88:91]
	v_mfma_f32_16x16x32_bf16 v[80:83], v[148:151], v[208:211], v[80:83]
	v_mfma_f32_16x16x32_bf16 v[72:75], v[156:159], v[208:211], v[72:75]
	s_setprio 0
	s_setprio 1
	v_mfma_f32_16x16x32_bf16 v[116:119], v[160:163], v[176:179], v[116:119]
	v_mfma_f32_16x16x32_bf16 v[108:111], v[168:171], v[176:179], v[108:111]
	v_mfma_f32_16x16x32_bf16 v[100:103], v[160:163], v[184:187], v[100:103]
	v_mfma_f32_16x16x32_bf16 v[92:95], v[168:171], v[184:187], v[92:95]
	v_mfma_f32_16x16x32_bf16 v[84:87], v[160:163], v[196:199], v[84:87]
	v_mfma_f32_16x16x32_bf16 v[76:79], v[168:171], v[196:199], v[76:79]
	v_mfma_f32_16x16x32_bf16 v[68:71], v[160:163], v[204:207], v[68:71]
	v_mfma_f32_16x16x32_bf16 v[64:67], v[168:171], v[204:207], v[64:67]
	v_mfma_f32_16x16x32_bf16 v[116:119], v[164:167], v[180:183], v[116:119]
	v_mfma_f32_16x16x32_bf16 v[108:111], v[172:175], v[180:183], v[108:111]
	v_mfma_f32_16x16x32_bf16 v[100:103], v[164:167], v[188:191], v[100:103]
	v_mfma_f32_16x16x32_bf16 v[92:95], v[172:175], v[188:191], v[92:95]
	v_mfma_f32_16x16x32_bf16 v[84:87], v[164:167], v[200:203], v[84:87]
	v_mfma_f32_16x16x32_bf16 v[76:79], v[172:175], v[200:203], v[76:79]
	v_mfma_f32_16x16x32_bf16 v[68:71], v[164:167], v[208:211], v[68:71]
	v_mfma_f32_16x16x32_bf16 v[64:67], v[172:175], v[208:211], v[64:67]
	s_setprio 0
	s_barrier
; #define PG8_STAGE(bufoff, gbase, voff) do { _Pragma("unroll") for (int _i = 0; _i < 2; ++_i) \
;         __builtin_amdgcn_global_load_lds((const unsigned*)((const char*)(gbase) + (voff)[_i]), (LAS unsigned*)(lds + (bufoff) + ldsw + _i * 8192), 16, 0, 0); } while (0)
; #define PG8_LDA(dst, b, h) do { _Pragma("unroll") for (int m = 0; m < 4; ++m) _Pragma("unroll") for (int k = 0; k < 2; ++k) dst[m][k] = *(const LAS bf16x8*)(lds + PG8_SA(b, h) + aoff + m * 2048 + k * 1024); } while (0)
; #define PG8_MMA(ai, bj, At, Bt) do { __builtin_amdgcn_s_setprio(1); _Pragma("unroll") for (int m = 0; m < 4; ++m) _Pragma("unroll") for (int n = 0; n < 2; ++n) _Pragma("unroll") for (int k = 0; k < 2; ++k) \
;         acc[ai][bj][m][n] = __builtin_amdgcn_mfma_f32_16x16x32_bf16(Bt[n][k], At[m][k], acc[ai][bj][m][n], 0, 0, 0); __builtin_amdgcn_s_setprio(0); } while (0)
; #define PG8_WAIT_V(n) asm volatile("s_waitcnt vmcnt(" #n ")" ::: "memory")
; #define PG8_WAIT_L(n) asm volatile("s_waitcnt lgkmcnt(" #n ")" ::: "memory")
; #define PG8_BAR __builtin_amdgcn_s_barrier()
; #define PG8_SCHED __builtin_amdgcn_sched_barrier(0)
; template <class Epi, class Sched>
; __device__ __forceinline__ void gemm_phase(LAS unsigned char* lds, const Gemm g, const Sched& S, const Epi& E) {
;     ...
;             PG8_LDA(At, 1, 1); PG8_STAGE(PG8_SB(1, 0), b3, voffB); PG8_STAGE(PG8_SB(1, 1), b3 + hstepB, voffB); PG8_STAGE(PG8_SA(1, 0), a3, voffA);
;             PG8_WAIT_V(8); PG8_WAIT_L(0); PG8_BAR; PG8_MMA(1, 0, At, B0); PG8_MMA(1, 1, At, B1); PG8_BAR; PG8_SCHED;
;         }
;         if (wr == 0) PG8_BAR;
	s_mov_b32 m0, s74
	v_lshl_add_u64 v[136:137], v[136:137], 0, s[8:9]
	ds_read_b128 v[176:179], v143 offset:49152
	ds_read_b128 v[180:183], v143 offset:50176
	ds_read_b128 v[184:187], v143 offset:51200
	ds_read_b128 v[188:191], v143 offset:52224
	ds_read_b128 v[196:199], v143 offset:53248
	ds_read_b128 v[200:203], v143 offset:54272
	ds_read_b128 v[204:207], v143 offset:55296
	ds_read_b128 v[208:211], v143 offset:56320
	global_load_lds_dwordx4 v[136:137], off
	v_lshl_add_u64 v[136:137], v[192:193], 0, s[8:9]
	s_mov_b32 m0, s73
	s_nop 0
	global_load_lds_dwordx4 v[136:137], off
	v_lshl_add_u64 v[136:137], s[38:39], 0, v[130:131]
	s_mov_b32 m0, s82
	s_nop 0
	global_load_lds_dwordx4 v[136:137], off
	v_lshl_add_u64 v[136:137], s[38:39], 0, v[134:135]
	s_mov_b32 m0, s81
	s_nop 0
	global_load_lds_dwordx4 v[136:137], off
	v_lshl_add_u64 v[136:137], v[212:213], 0, s[8:9]
	s_mov_b32 m0, s59
	s_nop 0
	global_load_lds_dwordx4 v[136:137], off
	v_lshl_add_u64 v[136:137], v[214:215], 0, s[8:9]
	s_mov_b32 m0, s60
	s_nop 0
	global_load_lds_dwordx4 v[136:137], off
	s_waitcnt vmcnt(8)
	s_waitcnt lgkmcnt(0)
	v_mfma_f32_16x16x32_bf16 v[60:63], v[144:147], v[176:179], v[60:63]
	v_mfma_f32_16x16x32_bf16 v[56:59], v[152:155], v[176:179], v[56:59]
	s_barrier
	s_setprio 1
	s_waitcnt lgkmcnt(0)
	v_mfma_f32_16x16x32_bf16 v[48:51], v[144:147], v[184:187], v[48:51]
	v_mfma_f32_16x16x32_bf16 v[40:43], v[152:155], v[184:187], v[40:43]
	v_mfma_f32_16x16x32_bf16 v[32:35], v[144:147], v[196:199], v[32:35]
	v_mfma_f32_16x16x32_bf16 v[24:27], v[152:155], v[196:199], v[24:27]
	v_mfma_f32_16x16x32_bf16 v[16:19], v[144:147], v[204:207], v[16:19]
	v_mfma_f32_16x16x32_bf16 v[8:11], v[152:155], v[204:207], v[8:11]
	v_mfma_f32_16x16x32_bf16 v[60:63], v[148:151], v[180:183], v[60:63]
	v_mfma_f32_16x16x32_bf16 v[56:59], v[156:159], v[180:183], v[56:59]
	v_mfma_f32_16x16x32_bf16 v[48:51], v[148:151], v[188:191], v[48:51]
	v_mfma_f32_16x16x32_bf16 v[40:43], v[156:159], v[188:191], v[40:43]
	v_mfma_f32_16x16x32_bf16 v[32:35], v[148:151], v[200:203], v[32:35]
	v_mfma_f32_16x16x32_bf16 v[24:27], v[156:159], v[200:203], v[24:27]
	v_mfma_f32_16x16x32_bf16 v[16:19], v[148:151], v[208:211], v[16:19]
	v_mfma_f32_16x16x32_bf16 v[8:11], v[156:159], v[208:211], v[8:11]
	s_setprio 0
	s_setprio 1
	v_mfma_f32_16x16x32_bf16 v[52:55], v[160:163], v[176:179], v[52:55]
	v_mfma_f32_16x16x32_bf16 v[44:47], v[168:171], v[176:179], v[44:47]
	v_mfma_f32_16x16x32_bf16 v[36:39], v[160:163], v[184:187], v[36:39]
	v_mfma_f32_16x16x32_bf16 v[28:31], v[168:171], v[184:187], v[28:31]
	v_mfma_f32_16x16x32_bf16 v[20:23], v[160:163], v[196:199], v[20:23]
	v_mfma_f32_16x16x32_bf16 v[12:15], v[168:171], v[196:199], v[12:15]
	v_mfma_f32_16x16x32_bf16 v[4:7], v[160:163], v[204:207], v[4:7]
	v_mfma_f32_16x16x32_bf16 v[0:3], v[168:171], v[204:207], v[0:3]
	v_mfma_f32_16x16x32_bf16 v[52:55], v[164:167], v[180:183], v[52:55]
	v_mfma_f32_16x16x32_bf16 v[44:47], v[172:175], v[180:183], v[44:47]
	v_mfma_f32_16x16x32_bf16 v[36:39], v[164:167], v[188:191], v[36:39]
	v_mfma_f32_16x16x32_bf16 v[28:31], v[172:175], v[188:191], v[28:31]
	v_mfma_f32_16x16x32_bf16 v[20:23], v[164:167], v[200:203], v[20:23]
	v_mfma_f32_16x16x32_bf16 v[12:15], v[172:175], v[200:203], v[12:15]
	v_mfma_f32_16x16x32_bf16 v[4:7], v[164:167], v[208:211], v[4:7]
	v_mfma_f32_16x16x32_bf16 v[0:3], v[172:175], v[208:211], v[0:3]
	s_setprio 0
	s_barrier
	s_movk_i32 s40, 0x100
	s_andn2_b64 vcc, exec, s[36:37]
	s_mov_b64 s[38:39], -1
	s_mov_b64 s[36:37], 0
	s_cbranch_vccz .LBB0_3336
	s_and_b64 vcc, exec, s[10:11]
	s_cbranch_vccz .LBB0_3339
	s_barrier

; #define PG8_STAGE(bufoff, gbase, voff) do { _Pragma("unroll") for (int _i = 0; _i < 2; ++_i) \
;         __builtin_amdgcn_global_load_lds((const unsigned*)((const char*)(gbase) + (voff)[_i]), (LAS unsigned*)(lds + (bufoff) + ldsw + _i * 8192), 16, 0, 0); } while (0)
; #define PG8_LDA(dst, b, h) do { _Pragma("unroll") for (int m = 0; m < 4; ++m) _Pragma("unroll") for (int k = 0; k < 2; ++k) dst[m][k] = *(const LAS bf16x8*)(lds + PG8_SA(b, h) + aoff + m * 2048 + k * 1024); } while (0)
; #define PG8_LDB(dst, b, h) do { _Pragma("unroll") for (int n = 0; n < 2; ++n) _Pragma("unroll") for (int k = 0; k < 2; ++k) dst[n][k] = *(const LAS bf16x8*)(lds + PG8_SB(b, h) + boff + n * 2048 + k * 1024); } while (0)
; #define PG8_MMA(ai, bj, At, Bt) do { __builtin_amdgcn_s_setprio(1); _Pragma("unroll") for (int m = 0; m < 4; ++m) _Pragma("unroll") for (int n = 0; n < 2; ++n) _Pragma("unroll") for (int k = 0; k < 2; ++k) \
;         acc[ai][bj][m][n] = __builtin_amdgcn_mfma_f32_16x16x32_bf16(Bt[n][k], At[m][k], acc[ai][bj][m][n], 0, 0, 0); __builtin_amdgcn_s_setprio(0); } while (0)
; #define PG8_WAIT_V(n) asm volatile("s_waitcnt vmcnt(" #n ")" ::: "memory")
; #define PG8_WAIT_L(n) asm volatile("s_waitcnt lgkmcnt(" #n ")" ::: "memory")
; #define PG8_BAR __builtin_amdgcn_s_barrier()
; #define PG8_SCHED __builtin_amdgcn_sched_barrier(0)
; template <class Epi, class Sched>
; __device__ __forceinline__ void gemm_phase(LAS unsigned char* lds, const Gemm g, const Sched& S, const Epi& E) {
;     ...
;             const bool last = (t == nt - 2);
;             const char* a1 = cA + (size_t)(t + 1) * kstep;
;             const char* a2 = last ? nA : cA + (size_t)(t + 2) * kstep; const char* b2 = last ? nB : cB + (size_t)(t + 2) * kstep;
;             const char* a3 = a2 + kstep; const char* b3 = b2 + kstep;
;             PG8_LDB(B0, 0, 0); PG8_LDB(B1, 0, 1); PG8_SCHED; PG8_LDA(At, 0, 0); PG8_STAGE(PG8_SA(1, 1), a1 + hstepA, voffA);
;             PG8_WAIT_V(8); PG8_WAIT_L(0); PG8_BAR; PG8_MMA(0, 0, At, B0); PG8_MMA(0, 1, At, B1); PG8_BAR; PG8_SCHED;
;             PG8_LDA(At, 0, 1); PG8_STAGE(PG8_SB(0, 0), b2, voffB); PG8_STAGE(PG8_SB(0, 1), b2 + hstepB, voffB); PG8_STAGE(PG8_SA(0, 0), a2, voffA);
.LBB0_3415:
	s_add_u32 s20, s18, 0xfff80080
	s_addc_u32 s21, s19, -1
	s_add_i32 s47, 0, 0x10000
	s_cmp_eq_u32 s46, 28
	s_cselect_b32 s23, s11, s21
	s_cselect_b32 s22, s17, s20
	s_cselect_b32 s21, s7, s45
	s_cselect_b32 s20, s24, s25
	s_add_i32 s50, 0, 0x14000
	v_add_u32_e32 v170, s47, v1
	v_add_u32_e32 v183, s50, v1
	s_waitcnt lgkmcnt(0)
	ds_read_b128 v[142:145], v170
	ds_read_b128 v[162:165], v170 offset:1024
	ds_read_b128 v[166:169], v170 offset:2048
	ds_read_b128 v[170:173], v170 offset:3072
	ds_read_b128 v[174:177], v183
	ds_read_b128 v[178:181], v183 offset:1024
	ds_read_b128 v[184:187], v183 offset:2048
	ds_read_b128 v[188:191], v183 offset:3072
	v_lshl_add_u64 v[192:193], s[18:19], 0, v[138:139]
	s_add_i32 m0, s31, 0xc000
	ds_read_b128 v[208:211], v182
	ds_read_b128 v[212:215], v182 offset:1024
	ds_read_b128 v[216:219], v182 offset:2048
	ds_read_b128 v[220:223], v182 offset:3072
	ds_read_b128 v[224:227], v182 offset:4096
	ds_read_b128 v[228:231], v182 offset:5120
	ds_read_b128 v[232:235], v182 offset:6144
	ds_read_b128 v[236:239], v182 offset:7168
	global_load_lds_dwordx4 v[192:193], off
	v_lshl_add_u64 v[192:193], s[18:19], 0, v[140:141]
	s_add_i32 m0, s31, 0xe000
	s_nop 0
	global_load_lds_dwordx4 v[192:193], off
	s_nop 0
	s_nop 0
	s_waitcnt vmcnt(8)
	s_waitcnt lgkmcnt(0)
	v_mfma_f32_16x16x32_bf16 v[126:129], v[142:145], v[208:211], v[126:129]
	v_mfma_f32_16x16x32_bf16 v[122:125], v[166:169], v[208:211], v[122:125]
	s_barrier
	s_setprio 1
	s_waitcnt lgkmcnt(0)
	v_mfma_f32_16x16x32_bf16 v[110:113], v[142:145], v[216:219], v[110:113]
	v_mfma_f32_16x16x32_bf16 v[106:109], v[166:169], v[216:219], v[106:109]
	v_mfma_f32_16x16x32_bf16 v[98:101], v[142:145], v[224:227], v[98:101]
	v_mfma_f32_16x16x32_bf16 v[90:93], v[166:169], v[224:227], v[90:93]
	v_mfma_f32_16x16x32_bf16 v[82:85], v[142:145], v[232:235], v[82:85]
	v_mfma_f32_16x16x32_bf16 v[74:77], v[166:169], v[232:235], v[74:77]
	v_mfma_f32_16x16x32_bf16 v[126:129], v[162:165], v[212:215], v[126:129]
	v_mfma_f32_16x16x32_bf16 v[122:125], v[170:173], v[212:215], v[122:125]
	v_mfma_f32_16x16x32_bf16 v[110:113], v[162:165], v[220:223], v[110:113]
	v_mfma_f32_16x16x32_bf16 v[106:109], v[170:173], v[220:223], v[106:109]
	v_mfma_f32_16x16x32_bf16 v[98:101], v[162:165], v[228:231], v[98:101]
	v_mfma_f32_16x16x32_bf16 v[90:93], v[170:173], v[228:231], v[90:93]
	v_mfma_f32_16x16x32_bf16 v[82:85], v[162:165], v[236:239], v[82:85]
	v_mfma_f32_16x16x32_bf16 v[74:77], v[170:173], v[236:239], v[74:77]
	s_setprio 0
	s_setprio 1
	v_mfma_f32_16x16x32_bf16 v[118:121], v[174:177], v[208:211], v[118:121]
	v_mfma_f32_16x16x32_bf16 v[114:117], v[184:187], v[208:211], v[114:117]
	v_mfma_f32_16x16x32_bf16 v[102:105], v[174:177], v[216:219], v[102:105]
	v_mfma_f32_16x16x32_bf16 v[94:97], v[184:187], v[216:219], v[94:97]
	v_mfma_f32_16x16x32_bf16 v[86:89], v[174:177], v[224:227], v[86:89]
	v_mfma_f32_16x16x32_bf16 v[78:81], v[184:187], v[224:227], v[78:81]
	v_mfma_f32_16x16x32_bf16 v[70:73], v[174:177], v[232:235], v[70:73]
	v_mfma_f32_16x16x32_bf16 v[66:69], v[184:187], v[232:235], v[66:69]
	v_mfma_f32_16x16x32_bf16 v[118:121], v[178:181], v[212:215], v[118:121]
	v_mfma_f32_16x16x32_bf16 v[114:117], v[188:191], v[212:215], v[114:117]
	v_mfma_f32_16x16x32_bf16 v[102:105], v[178:181], v[220:223], v[102:105]
	v_mfma_f32_16x16x32_bf16 v[94:97], v[188:191], v[220:223], v[94:97]
	v_mfma_f32_16x16x32_bf16 v[86:89], v[178:181], v[228:231], v[86:89]
	v_mfma_f32_16x16x32_bf16 v[78:81], v[188:191], v[228:231], v[78:81]
	v_mfma_f32_16x16x32_bf16 v[70:73], v[178:181], v[236:239], v[70:73]
	v_mfma_f32_16x16x32_bf16 v[66:69], v[188:191], v[236:239], v[66:69]
	s_setprio 0
	s_barrier
	s_add_i32 s47, s47, s30
	v_lshl_add_u64 v[192:193], s[20:21], 0, v[134:135]
	s_mov_b32 m0, s47
	ds_read_b128 v[208:211], v182 offset:16384
	ds_read_b128 v[212:215], v182 offset:17408
	ds_read_b128 v[216:219], v182 offset:18432
	ds_read_b128 v[220:223], v182 offset:19456
	ds_read_b128 v[224:227], v182 offset:20480
	ds_read_b128 v[228:231], v182 offset:21504
	ds_read_b128 v[232:235], v182 offset:22528
	ds_read_b128 v[236:239], v182 offset:23552
	global_load_lds_dwordx4 v[192:193], off
	s_add_i32 m0, s47, 0x2000
	s_add_u32 s48, s20, 0x80000
	v_lshl_add_u64 v[240:241], s[20:21], 0, v[130:131]
	s_addc_u32 s49, s21, 0
	s_add_i32 s47, s50, s30
	global_load_lds_dwordx4 v[240:241], off
	v_lshl_add_u64 v[242:243], s[48:49], 0, v[134:135]
	s_mov_b32 m0, s47
	v_lshl_add_u64 v[244:245], s[22:23], 0, v[132:133]
	global_load_lds_dwordx4 v[242:243], off
	v_lshl_add_u64 v[242:243], s[48:49], 0, v[130:131]
	s_add_i32 m0, s47, 0x2000
	s_nop 0
	global_load_lds_dwordx4 v[242:243], off
	v_lshl_add_u64 v[242:243], s[22:23], 0, v[136:137]
	s_mov_b32 m0, s31
	s_nop 0
	global_load_lds_dwordx4 v[242:243], off
	s_mov_b32 m0, s33
	s_nop 0
	global_load_lds_dwordx4 v[244:245], off
	s_nop 0
	s_nop 0
	s_nop 0
	s_waitcnt vmcnt(8)
	s_waitcnt lgkmcnt(0)
	v_mfma_f32_16x16x32_bf16 v[62:65], v[142:145], v[208:211], v[62:65]
	v_mfma_f32_16x16x32_bf16 v[58:61], v[166:169], v[208:211], v[58:61]
	s_barrier
; #define PG8_STAGE(bufoff, gbase, voff) do { _Pragma("unroll") for (int _i = 0; _i < 2; ++_i) \
;         __builtin_amdgcn_global_load_lds((const unsigned*)((const char*)(gbase) + (voff)[_i]), (LAS unsigned*)(lds + (bufoff) + ldsw + _i * 8192), 16, 0, 0); } while (0)
; #define PG8_LDA(dst, b, h) do { _Pragma("unroll") for (int m = 0; m < 4; ++m) _Pragma("unroll") for (int k = 0; k < 2; ++k) dst[m][k] = *(const LAS bf16x8*)(lds + PG8_SA(b, h) + aoff + m * 2048 + k * 1024); } while (0)
; #define PG8_LDB(dst, b, h) do { _Pragma("unroll") for (int n = 0; n < 2; ++n) _Pragma("unroll") for (int k = 0; k < 2; ++k) dst[n][k] = *(const LAS bf16x8*)(lds + PG8_SB(b, h) + boff + n * 2048 + k * 1024); } while (0)
; #define PG8_MMA(ai, bj, At, Bt) do { __builtin_amdgcn_s_setprio(1); _Pragma("unroll") for (int m = 0; m < 4; ++m) _Pragma("unroll") for (int n = 0; n < 2; ++n) _Pragma("unroll") for (int k = 0; k < 2; ++k) \
;         acc[ai][bj][m][n] = __builtin_amdgcn_mfma_f32_16x16x32_bf16(Bt[n][k], At[m][k], acc[ai][bj][m][n], 0, 0, 0); __builtin_amdgcn_s_setprio(0); } while (0)
; #define PG8_WAIT_V(n) asm volatile("s_waitcnt vmcnt(" #n ")" ::: "memory")
; #define PG8_WAIT_L(n) asm volatile("s_waitcnt lgkmcnt(" #n ")" ::: "memory")
; #define PG8_BAR __builtin_amdgcn_s_barrier()
; #define PG8_SCHED __builtin_amdgcn_sched_barrier(0)
; template <class Epi, class Sched>
; __device__ __forceinline__ void gemm_phase(LAS unsigned char* lds, const Gemm g, const Sched& S, const Epi& E) {
;     ...
;             PG8_WAIT_V(8); PG8_WAIT_L(0); PG8_BAR; PG8_MMA(1, 0, At, B0); PG8_MMA(1, 1, At, B1); PG8_BAR; PG8_SCHED;
;             PG8_LDB(B0, 1, 0); PG8_LDB(B1, 1, 1); PG8_SCHED; PG8_LDA(At, 1, 0); PG8_STAGE(PG8_SA(0, 1), a2 + hstepA, voffA);
;             PG8_WAIT_V(8); PG8_WAIT_L(0); PG8_BAR; PG8_MMA(0, 0, At, B0); PG8_MMA(0, 1, At, B1); PG8_BAR; PG8_SCHED;
	s_setprio 1
	s_waitcnt lgkmcnt(0)
	v_mfma_f32_16x16x32_bf16 v[50:53], v[142:145], v[216:219], v[50:53]
	v_mfma_f32_16x16x32_bf16 v[42:45], v[166:169], v[216:219], v[42:45]
	v_mfma_f32_16x16x32_bf16 v[34:37], v[142:145], v[224:227], v[34:37]
	v_mfma_f32_16x16x32_bf16 v[26:29], v[166:169], v[224:227], v[26:29]
	v_mfma_f32_16x16x32_bf16 v[18:21], v[142:145], v[232:235], v[18:21]
	v_mfma_f32_16x16x32_bf16 v[10:13], v[166:169], v[232:235], v[10:13]
	v_mfma_f32_16x16x32_bf16 v[62:65], v[162:165], v[212:215], v[62:65]
	v_mfma_f32_16x16x32_bf16 v[58:61], v[170:173], v[212:215], v[58:61]
	v_mfma_f32_16x16x32_bf16 v[50:53], v[162:165], v[220:223], v[50:53]
	v_mfma_f32_16x16x32_bf16 v[42:45], v[170:173], v[220:223], v[42:45]
	v_mfma_f32_16x16x32_bf16 v[34:37], v[162:165], v[228:231], v[34:37]
	v_mfma_f32_16x16x32_bf16 v[26:29], v[170:173], v[228:231], v[26:29]
	v_mfma_f32_16x16x32_bf16 v[18:21], v[162:165], v[236:239], v[18:21]
	v_mfma_f32_16x16x32_bf16 v[10:13], v[170:173], v[236:239], v[10:13]
	s_setprio 0
	s_setprio 1
	v_mfma_f32_16x16x32_bf16 v[54:57], v[174:177], v[208:211], v[54:57]
	v_mfma_f32_16x16x32_bf16 v[46:49], v[184:187], v[208:211], v[46:49]
	v_mfma_f32_16x16x32_bf16 v[38:41], v[174:177], v[216:219], v[38:41]
	v_mfma_f32_16x16x32_bf16 v[30:33], v[184:187], v[216:219], v[30:33]
	v_mfma_f32_16x16x32_bf16 v[22:25], v[174:177], v[224:227], v[22:25]
	v_mfma_f32_16x16x32_bf16 v[14:17], v[184:187], v[224:227], v[14:17]
	v_mfma_f32_16x16x32_bf16 v[6:9], v[174:177], v[232:235], v[6:9]
	v_mfma_f32_16x16x32_bf16 v[2:5], v[184:187], v[232:235], v[2:5]
	v_mfma_f32_16x16x32_bf16 v[54:57], v[178:181], v[212:215], v[54:57]
	v_mfma_f32_16x16x32_bf16 v[46:49], v[188:191], v[212:215], v[46:49]
	v_mfma_f32_16x16x32_bf16 v[38:41], v[178:181], v[220:223], v[38:41]
	v_mfma_f32_16x16x32_bf16 v[30:33], v[188:191], v[220:223], v[30:33]
	v_mfma_f32_16x16x32_bf16 v[22:25], v[178:181], v[228:231], v[22:25]
	v_mfma_f32_16x16x32_bf16 v[14:17], v[188:191], v[228:231], v[14:17]
	v_mfma_f32_16x16x32_bf16 v[6:9], v[178:181], v[236:239], v[6:9]
	v_mfma_f32_16x16x32_bf16 v[2:5], v[188:191], v[236:239], v[2:5]
	s_setprio 0
	s_barrier
	s_add_i32 s47, 0, 0x18000
	s_add_i32 s48, 0, 0x1c000
	v_add_u32_e32 v170, s47, v1
	v_add_u32_e32 v183, s48, v1
	ds_read_b128 v[142:145], v170
	ds_read_b128 v[162:165], v170 offset:1024
	ds_read_b128 v[166:169], v170 offset:2048
	ds_read_b128 v[170:173], v170 offset:3072
	ds_read_b128 v[174:177], v183
	ds_read_b128 v[178:181], v183 offset:1024
	ds_read_b128 v[184:187], v183 offset:2048
	ds_read_b128 v[188:191], v183 offset:3072
	s_add_u32 s22, s22, 0x80000
	s_addc_u32 s23, s23, 0
	s_mov_b32 m0, s34
	v_lshl_add_u64 v[246:247], s[22:23], 0, v[136:137]
	ds_read_b128 v[208:211], v182 offset:32768
	ds_read_b128 v[212:215], v182 offset:33792
	ds_read_b128 v[216:219], v182 offset:34816
	ds_read_b128 v[220:223], v182 offset:35840
	ds_read_b128 v[224:227], v182 offset:36864
	ds_read_b128 v[228:231], v182 offset:37888
	ds_read_b128 v[232:235], v182 offset:38912
	ds_read_b128 v[236:239], v182 offset:39936
	global_load_lds_dwordx4 v[246:247], off
	v_lshl_add_u64 v[246:247], s[22:23], 0, v[132:133]
	s_mov_b32 m0, s35
	s_nop 0
	global_load_lds_dwordx4 v[246:247], off
	s_nop 0
	s_nop 0
	s_nop 0
	s_waitcnt vmcnt(8)
	s_waitcnt lgkmcnt(0)
	v_mfma_f32_16x16x32_bf16 v[126:129], v[142:145], v[208:211], v[126:129]
	v_mfma_f32_16x16x32_bf16 v[122:125], v[166:169], v[208:211], v[122:125]
	s_barrier
	s_setprio 1
	s_waitcnt lgkmcnt(0)
	v_mfma_f32_16x16x32_bf16 v[110:113], v[142:145], v[216:219], v[110:113]
	v_mfma_f32_16x16x32_bf16 v[106:109], v[166:169], v[216:219], v[106:109]
	v_mfma_f32_16x16x32_bf16 v[98:101], v[142:145], v[224:227], v[98:101]
	v_mfma_f32_16x16x32_bf16 v[90:93], v[166:169], v[224:227], v[90:93]
	v_mfma_f32_16x16x32_bf16 v[82:85], v[142:145], v[232:235], v[82:85]
	v_mfma_f32_16x16x32_bf16 v[74:77], v[166:169], v[232:235], v[74:77]
	v_mfma_f32_16x16x32_bf16 v[126:129], v[162:165], v[212:215], v[126:129]
	v_mfma_f32_16x16x32_bf16 v[122:125], v[170:173], v[212:215], v[122:125]
	v_mfma_f32_16x16x32_bf16 v[110:113], v[162:165], v[220:223], v[110:113]
	v_mfma_f32_16x16x32_bf16 v[106:109], v[170:173], v[220:223], v[106:109]
	v_mfma_f32_16x16x32_bf16 v[98:101], v[162:165], v[228:231], v[98:101]
	v_mfma_f32_16x16x32_bf16 v[90:93], v[170:173], v[228:231], v[90:93]
	v_mfma_f32_16x16x32_bf16 v[82:85], v[162:165], v[236:239], v[82:85]
	v_mfma_f32_16x16x32_bf16 v[74:77], v[170:173], v[236:239], v[74:77]
	s_setprio 0
	s_setprio 1
	v_mfma_f32_16x16x32_bf16 v[118:121], v[174:177], v[208:211], v[118:121]
	v_mfma_f32_16x16x32_bf16 v[114:117], v[184:187], v[208:211], v[114:117]
	v_mfma_f32_16x16x32_bf16 v[102:105], v[174:177], v[216:219], v[102:105]
	v_mfma_f32_16x16x32_bf16 v[94:97], v[184:187], v[216:219], v[94:97]
	v_mfma_f32_16x16x32_bf16 v[86:89], v[174:177], v[224:227], v[86:89]
	v_mfma_f32_16x16x32_bf16 v[78:81], v[184:187], v[224:227], v[78:81]
	v_mfma_f32_16x16x32_bf16 v[70:73], v[174:177], v[232:235], v[70:73]
	v_mfma_f32_16x16x32_bf16 v[66:69], v[184:187], v[232:235], v[66:69]
	v_mfma_f32_16x16x32_bf16 v[118:121], v[178:181], v[212:215], v[118:121]
	v_mfma_f32_16x16x32_bf16 v[114:117], v[188:191], v[212:215], v[114:117]
	v_mfma_f32_16x16x32_bf16 v[102:105], v[178:181], v[220:223], v[102:105]
	v_mfma_f32_16x16x32_bf16 v[94:97], v[188:191], v[220:223], v[94:97]
	v_mfma_f32_16x16x32_bf16 v[86:89], v[178:181], v[228:231], v[86:89]
	v_mfma_f32_16x16x32_bf16 v[78:81], v[188:191], v[228:231], v[78:81]
	v_mfma_f32_16x16x32_bf16 v[70:73], v[178:181], v[236:239], v[70:73]
	v_mfma_f32_16x16x32_bf16 v[66:69], v[188:191], v[236:239], v[66:69]
	s_setprio 0
	s_barrier
; #define PG8_STAGE(bufoff, gbase, voff) do { _Pragma("unroll") for (int _i = 0; _i < 2; ++_i) \
;         __builtin_amdgcn_global_load_lds((const unsigned*)((const char*)(gbase) + (voff)[_i]), (LAS unsigned*)(lds + (bufoff) + ldsw + _i * 8192), 16, 0, 0); } while (0)
; #define PG8_LDA(dst, b, h) do { _Pragma("unroll") for (int m = 0; m < 4; ++m) _Pragma("unroll") for (int k = 0; k < 2; ++k) dst[m][k] = *(const LAS bf16x8*)(lds + PG8_SA(b, h) + aoff + m * 2048 + k * 1024); } while (0)
; #define PG8_MMA(ai, bj, At, Bt) do { __builtin_amdgcn_s_setprio(1); _Pragma("unroll") for (int m = 0; m < 4; ++m) _Pragma("unroll") for (int n = 0; n < 2; ++n) _Pragma("unroll") for (int k = 0; k < 2; ++k) \
;         acc[ai][bj][m][n] = __builtin_amdgcn_mfma_f32_16x16x32_bf16(Bt[n][k], At[m][k], acc[ai][bj][m][n], 0, 0, 0); __builtin_amdgcn_s_setprio(0); } while (0)
; #define PG8_WAIT_V(n) asm volatile("s_waitcnt vmcnt(" #n ")" ::: "memory")
; #define PG8_WAIT_L(n) asm volatile("s_waitcnt lgkmcnt(" #n ")" ::: "memory")
; #define PG8_BAR __builtin_amdgcn_s_barrier()
; #define PG8_SCHED __builtin_amdgcn_sched_barrier(0)
; template <class Epi, class Sched>
; __device__ __forceinline__ void gemm_phase(LAS unsigned char* lds, const Gemm g, const Sched& S, const Epi& E) {
;     ...
;             PG8_LDA(At, 1, 1); PG8_STAGE(PG8_SB(1, 0), b3, voffB); PG8_STAGE(PG8_SB(1, 1), b3 + hstepB, voffB); PG8_STAGE(PG8_SA(1, 0), a3, voffA);
;             PG8_WAIT_V(8); PG8_WAIT_L(0); PG8_BAR; PG8_MMA(1, 0, At, B0); PG8_MMA(1, 1, At, B1); PG8_BAR; PG8_SCHED;
;         }
	s_add_i32 s22, s47, s30
	v_lshl_add_u64 v[192:193], v[192:193], 0, s[56:57]
	s_mov_b32 m0, s22
	ds_read_b128 v[208:211], v182 offset:49152
	ds_read_b128 v[212:215], v182 offset:50176
	ds_read_b128 v[216:219], v182 offset:51200
	ds_read_b128 v[220:223], v182 offset:52224
	ds_read_b128 v[224:227], v182 offset:53248
	ds_read_b128 v[228:231], v182 offset:54272
	ds_read_b128 v[232:235], v182 offset:55296
	ds_read_b128 v[236:239], v182 offset:56320
	global_load_lds_dwordx4 v[192:193], off
	s_add_i32 m0, s22, 0x2000
	s_add_u32 s20, s20, 0x80080
	v_lshl_add_u64 v[192:193], v[240:241], 0, s[56:57]
	s_addc_u32 s21, s21, 0
	s_add_i32 s22, s48, s30
	global_load_lds_dwordx4 v[192:193], off
	v_lshl_add_u64 v[192:193], s[20:21], 0, v[134:135]
	s_mov_b32 m0, s22
	s_nop 0
	global_load_lds_dwordx4 v[192:193], off
	v_lshl_add_u64 v[192:193], s[20:21], 0, v[130:131]
	s_add_i32 m0, s22, 0x2000
	s_nop 0
	global_load_lds_dwordx4 v[192:193], off
	v_lshl_add_u64 v[192:193], v[242:243], 0, s[56:57]
	s_mov_b32 m0, s40
	s_nop 0
	global_load_lds_dwordx4 v[192:193], off
	v_lshl_add_u64 v[192:193], v[244:245], 0, s[56:57]
	s_mov_b32 m0, s41
	s_nop 0
	global_load_lds_dwordx4 v[192:193], off
	s_nop 0
	s_nop 0
	s_waitcnt vmcnt(8)
	s_waitcnt lgkmcnt(0)
	v_mfma_f32_16x16x32_bf16 v[62:65], v[142:145], v[208:211], v[62:65]
	v_mfma_f32_16x16x32_bf16 v[58:61], v[166:169], v[208:211], v[58:61]
	s_barrier
	s_setprio 1
	s_waitcnt lgkmcnt(0)
	v_mfma_f32_16x16x32_bf16 v[50:53], v[142:145], v[216:219], v[50:53]
	v_mfma_f32_16x16x32_bf16 v[42:45], v[166:169], v[216:219], v[42:45]
	v_mfma_f32_16x16x32_bf16 v[34:37], v[142:145], v[224:227], v[34:37]
	v_mfma_f32_16x16x32_bf16 v[26:29], v[166:169], v[224:227], v[26:29]
	v_mfma_f32_16x16x32_bf16 v[18:21], v[142:145], v[232:235], v[18:21]
	v_mfma_f32_16x16x32_bf16 v[10:13], v[166:169], v[232:235], v[10:13]
	v_mfma_f32_16x16x32_bf16 v[62:65], v[162:165], v[212:215], v[62:65]
	v_mfma_f32_16x16x32_bf16 v[58:61], v[170:173], v[212:215], v[58:61]
	v_mfma_f32_16x16x32_bf16 v[50:53], v[162:165], v[220:223], v[50:53]
	v_mfma_f32_16x16x32_bf16 v[42:45], v[170:173], v[220:223], v[42:45]
	v_mfma_f32_16x16x32_bf16 v[34:37], v[162:165], v[228:231], v[34:37]
	v_mfma_f32_16x16x32_bf16 v[26:29], v[170:173], v[228:231], v[26:29]
	v_mfma_f32_16x16x32_bf16 v[18:21], v[162:165], v[236:239], v[18:21]
	v_mfma_f32_16x16x32_bf16 v[10:13], v[170:173], v[236:239], v[10:13]
	s_setprio 0
	s_setprio 1
	v_mfma_f32_16x16x32_bf16 v[54:57], v[174:177], v[208:211], v[54:57]
	v_mfma_f32_16x16x32_bf16 v[46:49], v[184:187], v[208:211], v[46:49]
	v_mfma_f32_16x16x32_bf16 v[38:41], v[174:177], v[216:219], v[38:41]
	v_mfma_f32_16x16x32_bf16 v[30:33], v[184:187], v[216:219], v[30:33]
	v_mfma_f32_16x16x32_bf16 v[22:25], v[174:177], v[224:227], v[22:25]
	v_mfma_f32_16x16x32_bf16 v[14:17], v[184:187], v[224:227], v[14:17]
	v_mfma_f32_16x16x32_bf16 v[6:9], v[174:177], v[232:235], v[6:9]
	v_mfma_f32_16x16x32_bf16 v[2:5], v[184:187], v[232:235], v[2:5]
	v_mfma_f32_16x16x32_bf16 v[54:57], v[178:181], v[212:215], v[54:57]
	v_mfma_f32_16x16x32_bf16 v[46:49], v[188:191], v[212:215], v[46:49]
	v_mfma_f32_16x16x32_bf16 v[38:41], v[178:181], v[220:223], v[38:41]
	v_mfma_f32_16x16x32_bf16 v[30:33], v[188:191], v[220:223], v[30:33]
	v_mfma_f32_16x16x32_bf16 v[22:25], v[178:181], v[228:231], v[22:25]
	v_mfma_f32_16x16x32_bf16 v[14:17], v[188:191], v[228:231], v[14:17]
	v_mfma_f32_16x16x32_bf16 v[6:9], v[178:181], v[236:239], v[6:9]
	v_mfma_f32_16x16x32_bf16 v[2:5], v[188:191], v[236:239], v[2:5]
	s_setprio 0
	s_barrier
	s_add_i32 s46, s46, 2
	s_add_u32 s18, s18, 0x100
	s_addc_u32 s19, s19, 0
	s_add_u32 s25, s25, 0x100
	s_addc_u32 s45, s45, 0
	s_cmp_gt_u32 s46, 29
	s_cbranch_scc0 .LBB0_3415
	s_and_b64 vcc, exec, s[4:5]
	s_cbranch_vccz .LBB0_3418
	s_barrier

; #define PG8_STAGE(bufoff, gbase, voff) do { _Pragma("unroll") for (int _i = 0; _i < 2; ++_i) \
;         __builtin_amdgcn_global_load_lds((const unsigned*)((const char*)(gbase) + (voff)[_i]), (LAS unsigned*)(lds + (bufoff) + ldsw + _i * 8192), 16, 0, 0); } while (0)
; #define PG8_LDA(dst, b, h) do { _Pragma("unroll") for (int m = 0; m < 4; ++m) _Pragma("unroll") for (int k = 0; k < 2; ++k) dst[m][k] = *(const LAS bf16x8*)(lds + PG8_SA(b, h) + aoff + m * 2048 + k * 1024); } while (0)
; #define PG8_LDB(dst, b, h) do { _Pragma("unroll") for (int n = 0; n < 2; ++n) _Pragma("unroll") for (int k = 0; k < 2; ++k) dst[n][k] = *(const LAS bf16x8*)(lds + PG8_SB(b, h) + boff + n * 2048 + k * 1024); } while (0)
; #define PG8_MMA(ai, bj, At, Bt) do { __builtin_amdgcn_s_setprio(1); _Pragma("unroll") for (int m = 0; m < 4; ++m) _Pragma("unroll") for (int n = 0; n < 2; ++n) _Pragma("unroll") for (int k = 0; k < 2; ++k) \
;         acc[ai][bj][m][n] = __builtin_amdgcn_mfma_f32_16x16x32_bf16(Bt[n][k], At[m][k], acc[ai][bj][m][n], 0, 0, 0); __builtin_amdgcn_s_setprio(0); } while (0)
; #define PG8_WAIT_V(n) asm volatile("s_waitcnt vmcnt(" #n ")" ::: "memory")
; #define PG8_WAIT_L(n) asm volatile("s_waitcnt lgkmcnt(" #n ")" ::: "memory")
; #define PG8_BAR __builtin_amdgcn_s_barrier()
; #define PG8_SCHED __builtin_amdgcn_sched_barrier(0)
; template <class Epi, class Sched>
; __device__ __forceinline__ void gemm_phase(LAS unsigned char* lds, const Gemm g, const Sched& S, const Epi& E) {
;     ...
;             const bool last = (t == nt - 2);
;             const char* a1 = cA + (size_t)(t + 1) * kstep;
;             const char* a2 = last ? nA : cA + (size_t)(t + 2) * kstep; const char* b2 = last ? nB : cB + (size_t)(t + 2) * kstep;
;             const char* a3 = a2 + kstep; const char* b3 = b2 + kstep;
;             PG8_LDB(B0, 0, 0); PG8_LDB(B1, 0, 1); PG8_SCHED; PG8_LDA(At, 0, 0); PG8_STAGE(PG8_SA(1, 1), a1 + hstepA, voffA);
;             PG8_WAIT_V(8); PG8_WAIT_L(0); PG8_BAR; PG8_MMA(0, 0, At, B0); PG8_MMA(0, 1, At, B1); PG8_BAR; PG8_SCHED;
;             PG8_LDA(At, 0, 1); PG8_STAGE(PG8_SB(0, 0), b2, voffB); PG8_STAGE(PG8_SB(0, 1), b2 + hstepB, voffB); PG8_STAGE(PG8_SA(0, 0), a2, voffA);
.LBB0_3449:
	s_add_u32 s18, s16, 0xfff80080
	s_addc_u32 s19, s17, -1
	s_add_i32 s46, 0, 0x10000
	s_cmp_eq_u32 s45, 28
	s_cselect_b32 s21, s11, s19
	s_cselect_b32 s20, s41, s18
	v_add_u32_e32 v167, s46, v1
	s_cselect_b32 s19, s9, s44
	s_cselect_b32 s18, s42, s43
	s_add_i32 s48, 0, 0x14000
	s_waitcnt lgkmcnt(0)
	ds_read_b128 v[142:145], v167
	ds_read_b128 v[162:165], v167 offset:1024
	ds_read_b128 v[168:171], v167 offset:2048
	ds_read_b128 v[172:175], v167 offset:3072
	v_add_u32_e32 v167, s48, v1
	ds_read_b128 v[176:179], v167
	ds_read_b128 v[180:183], v167 offset:1024
	ds_read_b128 v[184:187], v167 offset:2048
	ds_read_b128 v[188:191], v167 offset:3072
	v_lshl_add_u64 v[192:193], s[16:17], 0, v[138:139]
	s_add_i32 m0, s27, 0xc000
	ds_read_b128 v[208:211], v166
	ds_read_b128 v[212:215], v166 offset:1024
	ds_read_b128 v[216:219], v166 offset:2048
	ds_read_b128 v[220:223], v166 offset:3072
	ds_read_b128 v[224:227], v166 offset:4096
	ds_read_b128 v[228:231], v166 offset:5120
	ds_read_b128 v[232:235], v166 offset:6144
	ds_read_b128 v[236:239], v166 offset:7168
	global_load_lds_dwordx4 v[192:193], off
	v_lshl_add_u64 v[192:193], s[16:17], 0, v[140:141]
	s_add_i32 m0, s27, 0xe000
	s_nop 0
	global_load_lds_dwordx4 v[192:193], off
	s_nop 0
	s_nop 0
	s_nop 0
	s_waitcnt vmcnt(8)
	s_waitcnt lgkmcnt(0)
	v_mfma_f32_16x16x32_bf16 v[126:129], v[142:145], v[208:211], v[126:129]
	v_mfma_f32_16x16x32_bf16 v[122:125], v[168:171], v[208:211], v[122:125]
	s_barrier
	s_setprio 1
	s_waitcnt lgkmcnt(0)
	v_mfma_f32_16x16x32_bf16 v[114:117], v[142:145], v[216:219], v[114:117]
	v_mfma_f32_16x16x32_bf16 v[106:109], v[168:171], v[216:219], v[106:109]
	v_mfma_f32_16x16x32_bf16 v[98:101], v[142:145], v[224:227], v[98:101]
	v_mfma_f32_16x16x32_bf16 v[90:93], v[168:171], v[224:227], v[90:93]
	v_mfma_f32_16x16x32_bf16 v[82:85], v[142:145], v[232:235], v[82:85]
	v_mfma_f32_16x16x32_bf16 v[74:77], v[168:171], v[232:235], v[74:77]
	v_mfma_f32_16x16x32_bf16 v[126:129], v[162:165], v[212:215], v[126:129]
	v_mfma_f32_16x16x32_bf16 v[122:125], v[172:175], v[212:215], v[122:125]
	v_mfma_f32_16x16x32_bf16 v[114:117], v[162:165], v[220:223], v[114:117]
	v_mfma_f32_16x16x32_bf16 v[106:109], v[172:175], v[220:223], v[106:109]
	v_mfma_f32_16x16x32_bf16 v[98:101], v[162:165], v[228:231], v[98:101]
	v_mfma_f32_16x16x32_bf16 v[90:93], v[172:175], v[228:231], v[90:93]
	v_mfma_f32_16x16x32_bf16 v[82:85], v[162:165], v[236:239], v[82:85]
	v_mfma_f32_16x16x32_bf16 v[74:77], v[172:175], v[236:239], v[74:77]
	s_setprio 0
	s_setprio 1
	v_mfma_f32_16x16x32_bf16 v[118:121], v[176:179], v[208:211], v[118:121]
	v_mfma_f32_16x16x32_bf16 v[110:113], v[184:187], v[208:211], v[110:113]
	v_mfma_f32_16x16x32_bf16 v[102:105], v[176:179], v[216:219], v[102:105]
	v_mfma_f32_16x16x32_bf16 v[94:97], v[184:187], v[216:219], v[94:97]
	v_mfma_f32_16x16x32_bf16 v[86:89], v[176:179], v[224:227], v[86:89]
	v_mfma_f32_16x16x32_bf16 v[78:81], v[184:187], v[224:227], v[78:81]
	v_mfma_f32_16x16x32_bf16 v[70:73], v[176:179], v[232:235], v[70:73]
	v_mfma_f32_16x16x32_bf16 v[66:69], v[184:187], v[232:235], v[66:69]
	v_mfma_f32_16x16x32_bf16 v[118:121], v[180:183], v[212:215], v[118:121]
	v_mfma_f32_16x16x32_bf16 v[110:113], v[188:191], v[212:215], v[110:113]
	v_mfma_f32_16x16x32_bf16 v[102:105], v[180:183], v[220:223], v[102:105]
	v_mfma_f32_16x16x32_bf16 v[94:97], v[188:191], v[220:223], v[94:97]
	v_mfma_f32_16x16x32_bf16 v[86:89], v[180:183], v[228:231], v[86:89]
	v_mfma_f32_16x16x32_bf16 v[78:81], v[188:191], v[228:231], v[78:81]
	v_mfma_f32_16x16x32_bf16 v[70:73], v[180:183], v[236:239], v[70:73]
	v_mfma_f32_16x16x32_bf16 v[66:69], v[188:191], v[236:239], v[66:69]
	s_setprio 0
	s_barrier
	s_add_i32 s46, s46, s26
	v_lshl_add_u64 v[192:193], s[18:19], 0, v[134:135]
	s_mov_b32 m0, s46
	ds_read_b128 v[208:211], v166 offset:16384
	ds_read_b128 v[212:215], v166 offset:17408
	ds_read_b128 v[216:219], v166 offset:18432
	ds_read_b128 v[220:223], v166 offset:19456
	ds_read_b128 v[224:227], v166 offset:20480
	ds_read_b128 v[228:231], v166 offset:21504
	ds_read_b128 v[232:235], v166 offset:22528
	ds_read_b128 v[236:239], v166 offset:23552
	global_load_lds_dwordx4 v[192:193], off
	s_add_i32 m0, s46, 0x2000
	s_add_u32 s46, s18, 0x80000
	v_lshl_add_u64 v[240:241], s[18:19], 0, v[130:131]
	s_addc_u32 s47, s19, 0
	s_add_i32 s48, s48, s26
	global_load_lds_dwordx4 v[240:241], off
	v_lshl_add_u64 v[242:243], s[46:47], 0, v[134:135]
	s_mov_b32 m0, s48
	v_lshl_add_u64 v[244:245], s[20:21], 0, v[132:133]
	global_load_lds_dwordx4 v[242:243], off
	v_lshl_add_u64 v[242:243], s[46:47], 0, v[130:131]
	s_add_i32 m0, s48, 0x2000
	s_nop 0
	global_load_lds_dwordx4 v[242:243], off
	v_lshl_add_u64 v[242:243], s[20:21], 0, v[136:137]
	s_mov_b32 m0, s27
	s_nop 0
	global_load_lds_dwordx4 v[242:243], off
	s_mov_b32 m0, s28
	s_nop 0
	global_load_lds_dwordx4 v[244:245], off
	s_nop 0
	s_nop 0
	s_nop 0
	s_waitcnt vmcnt(8)
	s_waitcnt lgkmcnt(0)
	v_mfma_f32_16x16x32_bf16 v[62:65], v[142:145], v[208:211], v[62:65]
	v_mfma_f32_16x16x32_bf16 v[58:61], v[168:171], v[208:211], v[58:61]
	s_barrier
; #define PG8_STAGE(bufoff, gbase, voff) do { _Pragma("unroll") for (int _i = 0; _i < 2; ++_i) \
;         __builtin_amdgcn_global_load_lds((const unsigned*)((const char*)(gbase) + (voff)[_i]), (LAS unsigned*)(lds + (bufoff) + ldsw + _i * 8192), 16, 0, 0); } while (0)
; #define PG8_LDA(dst, b, h) do { _Pragma("unroll") for (int m = 0; m < 4; ++m) _Pragma("unroll") for (int k = 0; k < 2; ++k) dst[m][k] = *(const LAS bf16x8*)(lds + PG8_SA(b, h) + aoff + m * 2048 + k * 1024); } while (0)
; #define PG8_LDB(dst, b, h) do { _Pragma("unroll") for (int n = 0; n < 2; ++n) _Pragma("unroll") for (int k = 0; k < 2; ++k) dst[n][k] = *(const LAS bf16x8*)(lds + PG8_SB(b, h) + boff + n * 2048 + k * 1024); } while (0)
; #define PG8_MMA(ai, bj, At, Bt) do { __builtin_amdgcn_s_setprio(1); _Pragma("unroll") for (int m = 0; m < 4; ++m) _Pragma("unroll") for (int n = 0; n < 2; ++n) _Pragma("unroll") for (int k = 0; k < 2; ++k) \
;         acc[ai][bj][m][n] = __builtin_amdgcn_mfma_f32_16x16x32_bf16(Bt[n][k], At[m][k], acc[ai][bj][m][n], 0, 0, 0); __builtin_amdgcn_s_setprio(0); } while (0)
; #define PG8_WAIT_V(n) asm volatile("s_waitcnt vmcnt(" #n ")" ::: "memory")
; #define PG8_WAIT_L(n) asm volatile("s_waitcnt lgkmcnt(" #n ")" ::: "memory")
; #define PG8_BAR __builtin_amdgcn_s_barrier()
; #define PG8_SCHED __builtin_amdgcn_sched_barrier(0)
; template <class Epi, class Sched>
; __device__ __forceinline__ void gemm_phase(LAS unsigned char* lds, const Gemm g, const Sched& S, const Epi& E) {
;     ...
;             PG8_WAIT_V(8); PG8_WAIT_L(0); PG8_BAR; PG8_MMA(1, 0, At, B0); PG8_MMA(1, 1, At, B1); PG8_BAR; PG8_SCHED;
;             PG8_LDB(B0, 1, 0); PG8_LDB(B1, 1, 1); PG8_SCHED; PG8_LDA(At, 1, 0); PG8_STAGE(PG8_SA(0, 1), a2 + hstepA, voffA);
;             PG8_WAIT_V(8); PG8_WAIT_L(0); PG8_BAR; PG8_MMA(0, 0, At, B0); PG8_MMA(0, 1, At, B1); PG8_BAR; PG8_SCHED;
	s_setprio 1
	s_waitcnt lgkmcnt(0)
	v_mfma_f32_16x16x32_bf16 v[50:53], v[142:145], v[216:219], v[50:53]
	v_mfma_f32_16x16x32_bf16 v[42:45], v[168:171], v[216:219], v[42:45]
	v_mfma_f32_16x16x32_bf16 v[34:37], v[142:145], v[224:227], v[34:37]
	v_mfma_f32_16x16x32_bf16 v[26:29], v[168:171], v[224:227], v[26:29]
	v_mfma_f32_16x16x32_bf16 v[18:21], v[142:145], v[232:235], v[18:21]
	v_mfma_f32_16x16x32_bf16 v[10:13], v[168:171], v[232:235], v[10:13]
	v_mfma_f32_16x16x32_bf16 v[62:65], v[162:165], v[212:215], v[62:65]
	v_mfma_f32_16x16x32_bf16 v[58:61], v[172:175], v[212:215], v[58:61]
	v_mfma_f32_16x16x32_bf16 v[50:53], v[162:165], v[220:223], v[50:53]
	v_mfma_f32_16x16x32_bf16 v[42:45], v[172:175], v[220:223], v[42:45]
	v_mfma_f32_16x16x32_bf16 v[34:37], v[162:165], v[228:231], v[34:37]
	v_mfma_f32_16x16x32_bf16 v[26:29], v[172:175], v[228:231], v[26:29]
	v_mfma_f32_16x16x32_bf16 v[18:21], v[162:165], v[236:239], v[18:21]
	v_mfma_f32_16x16x32_bf16 v[10:13], v[172:175], v[236:239], v[10:13]
	s_setprio 0
	s_setprio 1
	v_mfma_f32_16x16x32_bf16 v[54:57], v[176:179], v[208:211], v[54:57]
	v_mfma_f32_16x16x32_bf16 v[46:49], v[184:187], v[208:211], v[46:49]
	v_mfma_f32_16x16x32_bf16 v[38:41], v[176:179], v[216:219], v[38:41]
	v_mfma_f32_16x16x32_bf16 v[30:33], v[184:187], v[216:219], v[30:33]
	v_mfma_f32_16x16x32_bf16 v[22:25], v[176:179], v[224:227], v[22:25]
	v_mfma_f32_16x16x32_bf16 v[14:17], v[184:187], v[224:227], v[14:17]
	v_mfma_f32_16x16x32_bf16 v[6:9], v[176:179], v[232:235], v[6:9]
	v_mfma_f32_16x16x32_bf16 v[2:5], v[184:187], v[232:235], v[2:5]
	v_mfma_f32_16x16x32_bf16 v[54:57], v[180:183], v[212:215], v[54:57]
	v_mfma_f32_16x16x32_bf16 v[46:49], v[188:191], v[212:215], v[46:49]
	v_mfma_f32_16x16x32_bf16 v[38:41], v[180:183], v[220:223], v[38:41]
	v_mfma_f32_16x16x32_bf16 v[30:33], v[188:191], v[220:223], v[30:33]
	v_mfma_f32_16x16x32_bf16 v[22:25], v[180:183], v[228:231], v[22:25]
	v_mfma_f32_16x16x32_bf16 v[14:17], v[188:191], v[228:231], v[14:17]
	v_mfma_f32_16x16x32_bf16 v[6:9], v[180:183], v[236:239], v[6:9]
	v_mfma_f32_16x16x32_bf16 v[2:5], v[188:191], v[236:239], v[2:5]
	s_setprio 0
	s_barrier
	s_add_i32 s46, 0, 0x18000
	v_add_u32_e32 v167, s46, v1
	s_add_i32 s47, 0, 0x1c000
	ds_read_b128 v[142:145], v167
	ds_read_b128 v[162:165], v167 offset:1024
	ds_read_b128 v[168:171], v167 offset:2048
	ds_read_b128 v[172:175], v167 offset:3072
	v_add_u32_e32 v167, s47, v1
	ds_read_b128 v[176:179], v167
	ds_read_b128 v[180:183], v167 offset:1024
	ds_read_b128 v[184:187], v167 offset:2048
	ds_read_b128 v[188:191], v167 offset:3072
	s_add_u32 s20, s20, 0x80000
	s_addc_u32 s21, s21, 0
	s_mov_b32 m0, s29
	v_lshl_add_u64 v[246:247], s[20:21], 0, v[136:137]
	ds_read_b128 v[208:211], v166 offset:32768
	ds_read_b128 v[212:215], v166 offset:33792
	ds_read_b128 v[216:219], v166 offset:34816
	ds_read_b128 v[220:223], v166 offset:35840
	ds_read_b128 v[224:227], v166 offset:36864
	ds_read_b128 v[228:231], v166 offset:37888
	ds_read_b128 v[232:235], v166 offset:38912
	ds_read_b128 v[236:239], v166 offset:39936
	global_load_lds_dwordx4 v[246:247], off
	v_lshl_add_u64 v[246:247], s[20:21], 0, v[132:133]
	s_mov_b32 m0, s30
	s_nop 0
	global_load_lds_dwordx4 v[246:247], off
	s_nop 0
	s_nop 0
	s_nop 0
	s_waitcnt vmcnt(8)
	s_waitcnt lgkmcnt(0)
	v_mfma_f32_16x16x32_bf16 v[126:129], v[142:145], v[208:211], v[126:129]
	v_mfma_f32_16x16x32_bf16 v[122:125], v[168:171], v[208:211], v[122:125]
	s_barrier
	s_setprio 1
	s_waitcnt lgkmcnt(0)
	v_mfma_f32_16x16x32_bf16 v[114:117], v[142:145], v[216:219], v[114:117]
	v_mfma_f32_16x16x32_bf16 v[106:109], v[168:171], v[216:219], v[106:109]
	v_mfma_f32_16x16x32_bf16 v[98:101], v[142:145], v[224:227], v[98:101]
	v_mfma_f32_16x16x32_bf16 v[90:93], v[168:171], v[224:227], v[90:93]
	v_mfma_f32_16x16x32_bf16 v[82:85], v[142:145], v[232:235], v[82:85]
	v_mfma_f32_16x16x32_bf16 v[74:77], v[168:171], v[232:235], v[74:77]
	v_mfma_f32_16x16x32_bf16 v[126:129], v[162:165], v[212:215], v[126:129]
	v_mfma_f32_16x16x32_bf16 v[122:125], v[172:175], v[212:215], v[122:125]
	v_mfma_f32_16x16x32_bf16 v[114:117], v[162:165], v[220:223], v[114:117]
	v_mfma_f32_16x16x32_bf16 v[106:109], v[172:175], v[220:223], v[106:109]
	v_mfma_f32_16x16x32_bf16 v[98:101], v[162:165], v[228:231], v[98:101]
	v_mfma_f32_16x16x32_bf16 v[90:93], v[172:175], v[228:231], v[90:93]
	v_mfma_f32_16x16x32_bf16 v[82:85], v[162:165], v[236:239], v[82:85]
	v_mfma_f32_16x16x32_bf16 v[74:77], v[172:175], v[236:239], v[74:77]
	s_setprio 0
	s_setprio 1
	v_mfma_f32_16x16x32_bf16 v[118:121], v[176:179], v[208:211], v[118:121]
	v_mfma_f32_16x16x32_bf16 v[110:113], v[184:187], v[208:211], v[110:113]
	v_mfma_f32_16x16x32_bf16 v[102:105], v[176:179], v[216:219], v[102:105]
	v_mfma_f32_16x16x32_bf16 v[94:97], v[184:187], v[216:219], v[94:97]
	v_mfma_f32_16x16x32_bf16 v[86:89], v[176:179], v[224:227], v[86:89]
	v_mfma_f32_16x16x32_bf16 v[78:81], v[184:187], v[224:227], v[78:81]
	v_mfma_f32_16x16x32_bf16 v[70:73], v[176:179], v[232:235], v[70:73]
	v_mfma_f32_16x16x32_bf16 v[66:69], v[184:187], v[232:235], v[66:69]
	v_mfma_f32_16x16x32_bf16 v[118:121], v[180:183], v[212:215], v[118:121]
	v_mfma_f32_16x16x32_bf16 v[110:113], v[188:191], v[212:215], v[110:113]
	v_mfma_f32_16x16x32_bf16 v[102:105], v[180:183], v[220:223], v[102:105]
	v_mfma_f32_16x16x32_bf16 v[94:97], v[188:191], v[220:223], v[94:97]
	v_mfma_f32_16x16x32_bf16 v[86:89], v[180:183], v[228:231], v[86:89]
	v_mfma_f32_16x16x32_bf16 v[78:81], v[188:191], v[228:231], v[78:81]
	v_mfma_f32_16x16x32_bf16 v[70:73], v[180:183], v[236:239], v[70:73]
	v_mfma_f32_16x16x32_bf16 v[66:69], v[188:191], v[236:239], v[66:69]
	s_setprio 0
	s_barrier
; #define PG8_STAGE(bufoff, gbase, voff) do { _Pragma("unroll") for (int _i = 0; _i < 2; ++_i) \
;         __builtin_amdgcn_global_load_lds((const unsigned*)((const char*)(gbase) + (voff)[_i]), (LAS unsigned*)(lds + (bufoff) + ldsw + _i * 8192), 16, 0, 0); } while (0)
; #define PG8_LDA(dst, b, h) do { _Pragma("unroll") for (int m = 0; m < 4; ++m) _Pragma("unroll") for (int k = 0; k < 2; ++k) dst[m][k] = *(const LAS bf16x8*)(lds + PG8_SA(b, h) + aoff + m * 2048 + k * 1024); } while (0)
; #define PG8_MMA(ai, bj, At, Bt) do { __builtin_amdgcn_s_setprio(1); _Pragma("unroll") for (int m = 0; m < 4; ++m) _Pragma("unroll") for (int n = 0; n < 2; ++n) _Pragma("unroll") for (int k = 0; k < 2; ++k) \
;         acc[ai][bj][m][n] = __builtin_amdgcn_mfma_f32_16x16x32_bf16(Bt[n][k], At[m][k], acc[ai][bj][m][n], 0, 0, 0); __builtin_amdgcn_s_setprio(0); } while (0)
; #define PG8_WAIT_V(n) asm volatile("s_waitcnt vmcnt(" #n ")" ::: "memory")
; #define PG8_WAIT_L(n) asm volatile("s_waitcnt lgkmcnt(" #n ")" ::: "memory")
; #define PG8_BAR __builtin_amdgcn_s_barrier()
; #define PG8_SCHED __builtin_amdgcn_sched_barrier(0)
; template <class Epi, class Sched>
; __device__ __forceinline__ void gemm_phase(LAS unsigned char* lds, const Gemm g, const Sched& S, const Epi& E) {
;     ...
;             PG8_LDA(At, 1, 1); PG8_STAGE(PG8_SB(1, 0), b3, voffB); PG8_STAGE(PG8_SB(1, 1), b3 + hstepB, voffB); PG8_STAGE(PG8_SA(1, 0), a3, voffA);
;             PG8_WAIT_V(8); PG8_WAIT_L(0); PG8_BAR; PG8_MMA(1, 0, At, B0); PG8_MMA(1, 1, At, B1); PG8_BAR; PG8_SCHED;
;         }
;         if (wr == 0) PG8_BAR;
	s_add_i32 s20, s46, s26
	v_lshl_add_u64 v[192:193], v[192:193], 0, s[56:57]
	s_mov_b32 m0, s20
	ds_read_b128 v[208:211], v166 offset:49152
	ds_read_b128 v[212:215], v166 offset:50176
	ds_read_b128 v[216:219], v166 offset:51200
	ds_read_b128 v[220:223], v166 offset:52224
	ds_read_b128 v[224:227], v166 offset:53248
	ds_read_b128 v[228:231], v166 offset:54272
	ds_read_b128 v[232:235], v166 offset:55296
	ds_read_b128 v[236:239], v166 offset:56320
	global_load_lds_dwordx4 v[192:193], off
	s_add_i32 m0, s20, 0x2000
	s_add_u32 s18, s18, 0x80080
	v_lshl_add_u64 v[192:193], v[240:241], 0, s[56:57]
	s_addc_u32 s19, s19, 0
	s_add_i32 s20, s47, s26
	global_load_lds_dwordx4 v[192:193], off
	v_lshl_add_u64 v[192:193], s[18:19], 0, v[134:135]
	s_mov_b32 m0, s20
	s_nop 0
	global_load_lds_dwordx4 v[192:193], off
	v_lshl_add_u64 v[192:193], s[18:19], 0, v[130:131]
	s_add_i32 m0, s20, 0x2000
	s_nop 0
	global_load_lds_dwordx4 v[192:193], off
	v_lshl_add_u64 v[192:193], v[242:243], 0, s[56:57]
	s_mov_b32 m0, s34
	s_nop 0
	global_load_lds_dwordx4 v[192:193], off
	v_lshl_add_u64 v[192:193], v[244:245], 0, s[56:57]
	s_mov_b32 m0, s35
	s_nop 0
	global_load_lds_dwordx4 v[192:193], off
	s_nop 0
	s_nop 0
	s_waitcnt vmcnt(8)
	s_waitcnt lgkmcnt(0)
	v_mfma_f32_16x16x32_bf16 v[62:65], v[142:145], v[208:211], v[62:65]
	v_mfma_f32_16x16x32_bf16 v[58:61], v[168:171], v[208:211], v[58:61]
	s_barrier
	s_setprio 1
	s_waitcnt lgkmcnt(0)
	v_mfma_f32_16x16x32_bf16 v[50:53], v[142:145], v[216:219], v[50:53]
	v_mfma_f32_16x16x32_bf16 v[42:45], v[168:171], v[216:219], v[42:45]
	v_mfma_f32_16x16x32_bf16 v[34:37], v[142:145], v[224:227], v[34:37]
	v_mfma_f32_16x16x32_bf16 v[26:29], v[168:171], v[224:227], v[26:29]
	v_mfma_f32_16x16x32_bf16 v[18:21], v[142:145], v[232:235], v[18:21]
	v_mfma_f32_16x16x32_bf16 v[10:13], v[168:171], v[232:235], v[10:13]
	v_mfma_f32_16x16x32_bf16 v[62:65], v[162:165], v[212:215], v[62:65]
	v_mfma_f32_16x16x32_bf16 v[58:61], v[172:175], v[212:215], v[58:61]
	v_mfma_f32_16x16x32_bf16 v[50:53], v[162:165], v[220:223], v[50:53]
	v_mfma_f32_16x16x32_bf16 v[42:45], v[172:175], v[220:223], v[42:45]
	v_mfma_f32_16x16x32_bf16 v[34:37], v[162:165], v[228:231], v[34:37]
	v_mfma_f32_16x16x32_bf16 v[26:29], v[172:175], v[228:231], v[26:29]
	v_mfma_f32_16x16x32_bf16 v[18:21], v[162:165], v[236:239], v[18:21]
	v_mfma_f32_16x16x32_bf16 v[10:13], v[172:175], v[236:239], v[10:13]
	s_setprio 0
	s_setprio 1
	v_mfma_f32_16x16x32_bf16 v[54:57], v[176:179], v[208:211], v[54:57]
	v_mfma_f32_16x16x32_bf16 v[46:49], v[184:187], v[208:211], v[46:49]
	v_mfma_f32_16x16x32_bf16 v[38:41], v[176:179], v[216:219], v[38:41]
	v_mfma_f32_16x16x32_bf16 v[30:33], v[184:187], v[216:219], v[30:33]
	v_mfma_f32_16x16x32_bf16 v[22:25], v[176:179], v[224:227], v[22:25]
	v_mfma_f32_16x16x32_bf16 v[14:17], v[184:187], v[224:227], v[14:17]
	v_mfma_f32_16x16x32_bf16 v[6:9], v[176:179], v[232:235], v[6:9]
	v_mfma_f32_16x16x32_bf16 v[2:5], v[184:187], v[232:235], v[2:5]
	v_mfma_f32_16x16x32_bf16 v[54:57], v[180:183], v[212:215], v[54:57]
	v_mfma_f32_16x16x32_bf16 v[46:49], v[188:191], v[212:215], v[46:49]
	v_mfma_f32_16x16x32_bf16 v[38:41], v[180:183], v[220:223], v[38:41]
	v_mfma_f32_16x16x32_bf16 v[30:33], v[188:191], v[220:223], v[30:33]
	v_mfma_f32_16x16x32_bf16 v[22:25], v[180:183], v[228:231], v[22:25]
	v_mfma_f32_16x16x32_bf16 v[14:17], v[188:191], v[228:231], v[14:17]
	v_mfma_f32_16x16x32_bf16 v[6:9], v[180:183], v[236:239], v[6:9]
	v_mfma_f32_16x16x32_bf16 v[2:5], v[188:191], v[236:239], v[2:5]
	s_setprio 0
	s_barrier
	s_add_i32 s45, s45, 2
	s_add_u32 s16, s16, 0x100
	s_addc_u32 s17, s17, 0
	s_add_u32 s43, s43, 0x100
	s_addc_u32 s44, s44, 0
	s_cmp_gt_u32 s45, 29
	s_cbranch_scc0 .LBB0_3449
	s_and_b64 vcc, exec, s[6:7]
	s_cbranch_vccz .LBB0_3452
	s_barrier

; #define PG8_STAGE(bufoff, gbase, voff) do { _Pragma("unroll") for (int _i = 0; _i < 2; ++_i) \
;         __builtin_amdgcn_global_load_lds((const unsigned*)((const char*)(gbase) + (voff)[_i]), (LAS unsigned*)(lds + (bufoff) + ldsw + _i * 8192), 16, 0, 0); } while (0)
; #define PG8_LDA(dst, b, h) do { _Pragma("unroll") for (int m = 0; m < 4; ++m) _Pragma("unroll") for (int k = 0; k < 2; ++k) dst[m][k] = *(const LAS bf16x8*)(lds + PG8_SA(b, h) + aoff + m * 2048 + k * 1024); } while (0)
; #define PG8_LDB(dst, b, h) do { _Pragma("unroll") for (int n = 0; n < 2; ++n) _Pragma("unroll") for (int k = 0; k < 2; ++k) dst[n][k] = *(const LAS bf16x8*)(lds + PG8_SB(b, h) + boff + n * 2048 + k * 1024); } while (0)
; #define PG8_MMA(ai, bj, At, Bt) do { __builtin_amdgcn_s_setprio(1); _Pragma("unroll") for (int m = 0; m < 4; ++m) _Pragma("unroll") for (int n = 0; n < 2; ++n) _Pragma("unroll") for (int k = 0; k < 2; ++k) \
;         acc[ai][bj][m][n] = __builtin_amdgcn_mfma_f32_16x16x32_bf16(Bt[n][k], At[m][k], acc[ai][bj][m][n], 0, 0, 0); __builtin_amdgcn_s_setprio(0); } while (0)
; #define PG8_WAIT_V(n) asm volatile("s_waitcnt vmcnt(" #n ")" ::: "memory")
; template <class Epi, class Sched>
; __device__ __forceinline__ void gemm_phase(LAS unsigned char* lds, const Gemm g, const Sched& S, const Epi& E) {
;     ...
;         const bool has_next = S.next(ui + 1, nxt);
;         const char* nA = has_next ? (const char*)g.A + (size_t)nxt.pm * tstepA : cA; const char* nB = has_next ? (const char*)g.Bt + (size_t)nxt.pn * tstepB : cB;
;         for (int t = 0; t < nt; t += 2) {
;             const bool last = (t == nt - 2);
;             const char* a1 = cA + (size_t)(t + 1) * kstep;
;             const char* a2 = last ? nA : cA + (size_t)(t + 2) * kstep; const char* b2 = last ? nB : cB + (size_t)(t + 2) * kstep;
;             const char* a3 = a2 + kstep; const char* b3 = b2 + kstep;
;             PG8_LDB(B0, 0, 0); PG8_LDB(B1, 0, 1); PG8_SCHED; PG8_LDA(At, 0, 0); PG8_STAGE(PG8_SA(1, 1), a1 + hstepA, voffA);
;             PG8_WAIT_V(8); PG8_WAIT_L(0); PG8_BAR; PG8_MMA(0, 0, At, B0); PG8_MMA(0, 1, At, B1); PG8_BAR; PG8_SCHED;
;             PG8_LDA(At, 0, 1); PG8_STAGE(PG8_SB(0, 0), b2, voffB); PG8_STAGE(PG8_SB(0, 1), b2 + hstepB, voffB); PG8_STAGE(PG8_SA(0, 0), a2, voffA);
;             PG8_WAIT_V(8); PG8_WAIT_L(0); PG8_BAR; PG8_MMA(1, 0, At, B0); PG8_MMA(1, 1, At, B1); PG8_BAR; PG8_SCHED;
.LBB0_3538:
	s_add_u32 s23, s16, s22
	s_addc_u32 s28, s17, 0
	s_add_u32 s26, s23, 0x100
	s_addc_u32 s27, s28, 0
	s_and_b64 s[24:25], s[20:21], exec
	s_cselect_b32 s25, s7, s27
	s_cselect_b32 s24, s49, s26
	s_add_u32 s22, s14, s22
	s_addc_u32 s26, s15, 0
	s_add_u32 s22, s22, 0x100
	s_addc_u32 s26, s26, 0
	s_add_i32 s59, 0, 0x10000
	s_and_b64 s[20:21], s[20:21], exec
	s_cselect_b32 s27, s9, s26
	s_cselect_b32 s26, s50, s22
	s_add_i32 s21, 0, 0x14000
	s_add_u32 s30, s23, 0x10080
	s_addc_u32 s31, s28, 0
	s_add_i32 s58, s59, s38
	s_add_i32 m0, s39, 0xc000
	s_add_i32 s61, s39, 0xe000
	s_add_i32 s55, s58, 0x2000
	v_add_u32_e32 v138, s59, v1
	s_add_u32 s28, s26, 0x10000
	s_waitcnt lgkmcnt(0)
	ds_read_b128 v[142:145], v138
	ds_read_b128 v[162:165], v138 offset:1024
	ds_read_b128 v[166:169], v138 offset:2048
	ds_read_b128 v[170:173], v138 offset:3072
	v_add_u32_e32 v138, s21, v1
	s_addc_u32 s29, s27, 0
	s_add_i32 s57, s21, s38
	ds_read_b128 v[174:177], v138
	ds_read_b128 v[178:181], v138 offset:1024
	ds_read_b128 v[182:185], v138 offset:2048
	ds_read_b128 v[186:189], v138 offset:3072
	s_add_i32 s56, s57, 0x2000
	s_add_i32 s54, 0, 0x18000
	s_add_i32 s53, 0, 0x1c000
	s_add_u32 s22, s24, 0x10000
	s_addc_u32 s23, s25, 0
	s_add_i32 s52, s54, s38
	s_add_i32 s51, s52, 0x2000
	s_add_u32 s20, s26, 0x10080
	s_addc_u32 s21, s27, 0
	s_add_i32 s60, s53, s38
	s_add_i32 s59, s60, 0x2000
	v_lshl_add_u64 v[138:139], s[30:31], 0, v[136:137]
	ds_read_b128 v[190:193], v140
	ds_read_b128 v[208:211], v140 offset:1024
	ds_read_b128 v[212:215], v140 offset:2048
	ds_read_b128 v[216:219], v140 offset:3072
	ds_read_b128 v[220:223], v140 offset:4096
	ds_read_b128 v[224:227], v140 offset:5120
	ds_read_b128 v[228:231], v140 offset:6144
	ds_read_b128 v[232:235], v140 offset:7168
	global_load_lds_dwordx4 v[138:139], off
	v_lshl_add_u64 v[138:139], s[30:31], 0, v[132:133]
	s_mov_b32 m0, s61
	s_nop 0
	global_load_lds_dwordx4 v[138:139], off
	s_nop 0
	s_nop 0
	s_nop 0
	s_waitcnt vmcnt(8)
	s_waitcnt lgkmcnt(0)
	v_mfma_f32_16x16x32_bf16 v[126:129], v[142:145], v[190:193], v[126:129]
	v_mfma_f32_16x16x32_bf16 v[122:125], v[166:169], v[190:193], v[122:125]
	s_barrier
	s_setprio 1
	s_waitcnt lgkmcnt(0)
	v_mfma_f32_16x16x32_bf16 v[114:117], v[142:145], v[212:215], v[114:117]
	v_mfma_f32_16x16x32_bf16 v[106:109], v[166:169], v[212:215], v[106:109]
	v_mfma_f32_16x16x32_bf16 v[98:101], v[142:145], v[220:223], v[98:101]
	v_mfma_f32_16x16x32_bf16 v[90:93], v[166:169], v[220:223], v[90:93]
	v_mfma_f32_16x16x32_bf16 v[78:81], v[142:145], v[228:231], v[78:81]
	v_mfma_f32_16x16x32_bf16 v[74:77], v[166:169], v[228:231], v[74:77]
	v_mfma_f32_16x16x32_bf16 v[126:129], v[162:165], v[208:211], v[126:129]
	v_mfma_f32_16x16x32_bf16 v[122:125], v[170:173], v[208:211], v[122:125]
	v_mfma_f32_16x16x32_bf16 v[114:117], v[162:165], v[216:219], v[114:117]
	v_mfma_f32_16x16x32_bf16 v[106:109], v[170:173], v[216:219], v[106:109]
	v_mfma_f32_16x16x32_bf16 v[98:101], v[162:165], v[224:227], v[98:101]
	v_mfma_f32_16x16x32_bf16 v[90:93], v[170:173], v[224:227], v[90:93]
	v_mfma_f32_16x16x32_bf16 v[78:81], v[162:165], v[232:235], v[78:81]
	v_mfma_f32_16x16x32_bf16 v[74:77], v[170:173], v[232:235], v[74:77]
	s_setprio 0
	s_setprio 1
	v_mfma_f32_16x16x32_bf16 v[118:121], v[174:177], v[190:193], v[118:121]
	v_mfma_f32_16x16x32_bf16 v[110:113], v[182:185], v[190:193], v[110:113]
	v_mfma_f32_16x16x32_bf16 v[102:105], v[174:177], v[212:215], v[102:105]
	v_mfma_f32_16x16x32_bf16 v[94:97], v[182:185], v[212:215], v[94:97]
	v_mfma_f32_16x16x32_bf16 v[86:89], v[174:177], v[220:223], v[86:89]
	v_mfma_f32_16x16x32_bf16 v[82:85], v[182:185], v[220:223], v[82:85]
	v_mfma_f32_16x16x32_bf16 v[70:73], v[174:177], v[228:231], v[70:73]
	v_mfma_f32_16x16x32_bf16 v[66:69], v[182:185], v[228:231], v[66:69]
	v_mfma_f32_16x16x32_bf16 v[118:121], v[178:181], v[208:211], v[118:121]
	v_mfma_f32_16x16x32_bf16 v[110:113], v[186:189], v[208:211], v[110:113]
	v_mfma_f32_16x16x32_bf16 v[102:105], v[178:181], v[216:219], v[102:105]
	v_mfma_f32_16x16x32_bf16 v[94:97], v[186:189], v[216:219], v[94:97]
	v_mfma_f32_16x16x32_bf16 v[86:89], v[178:181], v[224:227], v[86:89]
	v_mfma_f32_16x16x32_bf16 v[82:85], v[186:189], v[224:227], v[82:85]
	v_mfma_f32_16x16x32_bf16 v[70:73], v[178:181], v[232:235], v[70:73]
	v_mfma_f32_16x16x32_bf16 v[66:69], v[186:189], v[232:235], v[66:69]
	s_setprio 0
	s_barrier
	s_mov_b32 m0, s58
	v_lshl_add_u64 v[138:139], s[26:27], 0, v[134:135]
	ds_read_b128 v[190:193], v140 offset:16384
	ds_read_b128 v[208:211], v140 offset:17408
	ds_read_b128 v[212:215], v140 offset:18432
	ds_read_b128 v[216:219], v140 offset:19456
	ds_read_b128 v[220:223], v140 offset:20480
	ds_read_b128 v[224:227], v140 offset:21504
	ds_read_b128 v[228:231], v140 offset:22528
	ds_read_b128 v[232:235], v140 offset:23552
	global_load_lds_dwordx4 v[138:139], off
	v_lshl_add_u64 v[236:237], s[26:27], 0, v[130:131]
	s_mov_b32 m0, s55
	v_lshl_add_u64 v[238:239], s[28:29], 0, v[134:135]
	global_load_lds_dwordx4 v[236:237], off
	s_mov_b32 m0, s57
	v_lshl_add_u64 v[240:241], s[24:25], 0, v[132:133]
	global_load_lds_dwordx4 v[238:239], off
	v_lshl_add_u64 v[238:239], s[28:29], 0, v[130:131]
	s_mov_b32 m0, s56
	s_nop 0
	global_load_lds_dwordx4 v[238:239], off
	v_lshl_add_u64 v[238:239], s[24:25], 0, v[136:137]
	s_mov_b32 m0, s39
	s_nop 0
	global_load_lds_dwordx4 v[238:239], off
	s_mov_b32 m0, s40
	s_nop 0
	global_load_lds_dwordx4 v[240:241], off
	s_nop 0
	s_nop 0
	s_waitcnt vmcnt(8)
	s_waitcnt lgkmcnt(0)
	v_mfma_f32_16x16x32_bf16 v[62:65], v[142:145], v[190:193], v[62:65]
	v_mfma_f32_16x16x32_bf16 v[58:61], v[166:169], v[190:193], v[58:61]
	s_barrier
; #define PG8_STAGE(bufoff, gbase, voff) do { _Pragma("unroll") for (int _i = 0; _i < 2; ++_i) \
;         __builtin_amdgcn_global_load_lds((const unsigned*)((const char*)(gbase) + (voff)[_i]), (LAS unsigned*)(lds + (bufoff) + ldsw + _i * 8192), 16, 0, 0); } while (0)
; #define PG8_LDA(dst, b, h) do { _Pragma("unroll") for (int m = 0; m < 4; ++m) _Pragma("unroll") for (int k = 0; k < 2; ++k) dst[m][k] = *(const LAS bf16x8*)(lds + PG8_SA(b, h) + aoff + m * 2048 + k * 1024); } while (0)
; #define PG8_LDB(dst, b, h) do { _Pragma("unroll") for (int n = 0; n < 2; ++n) _Pragma("unroll") for (int k = 0; k < 2; ++k) dst[n][k] = *(const LAS bf16x8*)(lds + PG8_SB(b, h) + boff + n * 2048 + k * 1024); } while (0)
; #define PG8_MMA(ai, bj, At, Bt) do { __builtin_amdgcn_s_setprio(1); _Pragma("unroll") for (int m = 0; m < 4; ++m) _Pragma("unroll") for (int n = 0; n < 2; ++n) _Pragma("unroll") for (int k = 0; k < 2; ++k) \
;         acc[ai][bj][m][n] = __builtin_amdgcn_mfma_f32_16x16x32_bf16(Bt[n][k], At[m][k], acc[ai][bj][m][n], 0, 0, 0); __builtin_amdgcn_s_setprio(0); } while (0)
; #define PG8_WAIT_V(n) asm volatile("s_waitcnt vmcnt(" #n ")" ::: "memory")
; #define PG8_WAIT_L(n) asm volatile("s_waitcnt lgkmcnt(" #n ")" ::: "memory")
; #define PG8_BAR __builtin_amdgcn_s_barrier()
; #define PG8_SCHED __builtin_amdgcn_sched_barrier(0)
; template <class Epi, class Sched>
; __device__ __forceinline__ void gemm_phase(LAS unsigned char* lds, const Gemm g, const Sched& S, const Epi& E) {
;     ...
;             PG8_WAIT_V(8); PG8_WAIT_L(0); PG8_BAR; PG8_MMA(1, 0, At, B0); PG8_MMA(1, 1, At, B1); PG8_BAR; PG8_SCHED;
;             PG8_LDB(B0, 1, 0); PG8_LDB(B1, 1, 1); PG8_SCHED; PG8_LDA(At, 1, 0); PG8_STAGE(PG8_SA(0, 1), a2 + hstepA, voffA);
;             PG8_WAIT_V(8); PG8_WAIT_L(0); PG8_BAR; PG8_MMA(0, 0, At, B0); PG8_MMA(0, 1, At, B1); PG8_BAR; PG8_SCHED;
	s_setprio 1
	s_waitcnt lgkmcnt(0)
	v_mfma_f32_16x16x32_bf16 v[50:53], v[142:145], v[212:215], v[50:53]
	v_mfma_f32_16x16x32_bf16 v[42:45], v[166:169], v[212:215], v[42:45]
	v_mfma_f32_16x16x32_bf16 v[34:37], v[142:145], v[220:223], v[34:37]
	v_mfma_f32_16x16x32_bf16 v[26:29], v[166:169], v[220:223], v[26:29]
	v_mfma_f32_16x16x32_bf16 v[18:21], v[142:145], v[228:231], v[18:21]
	v_mfma_f32_16x16x32_bf16 v[10:13], v[166:169], v[228:231], v[10:13]
	v_mfma_f32_16x16x32_bf16 v[62:65], v[162:165], v[208:211], v[62:65]
	v_mfma_f32_16x16x32_bf16 v[58:61], v[170:173], v[208:211], v[58:61]
	v_mfma_f32_16x16x32_bf16 v[50:53], v[162:165], v[216:219], v[50:53]
	v_mfma_f32_16x16x32_bf16 v[42:45], v[170:173], v[216:219], v[42:45]
	v_mfma_f32_16x16x32_bf16 v[34:37], v[162:165], v[224:227], v[34:37]
	v_mfma_f32_16x16x32_bf16 v[26:29], v[170:173], v[224:227], v[26:29]
	v_mfma_f32_16x16x32_bf16 v[18:21], v[162:165], v[232:235], v[18:21]
	v_mfma_f32_16x16x32_bf16 v[10:13], v[170:173], v[232:235], v[10:13]
	s_setprio 0
	s_setprio 1
	v_mfma_f32_16x16x32_bf16 v[54:57], v[174:177], v[190:193], v[54:57]
	v_mfma_f32_16x16x32_bf16 v[46:49], v[182:185], v[190:193], v[46:49]
	v_mfma_f32_16x16x32_bf16 v[38:41], v[174:177], v[212:215], v[38:41]
	v_mfma_f32_16x16x32_bf16 v[30:33], v[182:185], v[212:215], v[30:33]
	v_mfma_f32_16x16x32_bf16 v[22:25], v[174:177], v[220:223], v[22:25]
	v_mfma_f32_16x16x32_bf16 v[14:17], v[182:185], v[220:223], v[14:17]
	v_mfma_f32_16x16x32_bf16 v[6:9], v[174:177], v[228:231], v[6:9]
	v_mfma_f32_16x16x32_bf16 v[2:5], v[182:185], v[228:231], v[2:5]
	v_mfma_f32_16x16x32_bf16 v[54:57], v[178:181], v[208:211], v[54:57]
	v_mfma_f32_16x16x32_bf16 v[46:49], v[186:189], v[208:211], v[46:49]
	v_mfma_f32_16x16x32_bf16 v[38:41], v[178:181], v[216:219], v[38:41]
	v_mfma_f32_16x16x32_bf16 v[30:33], v[186:189], v[216:219], v[30:33]
	v_mfma_f32_16x16x32_bf16 v[22:25], v[178:181], v[224:227], v[22:25]
	v_mfma_f32_16x16x32_bf16 v[14:17], v[186:189], v[224:227], v[14:17]
	v_mfma_f32_16x16x32_bf16 v[6:9], v[178:181], v[232:235], v[6:9]
	v_mfma_f32_16x16x32_bf16 v[2:5], v[186:189], v[232:235], v[2:5]
	s_setprio 0
	s_barrier
	v_add_u32_e32 v141, s54, v1
	ds_read_b128 v[142:145], v141
	ds_read_b128 v[162:165], v141 offset:1024
	ds_read_b128 v[166:169], v141 offset:2048
	ds_read_b128 v[170:173], v141 offset:3072
	v_add_u32_e32 v141, s53, v1
	ds_read_b128 v[174:177], v141
	ds_read_b128 v[178:181], v141 offset:1024
	ds_read_b128 v[182:185], v141 offset:2048
	ds_read_b128 v[186:189], v141 offset:3072
	s_mov_b32 m0, s41
	v_lshl_add_u64 v[242:243], s[22:23], 0, v[136:137]
	ds_read_b128 v[190:193], v140 offset:32768
	ds_read_b128 v[208:211], v140 offset:33792
	ds_read_b128 v[212:215], v140 offset:34816
	ds_read_b128 v[216:219], v140 offset:35840
	ds_read_b128 v[220:223], v140 offset:36864
	ds_read_b128 v[224:227], v140 offset:37888
	ds_read_b128 v[228:231], v140 offset:38912
	ds_read_b128 v[232:235], v140 offset:39936
	global_load_lds_dwordx4 v[242:243], off
	v_lshl_add_u64 v[242:243], s[22:23], 0, v[132:133]
	s_mov_b32 m0, s42
	s_nop 0
	global_load_lds_dwordx4 v[242:243], off
	s_nop 0
	s_nop 0
	s_waitcnt vmcnt(8)
	s_waitcnt lgkmcnt(0)
	v_mfma_f32_16x16x32_bf16 v[126:129], v[142:145], v[190:193], v[126:129]
	v_mfma_f32_16x16x32_bf16 v[122:125], v[166:169], v[190:193], v[122:125]
	s_barrier
	s_setprio 1
	s_waitcnt lgkmcnt(0)
	v_mfma_f32_16x16x32_bf16 v[114:117], v[142:145], v[212:215], v[114:117]
	v_mfma_f32_16x16x32_bf16 v[106:109], v[166:169], v[212:215], v[106:109]
	v_mfma_f32_16x16x32_bf16 v[98:101], v[142:145], v[220:223], v[98:101]
	v_mfma_f32_16x16x32_bf16 v[90:93], v[166:169], v[220:223], v[90:93]
	v_mfma_f32_16x16x32_bf16 v[78:81], v[142:145], v[228:231], v[78:81]
	v_mfma_f32_16x16x32_bf16 v[74:77], v[166:169], v[228:231], v[74:77]
	v_mfma_f32_16x16x32_bf16 v[126:129], v[162:165], v[208:211], v[126:129]
	v_mfma_f32_16x16x32_bf16 v[122:125], v[170:173], v[208:211], v[122:125]
	v_mfma_f32_16x16x32_bf16 v[114:117], v[162:165], v[216:219], v[114:117]
	v_mfma_f32_16x16x32_bf16 v[106:109], v[170:173], v[216:219], v[106:109]
	v_mfma_f32_16x16x32_bf16 v[98:101], v[162:165], v[224:227], v[98:101]
	v_mfma_f32_16x16x32_bf16 v[90:93], v[170:173], v[224:227], v[90:93]
	v_mfma_f32_16x16x32_bf16 v[78:81], v[162:165], v[232:235], v[78:81]
	v_mfma_f32_16x16x32_bf16 v[74:77], v[170:173], v[232:235], v[74:77]
	s_setprio 0
	s_setprio 1
	v_mfma_f32_16x16x32_bf16 v[118:121], v[174:177], v[190:193], v[118:121]
	v_mfma_f32_16x16x32_bf16 v[110:113], v[182:185], v[190:193], v[110:113]
	v_mfma_f32_16x16x32_bf16 v[102:105], v[174:177], v[212:215], v[102:105]
	v_mfma_f32_16x16x32_bf16 v[94:97], v[182:185], v[212:215], v[94:97]
	v_mfma_f32_16x16x32_bf16 v[86:89], v[174:177], v[220:223], v[86:89]
	v_mfma_f32_16x16x32_bf16 v[82:85], v[182:185], v[220:223], v[82:85]
	v_mfma_f32_16x16x32_bf16 v[70:73], v[174:177], v[228:231], v[70:73]
	v_mfma_f32_16x16x32_bf16 v[66:69], v[182:185], v[228:231], v[66:69]
	v_mfma_f32_16x16x32_bf16 v[118:121], v[178:181], v[208:211], v[118:121]
	v_mfma_f32_16x16x32_bf16 v[110:113], v[186:189], v[208:211], v[110:113]
	v_mfma_f32_16x16x32_bf16 v[102:105], v[178:181], v[216:219], v[102:105]
	v_mfma_f32_16x16x32_bf16 v[94:97], v[186:189], v[216:219], v[94:97]
	v_mfma_f32_16x16x32_bf16 v[86:89], v[178:181], v[224:227], v[86:89]
	v_mfma_f32_16x16x32_bf16 v[82:85], v[186:189], v[224:227], v[82:85]
	v_mfma_f32_16x16x32_bf16 v[70:73], v[178:181], v[232:235], v[70:73]
	v_mfma_f32_16x16x32_bf16 v[66:69], v[186:189], v[232:235], v[66:69]
	s_setprio 0
	s_barrier
; #define PG8_STAGE(bufoff, gbase, voff) do { _Pragma("unroll") for (int _i = 0; _i < 2; ++_i) \
;         __builtin_amdgcn_global_load_lds((const unsigned*)((const char*)(gbase) + (voff)[_i]), (LAS unsigned*)(lds + (bufoff) + ldsw + _i * 8192), 16, 0, 0); } while (0)
; #define PG8_LDA(dst, b, h) do { _Pragma("unroll") for (int m = 0; m < 4; ++m) _Pragma("unroll") for (int k = 0; k < 2; ++k) dst[m][k] = *(const LAS bf16x8*)(lds + PG8_SA(b, h) + aoff + m * 2048 + k * 1024); } while (0)
; #define PG8_MMA(ai, bj, At, Bt) do { __builtin_amdgcn_s_setprio(1); _Pragma("unroll") for (int m = 0; m < 4; ++m) _Pragma("unroll") for (int n = 0; n < 2; ++n) _Pragma("unroll") for (int k = 0; k < 2; ++k) \
;         acc[ai][bj][m][n] = __builtin_amdgcn_mfma_f32_16x16x32_bf16(Bt[n][k], At[m][k], acc[ai][bj][m][n], 0, 0, 0); __builtin_amdgcn_s_setprio(0); } while (0)
; #define PG8_WAIT_V(n) asm volatile("s_waitcnt vmcnt(" #n ")" ::: "memory")
; #define PG8_WAIT_L(n) asm volatile("s_waitcnt lgkmcnt(" #n ")" ::: "memory")
; #define PG8_BAR __builtin_amdgcn_s_barrier()
; #define PG8_SCHED __builtin_amdgcn_sched_barrier(0)
; template <class Epi, class Sched>
; __device__ __forceinline__ void gemm_phase(LAS unsigned char* lds, const Gemm g, const Sched& S, const Epi& E) {
;     ...
;             PG8_LDA(At, 1, 1); PG8_STAGE(PG8_SB(1, 0), b3, voffB); PG8_STAGE(PG8_SB(1, 1), b3 + hstepB, voffB); PG8_STAGE(PG8_SA(1, 0), a3, voffA);
;             PG8_WAIT_V(8); PG8_WAIT_L(0); PG8_BAR; PG8_MMA(1, 0, At, B0); PG8_MMA(1, 1, At, B1); PG8_BAR; PG8_SCHED;
;         }
;         if (wr == 0) PG8_BAR;
	s_mov_b32 m0, s52
	v_lshl_add_u64 v[138:139], v[138:139], 0, s[64:65]
	ds_read_b128 v[190:193], v140 offset:49152
	ds_read_b128 v[208:211], v140 offset:50176
	ds_read_b128 v[212:215], v140 offset:51200
	ds_read_b128 v[216:219], v140 offset:52224
	ds_read_b128 v[220:223], v140 offset:53248
	ds_read_b128 v[224:227], v140 offset:54272
	ds_read_b128 v[228:231], v140 offset:55296
	ds_read_b128 v[232:235], v140 offset:56320
	global_load_lds_dwordx4 v[138:139], off
	v_lshl_add_u64 v[138:139], v[236:237], 0, s[64:65]
	s_mov_b32 m0, s51
	s_nop 0
	global_load_lds_dwordx4 v[138:139], off
	v_lshl_add_u64 v[138:139], s[20:21], 0, v[134:135]
	s_mov_b32 m0, s60
	s_nop 0
	global_load_lds_dwordx4 v[138:139], off
	v_lshl_add_u64 v[138:139], s[20:21], 0, v[130:131]
	s_mov_b32 m0, s59
	s_nop 0
	global_load_lds_dwordx4 v[138:139], off
	v_lshl_add_u64 v[138:139], v[238:239], 0, s[64:65]
	s_mov_b32 m0, s45
	s_nop 0
	global_load_lds_dwordx4 v[138:139], off
	v_lshl_add_u64 v[138:139], v[240:241], 0, s[64:65]
	s_mov_b32 m0, s46
	s_nop 0
	global_load_lds_dwordx4 v[138:139], off
	s_waitcnt vmcnt(8)
	s_waitcnt lgkmcnt(0)
	v_mfma_f32_16x16x32_bf16 v[62:65], v[142:145], v[190:193], v[62:65]
	v_mfma_f32_16x16x32_bf16 v[58:61], v[166:169], v[190:193], v[58:61]
	s_barrier
	s_setprio 1
	s_waitcnt lgkmcnt(0)
	v_mfma_f32_16x16x32_bf16 v[50:53], v[142:145], v[212:215], v[50:53]
	v_mfma_f32_16x16x32_bf16 v[42:45], v[166:169], v[212:215], v[42:45]
	v_mfma_f32_16x16x32_bf16 v[34:37], v[142:145], v[220:223], v[34:37]
	v_mfma_f32_16x16x32_bf16 v[26:29], v[166:169], v[220:223], v[26:29]
	v_mfma_f32_16x16x32_bf16 v[18:21], v[142:145], v[228:231], v[18:21]
	v_mfma_f32_16x16x32_bf16 v[10:13], v[166:169], v[228:231], v[10:13]
	v_mfma_f32_16x16x32_bf16 v[62:65], v[162:165], v[208:211], v[62:65]
	v_mfma_f32_16x16x32_bf16 v[58:61], v[170:173], v[208:211], v[58:61]
	v_mfma_f32_16x16x32_bf16 v[50:53], v[162:165], v[216:219], v[50:53]
	v_mfma_f32_16x16x32_bf16 v[42:45], v[170:173], v[216:219], v[42:45]
	v_mfma_f32_16x16x32_bf16 v[34:37], v[162:165], v[224:227], v[34:37]
	v_mfma_f32_16x16x32_bf16 v[26:29], v[170:173], v[224:227], v[26:29]
	v_mfma_f32_16x16x32_bf16 v[18:21], v[162:165], v[232:235], v[18:21]
	v_mfma_f32_16x16x32_bf16 v[10:13], v[170:173], v[232:235], v[10:13]
	s_setprio 0
	s_setprio 1
	v_mfma_f32_16x16x32_bf16 v[54:57], v[174:177], v[190:193], v[54:57]
	v_mfma_f32_16x16x32_bf16 v[46:49], v[182:185], v[190:193], v[46:49]
	v_mfma_f32_16x16x32_bf16 v[38:41], v[174:177], v[212:215], v[38:41]
	v_mfma_f32_16x16x32_bf16 v[30:33], v[182:185], v[212:215], v[30:33]
	v_mfma_f32_16x16x32_bf16 v[22:25], v[174:177], v[220:223], v[22:25]
	v_mfma_f32_16x16x32_bf16 v[14:17], v[182:185], v[220:223], v[14:17]
	v_mfma_f32_16x16x32_bf16 v[6:9], v[174:177], v[228:231], v[6:9]
	v_mfma_f32_16x16x32_bf16 v[2:5], v[182:185], v[228:231], v[2:5]
	v_mfma_f32_16x16x32_bf16 v[54:57], v[178:181], v[208:211], v[54:57]
	v_mfma_f32_16x16x32_bf16 v[46:49], v[186:189], v[208:211], v[46:49]
	v_mfma_f32_16x16x32_bf16 v[38:41], v[178:181], v[216:219], v[38:41]
	v_mfma_f32_16x16x32_bf16 v[30:33], v[186:189], v[216:219], v[30:33]
	v_mfma_f32_16x16x32_bf16 v[22:25], v[178:181], v[224:227], v[22:25]
	v_mfma_f32_16x16x32_bf16 v[14:17], v[186:189], v[224:227], v[14:17]
	v_mfma_f32_16x16x32_bf16 v[6:9], v[178:181], v[232:235], v[6:9]
	v_mfma_f32_16x16x32_bf16 v[2:5], v[186:189], v[232:235], v[2:5]
	s_setprio 0
	s_barrier
	s_movk_i32 s22, 0x100
	s_andn2_b64 vcc, exec, s[18:19]
	s_mov_b64 s[20:21], -1
	s_mov_b64 s[18:19], 0
	s_cbranch_vccz .LBB0_3538
	s_and_b64 vcc, exec, s[4:5]
	s_cbranch_vccz .LBB0_3541
	s_barrier

; #define PG8_STAGE(bufoff, gbase, voff) do { _Pragma("unroll") for (int _i = 0; _i < 2; ++_i) \
;         __builtin_amdgcn_global_load_lds((const unsigned*)((const char*)(gbase) + (voff)[_i]), (LAS unsigned*)(lds + (bufoff) + ldsw + _i * 8192), 16, 0, 0); } while (0)
; #define PG8_LDA(dst, b, h) do { _Pragma("unroll") for (int m = 0; m < 4; ++m) _Pragma("unroll") for (int k = 0; k < 2; ++k) dst[m][k] = *(const LAS bf16x8*)(lds + PG8_SA(b, h) + aoff + m * 2048 + k * 1024); } while (0)
; #define PG8_LDB(dst, b, h) do { _Pragma("unroll") for (int n = 0; n < 2; ++n) _Pragma("unroll") for (int k = 0; k < 2; ++k) dst[n][k] = *(const LAS bf16x8*)(lds + PG8_SB(b, h) + boff + n * 2048 + k * 1024); } while (0)
; #define PG8_MMA(ai, bj, At, Bt) do { __builtin_amdgcn_s_setprio(1); _Pragma("unroll") for (int m = 0; m < 4; ++m) _Pragma("unroll") for (int n = 0; n < 2; ++n) _Pragma("unroll") for (int k = 0; k < 2; ++k) \
;         acc[ai][bj][m][n] = __builtin_amdgcn_mfma_f32_16x16x32_bf16(Bt[n][k], At[m][k], acc[ai][bj][m][n], 0, 0, 0); __builtin_amdgcn_s_setprio(0); } while (0)
; #define PG8_WAIT_V(n) asm volatile("s_waitcnt vmcnt(" #n ")" ::: "memory")
; #define PG8_WAIT_L(n) asm volatile("s_waitcnt lgkmcnt(" #n ")" ::: "memory")
; #define PG8_BAR __builtin_amdgcn_s_barrier()
; #define PG8_SCHED __builtin_amdgcn_sched_barrier(0)
; template <class Epi, class Sched>
; __device__ __forceinline__ void gemm_phase(LAS unsigned char* lds, const Gemm g, const Sched& S, const Epi& E) {
;     ...
;         for (int t = 0; t < nt; t += 2) {
;             const bool last = (t == nt - 2);
;             const char* a1 = cA + (size_t)(t + 1) * kstep;
;             const char* a2 = last ? nA : cA + (size_t)(t + 2) * kstep; const char* b2 = last ? nB : cB + (size_t)(t + 2) * kstep;
;             const char* a3 = a2 + kstep; const char* b3 = b2 + kstep;
;             PG8_LDB(B0, 0, 0); PG8_LDB(B1, 0, 1); PG8_SCHED; PG8_LDA(At, 0, 0); PG8_STAGE(PG8_SA(1, 1), a1 + hstepA, voffA);
;             PG8_WAIT_V(8); PG8_WAIT_L(0); PG8_BAR; PG8_MMA(0, 0, At, B0); PG8_MMA(0, 1, At, B1); PG8_BAR; PG8_SCHED;
;             PG8_LDA(At, 0, 1); PG8_STAGE(PG8_SB(0, 0), b2, voffB); PG8_STAGE(PG8_SB(0, 1), b2 + hstepB, voffB); PG8_STAGE(PG8_SA(0, 0), a2, voffA);
;             PG8_WAIT_V(8); PG8_WAIT_L(0); PG8_BAR; PG8_MMA(1, 0, At, B0); PG8_MMA(1, 1, At, B1); PG8_BAR; PG8_SCHED;
.LBB0_3562:
	s_add_u32 s20, s18, 0xfff80080
	s_addc_u32 s21, s19, -1
	s_add_i32 s49, 0, 0x10000
	v_add_u32_e32 v83, s49, v1
	ds_read_b128 v[78:81], v83
	ds_read_b128 v[84:87], v83 offset:1024
	ds_read_b128 v[88:91], v83 offset:2048
	ds_read_b128 v[92:95], v83 offset:3072
	s_cmp_eq_u32 s48, 28
	s_cselect_b32 s23, s13, s21
	s_cselect_b32 s22, s44, s20
	s_cselect_b32 s21, s11, s47
	s_cselect_b32 s20, s45, s46
	v_lshl_add_u64 v[128:129], s[18:19], 0, v[74:75]
	s_add_i32 m0, s26, 0xc000
	ds_read_b128 v[96:99], v82
	ds_read_b128 v[100:103], v82 offset:1024
	ds_read_b128 v[104:107], v82 offset:2048
	ds_read_b128 v[108:111], v82 offset:3072
	ds_read_b128 v[112:115], v82 offset:4096
	ds_read_b128 v[116:119], v82 offset:5120
	ds_read_b128 v[120:123], v82 offset:6144
	ds_read_b128 v[124:127], v82 offset:7168
	global_load_lds_dwordx4 v[128:129], off
	v_lshl_add_u64 v[128:129], s[18:19], 0, v[76:77]
	s_add_i32 m0, s26, 0xe000
	s_nop 0
	global_load_lds_dwordx4 v[128:129], off
	s_nop 0
	s_nop 0
	s_waitcnt vmcnt(8)
	s_waitcnt lgkmcnt(0)
	v_mfma_f32_16x16x32_bf16 v[62:65], v[78:81], v[96:99], v[62:65]
	v_mfma_f32_16x16x32_bf16 v[58:61], v[88:91], v[96:99], v[58:61]
	s_barrier
	s_setprio 1
	s_waitcnt lgkmcnt(0)
	v_mfma_f32_16x16x32_bf16 v[54:57], v[78:81], v[104:107], v[54:57]
	v_mfma_f32_16x16x32_bf16 v[50:53], v[88:91], v[104:107], v[50:53]
	v_mfma_f32_16x16x32_bf16 v[46:49], v[78:81], v[112:115], v[46:49]
	v_mfma_f32_16x16x32_bf16 v[42:45], v[88:91], v[112:115], v[42:45]
	v_mfma_f32_16x16x32_bf16 v[38:41], v[78:81], v[120:123], v[38:41]
	v_mfma_f32_16x16x32_bf16 v[34:37], v[88:91], v[120:123], v[34:37]
	v_mfma_f32_16x16x32_bf16 v[62:65], v[84:87], v[100:103], v[62:65]
	v_mfma_f32_16x16x32_bf16 v[58:61], v[92:95], v[100:103], v[58:61]
	v_mfma_f32_16x16x32_bf16 v[54:57], v[84:87], v[108:111], v[54:57]
	v_mfma_f32_16x16x32_bf16 v[50:53], v[92:95], v[108:111], v[50:53]
	v_mfma_f32_16x16x32_bf16 v[46:49], v[84:87], v[116:119], v[46:49]
	v_mfma_f32_16x16x32_bf16 v[42:45], v[92:95], v[116:119], v[42:45]
	v_mfma_f32_16x16x32_bf16 v[38:41], v[84:87], v[124:127], v[38:41]
	v_mfma_f32_16x16x32_bf16 v[34:37], v[92:95], v[124:127], v[34:37]
	s_setprio 0
	s_setprio 1
	s_setprio 0
	s_barrier
	s_add_i32 s49, s49, s25
	v_lshl_add_u64 v[128:129], s[20:21], 0, v[70:71]
	s_mov_b32 m0, s49
	ds_read_b128 v[96:99], v82 offset:16384
	ds_read_b128 v[100:103], v82 offset:17408
	ds_read_b128 v[104:107], v82 offset:18432
	ds_read_b128 v[108:111], v82 offset:19456
	ds_read_b128 v[112:115], v82 offset:20480
	ds_read_b128 v[116:119], v82 offset:21504
	ds_read_b128 v[120:123], v82 offset:22528
	ds_read_b128 v[124:127], v82 offset:23552
	global_load_lds_dwordx4 v[128:129], off
	s_add_i32 m0, s49, 0x2000
	s_add_u32 s50, s20, 0x80000
	v_lshl_add_u64 v[130:131], s[20:21], 0, v[66:67]
	s_addc_u32 s51, s21, 0
	global_load_lds_dwordx4 v[130:131], off
	v_lshl_add_u64 v[132:133], s[50:51], 0, v[70:71]
	s_mov_b32 m0, s27
	v_lshl_add_u64 v[134:135], s[22:23], 0, v[68:69]
	global_load_lds_dwordx4 v[132:133], off
	v_lshl_add_u64 v[132:133], s[50:51], 0, v[66:67]
	s_mov_b32 m0, s28
	s_nop 0
	global_load_lds_dwordx4 v[132:133], off
	v_lshl_add_u64 v[132:133], s[22:23], 0, v[72:73]
	s_mov_b32 m0, s26
	s_nop 0
	global_load_lds_dwordx4 v[132:133], off
	s_mov_b32 m0, s29
	s_nop 0
	global_load_lds_dwordx4 v[134:135], off
	s_nop 0
	s_waitcnt vmcnt(8)
	s_waitcnt lgkmcnt(0)
	v_mfma_f32_16x16x32_bf16 v[30:33], v[78:81], v[96:99], v[30:33]
	v_mfma_f32_16x16x32_bf16 v[26:29], v[88:91], v[96:99], v[26:29]
	s_barrier
	s_setprio 1
	s_waitcnt lgkmcnt(0)
	v_mfma_f32_16x16x32_bf16 v[22:25], v[78:81], v[104:107], v[22:25]
	v_mfma_f32_16x16x32_bf16 v[18:21], v[88:91], v[104:107], v[18:21]
	v_mfma_f32_16x16x32_bf16 v[14:17], v[78:81], v[112:115], v[14:17]
	v_mfma_f32_16x16x32_bf16 v[10:13], v[88:91], v[112:115], v[10:13]
	v_mfma_f32_16x16x32_bf16 v[6:9], v[78:81], v[120:123], v[6:9]
	v_mfma_f32_16x16x32_bf16 v[2:5], v[88:91], v[120:123], v[2:5]
	v_mfma_f32_16x16x32_bf16 v[30:33], v[84:87], v[100:103], v[30:33]
	v_mfma_f32_16x16x32_bf16 v[26:29], v[92:95], v[100:103], v[26:29]
	v_mfma_f32_16x16x32_bf16 v[22:25], v[84:87], v[108:111], v[22:25]
	v_mfma_f32_16x16x32_bf16 v[18:21], v[92:95], v[108:111], v[18:21]
	v_mfma_f32_16x16x32_bf16 v[14:17], v[84:87], v[116:119], v[14:17]
	v_mfma_f32_16x16x32_bf16 v[10:13], v[92:95], v[116:119], v[10:13]
	v_mfma_f32_16x16x32_bf16 v[6:9], v[84:87], v[124:127], v[6:9]
	v_mfma_f32_16x16x32_bf16 v[2:5], v[92:95], v[124:127], v[2:5]
	s_setprio 0
	s_setprio 1
	s_setprio 0
	s_barrier
; #define PG8_STAGE(bufoff, gbase, voff) do { _Pragma("unroll") for (int _i = 0; _i < 2; ++_i) \
;         __builtin_amdgcn_global_load_lds((const unsigned*)((const char*)(gbase) + (voff)[_i]), (LAS unsigned*)(lds + (bufoff) + ldsw + _i * 8192), 16, 0, 0); } while (0)
; #define PG8_LDA(dst, b, h) do { _Pragma("unroll") for (int m = 0; m < 4; ++m) _Pragma("unroll") for (int k = 0; k < 2; ++k) dst[m][k] = *(const LAS bf16x8*)(lds + PG8_SA(b, h) + aoff + m * 2048 + k * 1024); } while (0)
; #define PG8_LDB(dst, b, h) do { _Pragma("unroll") for (int n = 0; n < 2; ++n) _Pragma("unroll") for (int k = 0; k < 2; ++k) dst[n][k] = *(const LAS bf16x8*)(lds + PG8_SB(b, h) + boff + n * 2048 + k * 1024); } while (0)
; #define PG8_MMA(ai, bj, At, Bt) do { __builtin_amdgcn_s_setprio(1); _Pragma("unroll") for (int m = 0; m < 4; ++m) _Pragma("unroll") for (int n = 0; n < 2; ++n) _Pragma("unroll") for (int k = 0; k < 2; ++k) \
;         acc[ai][bj][m][n] = __builtin_amdgcn_mfma_f32_16x16x32_bf16(Bt[n][k], At[m][k], acc[ai][bj][m][n], 0, 0, 0); __builtin_amdgcn_s_setprio(0); } while (0)
; #define PG8_WAIT_V(n) asm volatile("s_waitcnt vmcnt(" #n ")" ::: "memory")
; #define PG8_WAIT_L(n) asm volatile("s_waitcnt lgkmcnt(" #n ")" ::: "memory")
; #define PG8_BAR __builtin_amdgcn_s_barrier()
; #define PG8_SCHED __builtin_amdgcn_sched_barrier(0)
; template <class Epi, class Sched>
; __device__ __forceinline__ void gemm_phase(LAS unsigned char* lds, const Gemm g, const Sched& S, const Epi& E) {
;     ...
;             PG8_LDB(B0, 1, 0); PG8_LDB(B1, 1, 1); PG8_SCHED; PG8_LDA(At, 1, 0); PG8_STAGE(PG8_SA(0, 1), a2 + hstepA, voffA);
;             PG8_WAIT_V(8); PG8_WAIT_L(0); PG8_BAR; PG8_MMA(0, 0, At, B0); PG8_MMA(0, 1, At, B1); PG8_BAR; PG8_SCHED;
;             PG8_LDA(At, 1, 1); PG8_STAGE(PG8_SB(1, 0), b3, voffB); PG8_STAGE(PG8_SB(1, 1), b3 + hstepB, voffB); PG8_STAGE(PG8_SA(1, 0), a3, voffA);
;             PG8_WAIT_V(8); PG8_WAIT_L(0); PG8_BAR; PG8_MMA(1, 0, At, B0); PG8_MMA(1, 1, At, B1); PG8_BAR; PG8_SCHED;
;         }
;         if (wr == 0) PG8_BAR;
	s_add_i32 s49, 0, 0x18000
	v_add_u32_e32 v83, s49, v1
	ds_read_b128 v[78:81], v83
	ds_read_b128 v[84:87], v83 offset:1024
	ds_read_b128 v[88:91], v83 offset:2048
	ds_read_b128 v[92:95], v83 offset:3072
	s_add_u32 s22, s22, 0x80000
	s_addc_u32 s23, s23, 0
	s_mov_b32 m0, s30
	v_lshl_add_u64 v[136:137], s[22:23], 0, v[72:73]
	ds_read_b128 v[96:99], v82 offset:32768
	ds_read_b128 v[100:103], v82 offset:33792
	ds_read_b128 v[104:107], v82 offset:34816
	ds_read_b128 v[108:111], v82 offset:35840
	ds_read_b128 v[112:115], v82 offset:36864
	ds_read_b128 v[116:119], v82 offset:37888
	ds_read_b128 v[120:123], v82 offset:38912
	ds_read_b128 v[124:127], v82 offset:39936
	global_load_lds_dwordx4 v[136:137], off
	v_lshl_add_u64 v[136:137], s[22:23], 0, v[68:69]
	s_mov_b32 m0, s31
	s_nop 0
	global_load_lds_dwordx4 v[136:137], off
	s_nop 0
	s_nop 0
	s_waitcnt vmcnt(8)
	s_waitcnt lgkmcnt(0)
	v_mfma_f32_16x16x32_bf16 v[62:65], v[78:81], v[96:99], v[62:65]
	v_mfma_f32_16x16x32_bf16 v[58:61], v[88:91], v[96:99], v[58:61]
	s_barrier
	s_setprio 1
	s_waitcnt lgkmcnt(0)
	v_mfma_f32_16x16x32_bf16 v[54:57], v[78:81], v[104:107], v[54:57]
	v_mfma_f32_16x16x32_bf16 v[50:53], v[88:91], v[104:107], v[50:53]
	v_mfma_f32_16x16x32_bf16 v[46:49], v[78:81], v[112:115], v[46:49]
	v_mfma_f32_16x16x32_bf16 v[42:45], v[88:91], v[112:115], v[42:45]
	v_mfma_f32_16x16x32_bf16 v[38:41], v[78:81], v[120:123], v[38:41]
	v_mfma_f32_16x16x32_bf16 v[34:37], v[88:91], v[120:123], v[34:37]
	v_mfma_f32_16x16x32_bf16 v[62:65], v[84:87], v[100:103], v[62:65]
	v_mfma_f32_16x16x32_bf16 v[58:61], v[92:95], v[100:103], v[58:61]
	v_mfma_f32_16x16x32_bf16 v[54:57], v[84:87], v[108:111], v[54:57]
	v_mfma_f32_16x16x32_bf16 v[50:53], v[92:95], v[108:111], v[50:53]
	v_mfma_f32_16x16x32_bf16 v[46:49], v[84:87], v[116:119], v[46:49]
	v_mfma_f32_16x16x32_bf16 v[42:45], v[92:95], v[116:119], v[42:45]
	v_mfma_f32_16x16x32_bf16 v[38:41], v[84:87], v[124:127], v[38:41]
	v_mfma_f32_16x16x32_bf16 v[34:37], v[92:95], v[124:127], v[34:37]
	s_setprio 0
	s_setprio 1
	s_setprio 0
	s_barrier
	s_add_i32 s22, s49, s25
	v_lshl_add_u64 v[128:129], v[128:129], 0, s[56:57]
	s_mov_b32 m0, s22
	ds_read_b128 v[96:99], v82 offset:49152
	ds_read_b128 v[100:103], v82 offset:50176
	ds_read_b128 v[104:107], v82 offset:51200
	ds_read_b128 v[108:111], v82 offset:52224
	ds_read_b128 v[112:115], v82 offset:53248
	ds_read_b128 v[116:119], v82 offset:54272
	ds_read_b128 v[120:123], v82 offset:55296
	ds_read_b128 v[124:127], v82 offset:56320
	global_load_lds_dwordx4 v[128:129], off
	s_add_i32 m0, s22, 0x2000
	s_add_u32 s20, s20, 0x80080
	v_lshl_add_u64 v[128:129], v[130:131], 0, s[56:57]
	s_addc_u32 s21, s21, 0
	global_load_lds_dwordx4 v[128:129], off
	v_lshl_add_u64 v[128:129], s[20:21], 0, v[70:71]
	s_mov_b32 m0, s38
	s_nop 0
	global_load_lds_dwordx4 v[128:129], off
	v_lshl_add_u64 v[128:129], s[20:21], 0, v[66:67]
	s_mov_b32 m0, s39
	s_nop 0
	global_load_lds_dwordx4 v[128:129], off
	v_lshl_add_u64 v[128:129], v[132:133], 0, s[56:57]
	s_mov_b32 m0, s36
	s_nop 0
	global_load_lds_dwordx4 v[128:129], off
	v_lshl_add_u64 v[128:129], v[134:135], 0, s[56:57]
	s_mov_b32 m0, s37
	s_nop 0
	global_load_lds_dwordx4 v[128:129], off
	s_waitcnt vmcnt(8)
	s_waitcnt lgkmcnt(0)
	v_mfma_f32_16x16x32_bf16 v[30:33], v[78:81], v[96:99], v[30:33]
	v_mfma_f32_16x16x32_bf16 v[26:29], v[88:91], v[96:99], v[26:29]
	s_barrier
	s_setprio 1
	s_waitcnt lgkmcnt(0)
	v_mfma_f32_16x16x32_bf16 v[22:25], v[78:81], v[104:107], v[22:25]
	v_mfma_f32_16x16x32_bf16 v[18:21], v[88:91], v[104:107], v[18:21]
	v_mfma_f32_16x16x32_bf16 v[14:17], v[78:81], v[112:115], v[14:17]
	v_mfma_f32_16x16x32_bf16 v[10:13], v[88:91], v[112:115], v[10:13]
	v_mfma_f32_16x16x32_bf16 v[6:9], v[78:81], v[120:123], v[6:9]
	v_mfma_f32_16x16x32_bf16 v[2:5], v[88:91], v[120:123], v[2:5]
	v_mfma_f32_16x16x32_bf16 v[30:33], v[84:87], v[100:103], v[30:33]
	v_mfma_f32_16x16x32_bf16 v[26:29], v[92:95], v[100:103], v[26:29]
	v_mfma_f32_16x16x32_bf16 v[22:25], v[84:87], v[108:111], v[22:25]
	v_mfma_f32_16x16x32_bf16 v[18:21], v[92:95], v[108:111], v[18:21]
	v_mfma_f32_16x16x32_bf16 v[14:17], v[84:87], v[116:119], v[14:17]
	v_mfma_f32_16x16x32_bf16 v[10:13], v[92:95], v[116:119], v[10:13]
	v_mfma_f32_16x16x32_bf16 v[6:9], v[84:87], v[124:127], v[6:9]
	v_mfma_f32_16x16x32_bf16 v[2:5], v[92:95], v[124:127], v[2:5]
	s_setprio 0
	s_setprio 1
	s_setprio 0
	s_barrier
	s_add_i32 s48, s48, 2
	s_add_u32 s18, s18, 0x100
	s_addc_u32 s19, s19, 0
	s_add_u32 s46, s46, 0x100
	s_addc_u32 s47, s47, 0
	s_cmp_gt_u32 s48, 29
	s_cbranch_scc0 .LBB0_3562
	s_and_b64 vcc, exec, s[6:7]
	s_cbranch_vccz .LBB0_3565
	s_barrier

; #define PG8_STAGE(bufoff, gbase, voff) do { _Pragma("unroll") for (int _i = 0; _i < 2; ++_i) \
;         __builtin_amdgcn_global_load_lds((const unsigned*)((const char*)(gbase) + (voff)[_i]), (LAS unsigned*)(lds + (bufoff) + ldsw + _i * 8192), 16, 0, 0); } while (0)
; #define PG8_LDA(dst, b, h) do { _Pragma("unroll") for (int m = 0; m < 4; ++m) _Pragma("unroll") for (int k = 0; k < 2; ++k) dst[m][k] = *(const LAS bf16x8*)(lds + PG8_SA(b, h) + aoff + m * 2048 + k * 1024); } while (0)
; #define PG8_LDB(dst, b, h) do { _Pragma("unroll") for (int n = 0; n < 2; ++n) _Pragma("unroll") for (int k = 0; k < 2; ++k) dst[n][k] = *(const LAS bf16x8*)(lds + PG8_SB(b, h) + boff + n * 2048 + k * 1024); } while (0)
; #define PG8_MMA(ai, bj, At, Bt) do { __builtin_amdgcn_s_setprio(1); _Pragma("unroll") for (int m = 0; m < 4; ++m) _Pragma("unroll") for (int n = 0; n < 2; ++n) _Pragma("unroll") for (int k = 0; k < 2; ++k) \
;         acc[ai][bj][m][n] = __builtin_amdgcn_mfma_f32_16x16x32_bf16(Bt[n][k], At[m][k], acc[ai][bj][m][n], 0, 0, 0); __builtin_amdgcn_s_setprio(0); } while (0)
; #define PG8_WAIT_V(n) asm volatile("s_waitcnt vmcnt(" #n ")" ::: "memory")
; template <class Epi, class Sched>
; __device__ __forceinline__ void gemm_phase(LAS unsigned char* lds, const Gemm g, const Sched& S, const Epi& E) {
;     ...
;         const bool has_next = S.next(ui + 1, nxt);
;         const char* nA = has_next ? (const char*)g.A + (size_t)nxt.pm * tstepA : cA; const char* nB = has_next ? (const char*)g.Bt + (size_t)nxt.pn * tstepB : cB;
;         for (int t = 0; t < nt; t += 2) {
;             const bool last = (t == nt - 2);
;             const char* a1 = cA + (size_t)(t + 1) * kstep;
;             const char* a2 = last ? nA : cA + (size_t)(t + 2) * kstep; const char* b2 = last ? nB : cB + (size_t)(t + 2) * kstep;
;             const char* a3 = a2 + kstep; const char* b3 = b2 + kstep;
;             PG8_LDB(B0, 0, 0); PG8_LDB(B1, 0, 1); PG8_SCHED; PG8_LDA(At, 0, 0); PG8_STAGE(PG8_SA(1, 1), a1 + hstepA, voffA);
;             PG8_WAIT_V(8); PG8_WAIT_L(0); PG8_BAR; PG8_MMA(0, 0, At, B0); PG8_MMA(0, 1, At, B1); PG8_BAR; PG8_SCHED;
;             PG8_LDA(At, 0, 1); PG8_STAGE(PG8_SB(0, 0), b2, voffB); PG8_STAGE(PG8_SB(0, 1), b2 + hstepB, voffB); PG8_STAGE(PG8_SA(0, 0), a2, voffA);
;             PG8_WAIT_V(8); PG8_WAIT_L(0); PG8_BAR; PG8_MMA(1, 0, At, B0); PG8_MMA(1, 1, At, B1); PG8_BAR; PG8_SCHED;
.LBB0_3585:
	s_add_u32 s20, s18, 0xfff80080
	s_addc_u32 s21, s19, -1
	s_add_i32 s49, 0, 0x10000
	s_cmp_eq_u32 s48, 60
	s_cselect_b32 s23, s13, s21
	s_cselect_b32 s22, s44, s20
	s_cselect_b32 s21, s11, s47
	s_cselect_b32 s20, s45, s46
	s_add_i32 s52, 0, 0x14000
	v_add_u32_e32 v46, s49, v1
	v_add_u32_e32 v178, s52, v1
	ds_read_b128 v[26:29], v46
	ds_read_b128 v[30:33], v46 offset:1024
	ds_read_b128 v[42:45], v46 offset:2048
	ds_read_b128 v[46:49], v46 offset:3072
	ds_read_b128 v[174:177], v178
	ds_read_b128 v[182:185], v178 offset:1024
	ds_read_b128 v[186:189], v178 offset:2048
	ds_read_b128 v[190:193], v178 offset:3072
	v_lshl_add_u64 v[178:179], s[18:19], 0, v[170:171]
	s_add_i32 m0, s31, 0xc000
	ds_read_b128 v[208:211], v180
	ds_read_b128 v[212:215], v180 offset:1024
	ds_read_b128 v[216:219], v180 offset:2048
	ds_read_b128 v[220:223], v180 offset:3072
	ds_read_b128 v[224:227], v180 offset:4096
	ds_read_b128 v[228:231], v180 offset:5120
	ds_read_b128 v[232:235], v180 offset:6144
	ds_read_b128 v[236:239], v180 offset:7168
	global_load_lds_dwordx4 v[178:179], off
	v_lshl_add_u64 v[178:179], s[18:19], 0, v[172:173]
	s_add_i32 m0, s31, 0xe000
	s_nop 0
	global_load_lds_dwordx4 v[178:179], off
	s_nop 0
	s_nop 0
	s_nop 0
	s_waitcnt vmcnt(8)
	s_waitcnt lgkmcnt(0)
	v_mfma_f32_16x16x32_bf16 v[142:145], v[26:29], v[208:211], v[142:145]
	v_mfma_f32_16x16x32_bf16 v[138:141], v[42:45], v[208:211], v[138:141]
	s_barrier
	s_setprio 1
	s_waitcnt lgkmcnt(0)
	v_mfma_f32_16x16x32_bf16 v[126:129], v[26:29], v[216:219], v[126:129]
	v_mfma_f32_16x16x32_bf16 v[122:125], v[42:45], v[216:219], v[122:125]
	v_mfma_f32_16x16x32_bf16 v[110:113], v[26:29], v[224:227], v[110:113]
	v_mfma_f32_16x16x32_bf16 v[106:109], v[42:45], v[224:227], v[106:109]
	v_mfma_f32_16x16x32_bf16 v[94:97], v[26:29], v[232:235], v[94:97]
	v_mfma_f32_16x16x32_bf16 v[90:93], v[42:45], v[232:235], v[90:93]
	v_mfma_f32_16x16x32_bf16 v[142:145], v[30:33], v[212:215], v[142:145]
	v_mfma_f32_16x16x32_bf16 v[138:141], v[46:49], v[212:215], v[138:141]
	v_mfma_f32_16x16x32_bf16 v[126:129], v[30:33], v[220:223], v[126:129]
	v_mfma_f32_16x16x32_bf16 v[122:125], v[46:49], v[220:223], v[122:125]
	v_mfma_f32_16x16x32_bf16 v[110:113], v[30:33], v[228:231], v[110:113]
	v_mfma_f32_16x16x32_bf16 v[106:109], v[46:49], v[228:231], v[106:109]
	v_mfma_f32_16x16x32_bf16 v[94:97], v[30:33], v[236:239], v[94:97]
	v_mfma_f32_16x16x32_bf16 v[90:93], v[46:49], v[236:239], v[90:93]
	s_setprio 0
	s_setprio 1
	v_mfma_f32_16x16x32_bf16 v[134:137], v[174:177], v[208:211], v[134:137]
	v_mfma_f32_16x16x32_bf16 v[130:133], v[186:189], v[208:211], v[130:133]
	v_mfma_f32_16x16x32_bf16 v[118:121], v[174:177], v[216:219], v[118:121]
	v_mfma_f32_16x16x32_bf16 v[114:117], v[186:189], v[216:219], v[114:117]
	v_mfma_f32_16x16x32_bf16 v[102:105], v[174:177], v[224:227], v[102:105]
	v_mfma_f32_16x16x32_bf16 v[98:101], v[186:189], v[224:227], v[98:101]
	v_mfma_f32_16x16x32_bf16 v[86:89], v[174:177], v[232:235], v[86:89]
	v_mfma_f32_16x16x32_bf16 v[82:85], v[186:189], v[232:235], v[82:85]
	v_mfma_f32_16x16x32_bf16 v[134:137], v[182:185], v[212:215], v[134:137]
	v_mfma_f32_16x16x32_bf16 v[130:133], v[190:193], v[212:215], v[130:133]
	v_mfma_f32_16x16x32_bf16 v[118:121], v[182:185], v[220:223], v[118:121]
	v_mfma_f32_16x16x32_bf16 v[114:117], v[190:193], v[220:223], v[114:117]
	v_mfma_f32_16x16x32_bf16 v[102:105], v[182:185], v[228:231], v[102:105]
	v_mfma_f32_16x16x32_bf16 v[98:101], v[190:193], v[228:231], v[98:101]
	v_mfma_f32_16x16x32_bf16 v[86:89], v[182:185], v[236:239], v[86:89]
	v_mfma_f32_16x16x32_bf16 v[82:85], v[190:193], v[236:239], v[82:85]
	s_setprio 0
	s_barrier
	s_add_i32 s49, s49, s30
	v_lshl_add_u64 v[178:179], s[20:21], 0, v[164:165]
	s_mov_b32 m0, s49
	ds_read_b128 v[208:211], v180 offset:16384
	ds_read_b128 v[212:215], v180 offset:17408
	ds_read_b128 v[216:219], v180 offset:18432
	ds_read_b128 v[220:223], v180 offset:19456
	ds_read_b128 v[224:227], v180 offset:20480
	ds_read_b128 v[228:231], v180 offset:21504
	ds_read_b128 v[232:235], v180 offset:22528
	ds_read_b128 v[236:239], v180 offset:23552
	global_load_lds_dwordx4 v[178:179], off
	s_add_i32 m0, s49, 0x2000
	s_add_u32 s50, s20, 0x100000
	v_lshl_add_u64 v[240:241], s[20:21], 0, v[168:169]
	s_addc_u32 s51, s21, 0
	s_add_i32 s49, s52, s30
	global_load_lds_dwordx4 v[240:241], off
	v_lshl_add_u64 v[242:243], s[50:51], 0, v[164:165]
	s_mov_b32 m0, s49
	v_lshl_add_u64 v[244:245], s[22:23], 0, v[166:167]
	global_load_lds_dwordx4 v[242:243], off
	v_lshl_add_u64 v[242:243], s[50:51], 0, v[168:169]
	s_add_i32 m0, s49, 0x2000
	s_nop 0
	global_load_lds_dwordx4 v[242:243], off
	v_lshl_add_u64 v[242:243], s[22:23], 0, v[162:163]
	s_mov_b32 m0, s31
	s_nop 0
	global_load_lds_dwordx4 v[242:243], off
	s_mov_b32 m0, s34
	s_nop 0
	global_load_lds_dwordx4 v[244:245], off
	s_nop 0
	s_nop 0
	s_nop 0
	s_waitcnt vmcnt(8)
	s_waitcnt lgkmcnt(0)
	v_mfma_f32_16x16x32_bf16 v[78:81], v[26:29], v[208:211], v[78:81]
	v_mfma_f32_16x16x32_bf16 v[74:77], v[42:45], v[208:211], v[74:77]
	s_barrier
; #define PG8_STAGE(bufoff, gbase, voff) do { _Pragma("unroll") for (int _i = 0; _i < 2; ++_i) \
;         __builtin_amdgcn_global_load_lds((const unsigned*)((const char*)(gbase) + (voff)[_i]), (LAS unsigned*)(lds + (bufoff) + ldsw + _i * 8192), 16, 0, 0); } while (0)
; #define PG8_LDA(dst, b, h) do { _Pragma("unroll") for (int m = 0; m < 4; ++m) _Pragma("unroll") for (int k = 0; k < 2; ++k) dst[m][k] = *(const LAS bf16x8*)(lds + PG8_SA(b, h) + aoff + m * 2048 + k * 1024); } while (0)
; #define PG8_LDB(dst, b, h) do { _Pragma("unroll") for (int n = 0; n < 2; ++n) _Pragma("unroll") for (int k = 0; k < 2; ++k) dst[n][k] = *(const LAS bf16x8*)(lds + PG8_SB(b, h) + boff + n * 2048 + k * 1024); } while (0)
; #define PG8_MMA(ai, bj, At, Bt) do { __builtin_amdgcn_s_setprio(1); _Pragma("unroll") for (int m = 0; m < 4; ++m) _Pragma("unroll") for (int n = 0; n < 2; ++n) _Pragma("unroll") for (int k = 0; k < 2; ++k) \
;         acc[ai][bj][m][n] = __builtin_amdgcn_mfma_f32_16x16x32_bf16(Bt[n][k], At[m][k], acc[ai][bj][m][n], 0, 0, 0); __builtin_amdgcn_s_setprio(0); } while (0)
; #define PG8_WAIT_V(n) asm volatile("s_waitcnt vmcnt(" #n ")" ::: "memory")
; #define PG8_WAIT_L(n) asm volatile("s_waitcnt lgkmcnt(" #n ")" ::: "memory")
; #define PG8_BAR __builtin_amdgcn_s_barrier()
; #define PG8_SCHED __builtin_amdgcn_sched_barrier(0)
; template <class Epi, class Sched>
; __device__ __forceinline__ void gemm_phase(LAS unsigned char* lds, const Gemm g, const Sched& S, const Epi& E) {
;     ...
;             PG8_WAIT_V(8); PG8_WAIT_L(0); PG8_BAR; PG8_MMA(1, 0, At, B0); PG8_MMA(1, 1, At, B1); PG8_BAR; PG8_SCHED;
;             PG8_LDB(B0, 1, 0); PG8_LDB(B1, 1, 1); PG8_SCHED; PG8_LDA(At, 1, 0); PG8_STAGE(PG8_SA(0, 1), a2 + hstepA, voffA);
;             PG8_WAIT_V(8); PG8_WAIT_L(0); PG8_BAR; PG8_MMA(0, 0, At, B0); PG8_MMA(0, 1, At, B1); PG8_BAR; PG8_SCHED;
	s_setprio 1
	s_waitcnt lgkmcnt(0)
	v_mfma_f32_16x16x32_bf16 v[62:65], v[26:29], v[216:219], v[62:65]
	v_mfma_f32_16x16x32_bf16 v[58:61], v[42:45], v[216:219], v[58:61]
	v_mfma_f32_16x16x32_bf16 v[38:41], v[26:29], v[224:227], v[38:41]
	v_mfma_f32_16x16x32_bf16 v[34:37], v[42:45], v[224:227], v[34:37]
	v_mfma_f32_16x16x32_bf16 v[14:17], v[26:29], v[232:235], v[14:17]
	v_mfma_f32_16x16x32_bf16 v[10:13], v[42:45], v[232:235], v[10:13]
	v_mfma_f32_16x16x32_bf16 v[78:81], v[30:33], v[212:215], v[78:81]
	v_mfma_f32_16x16x32_bf16 v[74:77], v[46:49], v[212:215], v[74:77]
	v_mfma_f32_16x16x32_bf16 v[62:65], v[30:33], v[220:223], v[62:65]
	v_mfma_f32_16x16x32_bf16 v[58:61], v[46:49], v[220:223], v[58:61]
	v_mfma_f32_16x16x32_bf16 v[38:41], v[30:33], v[228:231], v[38:41]
	v_mfma_f32_16x16x32_bf16 v[34:37], v[46:49], v[228:231], v[34:37]
	v_mfma_f32_16x16x32_bf16 v[14:17], v[30:33], v[236:239], v[14:17]
	v_mfma_f32_16x16x32_bf16 v[10:13], v[46:49], v[236:239], v[10:13]
	s_setprio 0
	s_setprio 1
	v_mfma_f32_16x16x32_bf16 v[22:25], v[174:177], v[224:227], v[22:25]
	v_mfma_f32_16x16x32_bf16 v[18:21], v[186:189], v[224:227], v[18:21]
	v_mfma_f32_16x16x32_bf16 v[6:9], v[174:177], v[232:235], v[6:9]
	v_mfma_f32_16x16x32_bf16 v[2:5], v[186:189], v[232:235], v[2:5]
	v_mfma_f32_16x16x32_bf16 v[26:29], v[174:177], v[208:211], v[70:73]
	v_mfma_f32_16x16x32_bf16 v[30:33], v[186:189], v[208:211], v[66:69]
	v_mfma_f32_16x16x32_bf16 v[42:45], v[174:177], v[216:219], v[54:57]
	v_mfma_f32_16x16x32_bf16 v[46:49], v[186:189], v[216:219], v[50:53]
	v_mfma_f32_16x16x32_bf16 v[22:25], v[182:185], v[228:231], v[22:25]
	v_mfma_f32_16x16x32_bf16 v[18:21], v[190:193], v[228:231], v[18:21]
	v_mfma_f32_16x16x32_bf16 v[6:9], v[182:185], v[236:239], v[6:9]
	v_mfma_f32_16x16x32_bf16 v[2:5], v[190:193], v[236:239], v[2:5]
	v_mfma_f32_16x16x32_bf16 v[26:29], v[182:185], v[212:215], v[26:29]
	v_mfma_f32_16x16x32_bf16 v[30:33], v[190:193], v[212:215], v[30:33]
	v_mfma_f32_16x16x32_bf16 v[42:45], v[182:185], v[220:223], v[42:45]
	v_mfma_f32_16x16x32_bf16 v[46:49], v[190:193], v[220:223], v[46:49]
	s_setprio 0
	s_barrier
	s_add_i32 s49, 0, 0x18000
	s_add_i32 s50, 0, 0x1c000
	v_add_u32_e32 v70, s49, v1
	v_add_u32_e32 v181, s50, v1
	ds_read_b128 v[50:53], v70
	ds_read_b128 v[54:57], v70 offset:1024
	ds_read_b128 v[66:69], v70 offset:2048
	ds_read_b128 v[70:73], v70 offset:3072
	ds_read_b128 v[174:177], v181
	ds_read_b128 v[182:185], v181 offset:1024
	ds_read_b128 v[186:189], v181 offset:2048
	ds_read_b128 v[190:193], v181 offset:3072
	s_add_u32 s22, s22, 0x80000
	s_addc_u32 s23, s23, 0
	s_mov_b32 m0, s35
	v_lshl_add_u64 v[246:247], s[22:23], 0, v[162:163]
	ds_read_b128 v[208:211], v180 offset:32768
	ds_read_b128 v[212:215], v180 offset:33792
	ds_read_b128 v[216:219], v180 offset:34816
	ds_read_b128 v[220:223], v180 offset:35840
	ds_read_b128 v[224:227], v180 offset:36864
	ds_read_b128 v[228:231], v180 offset:37888
	ds_read_b128 v[232:235], v180 offset:38912
	ds_read_b128 v[236:239], v180 offset:39936
	global_load_lds_dwordx4 v[246:247], off
	v_lshl_add_u64 v[246:247], s[22:23], 0, v[166:167]
	s_mov_b32 m0, s36
	s_nop 0
	global_load_lds_dwordx4 v[246:247], off
	s_nop 0
	s_nop 0
	s_nop 0
	s_waitcnt vmcnt(8)
	s_waitcnt lgkmcnt(0)
	v_mfma_f32_16x16x32_bf16 v[142:145], v[50:53], v[208:211], v[142:145]
	v_mfma_f32_16x16x32_bf16 v[138:141], v[66:69], v[208:211], v[138:141]
	s_barrier
	s_setprio 1
	s_waitcnt lgkmcnt(0)
	v_mfma_f32_16x16x32_bf16 v[126:129], v[50:53], v[216:219], v[126:129]
	v_mfma_f32_16x16x32_bf16 v[122:125], v[66:69], v[216:219], v[122:125]
	v_mfma_f32_16x16x32_bf16 v[110:113], v[50:53], v[224:227], v[110:113]
	v_mfma_f32_16x16x32_bf16 v[106:109], v[66:69], v[224:227], v[106:109]
	v_mfma_f32_16x16x32_bf16 v[94:97], v[50:53], v[232:235], v[94:97]
	v_mfma_f32_16x16x32_bf16 v[90:93], v[66:69], v[232:235], v[90:93]
	v_mfma_f32_16x16x32_bf16 v[142:145], v[54:57], v[212:215], v[142:145]
	v_mfma_f32_16x16x32_bf16 v[138:141], v[70:73], v[212:215], v[138:141]
	v_mfma_f32_16x16x32_bf16 v[126:129], v[54:57], v[220:223], v[126:129]
	v_mfma_f32_16x16x32_bf16 v[122:125], v[70:73], v[220:223], v[122:125]
	v_mfma_f32_16x16x32_bf16 v[110:113], v[54:57], v[228:231], v[110:113]
	v_mfma_f32_16x16x32_bf16 v[106:109], v[70:73], v[228:231], v[106:109]
	v_mfma_f32_16x16x32_bf16 v[94:97], v[54:57], v[236:239], v[94:97]
	v_mfma_f32_16x16x32_bf16 v[90:93], v[70:73], v[236:239], v[90:93]
	s_setprio 0
	s_setprio 1
	v_mfma_f32_16x16x32_bf16 v[134:137], v[174:177], v[208:211], v[134:137]
	v_mfma_f32_16x16x32_bf16 v[130:133], v[186:189], v[208:211], v[130:133]
	v_mfma_f32_16x16x32_bf16 v[118:121], v[174:177], v[216:219], v[118:121]
	v_mfma_f32_16x16x32_bf16 v[114:117], v[186:189], v[216:219], v[114:117]
	v_mfma_f32_16x16x32_bf16 v[102:105], v[174:177], v[224:227], v[102:105]
	v_mfma_f32_16x16x32_bf16 v[98:101], v[186:189], v[224:227], v[98:101]
	v_mfma_f32_16x16x32_bf16 v[86:89], v[174:177], v[232:235], v[86:89]
	v_mfma_f32_16x16x32_bf16 v[82:85], v[186:189], v[232:235], v[82:85]
	v_mfma_f32_16x16x32_bf16 v[134:137], v[182:185], v[212:215], v[134:137]
	v_mfma_f32_16x16x32_bf16 v[130:133], v[190:193], v[212:215], v[130:133]
	v_mfma_f32_16x16x32_bf16 v[118:121], v[182:185], v[220:223], v[118:121]
	v_mfma_f32_16x16x32_bf16 v[114:117], v[190:193], v[220:223], v[114:117]
	v_mfma_f32_16x16x32_bf16 v[102:105], v[182:185], v[228:231], v[102:105]
	v_mfma_f32_16x16x32_bf16 v[98:101], v[190:193], v[228:231], v[98:101]
	v_mfma_f32_16x16x32_bf16 v[86:89], v[182:185], v[236:239], v[86:89]
	v_mfma_f32_16x16x32_bf16 v[82:85], v[190:193], v[236:239], v[82:85]
	s_setprio 0
	s_barrier
; #define PG8_STAGE(bufoff, gbase, voff) do { _Pragma("unroll") for (int _i = 0; _i < 2; ++_i) \
;         __builtin_amdgcn_global_load_lds((const unsigned*)((const char*)(gbase) + (voff)[_i]), (LAS unsigned*)(lds + (bufoff) + ldsw + _i * 8192), 16, 0, 0); } while (0)
; #define PG8_LDA(dst, b, h) do { _Pragma("unroll") for (int m = 0; m < 4; ++m) _Pragma("unroll") for (int k = 0; k < 2; ++k) dst[m][k] = *(const LAS bf16x8*)(lds + PG8_SA(b, h) + aoff + m * 2048 + k * 1024); } while (0)
; #define PG8_MMA(ai, bj, At, Bt) do { __builtin_amdgcn_s_setprio(1); _Pragma("unroll") for (int m = 0; m < 4; ++m) _Pragma("unroll") for (int n = 0; n < 2; ++n) _Pragma("unroll") for (int k = 0; k < 2; ++k) \
;         acc[ai][bj][m][n] = __builtin_amdgcn_mfma_f32_16x16x32_bf16(Bt[n][k], At[m][k], acc[ai][bj][m][n], 0, 0, 0); __builtin_amdgcn_s_setprio(0); } while (0)
; #define PG8_WAIT_V(n) asm volatile("s_waitcnt vmcnt(" #n ")" ::: "memory")
; #define PG8_WAIT_L(n) asm volatile("s_waitcnt lgkmcnt(" #n ")" ::: "memory")
; #define PG8_BAR __builtin_amdgcn_s_barrier()
; #define PG8_SCHED __builtin_amdgcn_sched_barrier(0)
; template <class Epi, class Sched>
; __device__ __forceinline__ void gemm_phase(LAS unsigned char* lds, const Gemm g, const Sched& S, const Epi& E) {
;     ...
;             PG8_LDA(At, 1, 1); PG8_STAGE(PG8_SB(1, 0), b3, voffB); PG8_STAGE(PG8_SB(1, 1), b3 + hstepB, voffB); PG8_STAGE(PG8_SA(1, 0), a3, voffA);
;             PG8_WAIT_V(8); PG8_WAIT_L(0); PG8_BAR; PG8_MMA(1, 0, At, B0); PG8_MMA(1, 1, At, B1); PG8_BAR; PG8_SCHED;
;         }
;         if (wr == 0) PG8_BAR;
	s_add_i32 s22, s49, s30
	v_lshl_add_u64 v[178:179], v[178:179], 0, s[56:57]
	s_mov_b32 m0, s22
	ds_read_b128 v[208:211], v180 offset:49152
	ds_read_b128 v[212:215], v180 offset:50176
	ds_read_b128 v[216:219], v180 offset:51200
	ds_read_b128 v[220:223], v180 offset:52224
	ds_read_b128 v[224:227], v180 offset:53248
	ds_read_b128 v[228:231], v180 offset:54272
	ds_read_b128 v[232:235], v180 offset:55296
	ds_read_b128 v[236:239], v180 offset:56320
	global_load_lds_dwordx4 v[178:179], off
	s_add_i32 m0, s22, 0x2000
	s_add_u32 s20, s20, 0x100080
	v_lshl_add_u64 v[178:179], v[240:241], 0, s[56:57]
	s_addc_u32 s21, s21, 0
	s_add_i32 s22, s50, s30
	global_load_lds_dwordx4 v[178:179], off
	v_lshl_add_u64 v[178:179], s[20:21], 0, v[164:165]
	s_mov_b32 m0, s22
	s_nop 0
	global_load_lds_dwordx4 v[178:179], off
	v_lshl_add_u64 v[178:179], s[20:21], 0, v[168:169]
	s_add_i32 m0, s22, 0x2000
	s_nop 0
	global_load_lds_dwordx4 v[178:179], off
	v_lshl_add_u64 v[178:179], v[242:243], 0, s[56:57]
	s_mov_b32 m0, s39
	s_nop 0
	global_load_lds_dwordx4 v[178:179], off
	v_lshl_add_u64 v[178:179], v[244:245], 0, s[56:57]
	s_mov_b32 m0, s40
	s_nop 0
	global_load_lds_dwordx4 v[178:179], off
	s_nop 0
	s_nop 0
	s_waitcnt vmcnt(8)
	s_waitcnt lgkmcnt(0)
	v_mfma_f32_16x16x32_bf16 v[78:81], v[50:53], v[208:211], v[78:81]
	v_mfma_f32_16x16x32_bf16 v[74:77], v[66:69], v[208:211], v[74:77]
	s_barrier
	s_setprio 1
	s_waitcnt lgkmcnt(0)
	v_mfma_f32_16x16x32_bf16 v[62:65], v[50:53], v[216:219], v[62:65]
	v_mfma_f32_16x16x32_bf16 v[58:61], v[66:69], v[216:219], v[58:61]
	v_mfma_f32_16x16x32_bf16 v[38:41], v[50:53], v[224:227], v[38:41]
	v_mfma_f32_16x16x32_bf16 v[34:37], v[66:69], v[224:227], v[34:37]
	v_mfma_f32_16x16x32_bf16 v[14:17], v[50:53], v[232:235], v[14:17]
	v_mfma_f32_16x16x32_bf16 v[10:13], v[66:69], v[232:235], v[10:13]
	v_mfma_f32_16x16x32_bf16 v[78:81], v[54:57], v[212:215], v[78:81]
	v_mfma_f32_16x16x32_bf16 v[74:77], v[70:73], v[212:215], v[74:77]
	v_mfma_f32_16x16x32_bf16 v[62:65], v[54:57], v[220:223], v[62:65]
	v_mfma_f32_16x16x32_bf16 v[58:61], v[70:73], v[220:223], v[58:61]
	v_mfma_f32_16x16x32_bf16 v[38:41], v[54:57], v[228:231], v[38:41]
	v_mfma_f32_16x16x32_bf16 v[34:37], v[70:73], v[228:231], v[34:37]
	v_mfma_f32_16x16x32_bf16 v[14:17], v[54:57], v[236:239], v[14:17]
	v_mfma_f32_16x16x32_bf16 v[10:13], v[70:73], v[236:239], v[10:13]
	s_setprio 0
	s_setprio 1
	v_mfma_f32_16x16x32_bf16 v[26:29], v[174:177], v[208:211], v[26:29]
	v_mfma_f32_16x16x32_bf16 v[70:73], v[182:185], v[212:215], v[26:29]
	v_mfma_f32_16x16x32_bf16 v[26:29], v[186:189], v[208:211], v[30:33]
	v_mfma_f32_16x16x32_bf16 v[66:69], v[190:193], v[212:215], v[26:29]
	v_mfma_f32_16x16x32_bf16 v[26:29], v[174:177], v[216:219], v[42:45]
	v_mfma_f32_16x16x32_bf16 v[54:57], v[182:185], v[220:223], v[26:29]
	v_mfma_f32_16x16x32_bf16 v[26:29], v[186:189], v[216:219], v[46:49]
	v_mfma_f32_16x16x32_bf16 v[22:25], v[174:177], v[224:227], v[22:25]
	v_mfma_f32_16x16x32_bf16 v[18:21], v[186:189], v[224:227], v[18:21]
	v_mfma_f32_16x16x32_bf16 v[6:9], v[174:177], v[232:235], v[6:9]
	v_mfma_f32_16x16x32_bf16 v[2:5], v[186:189], v[232:235], v[2:5]
	v_mfma_f32_16x16x32_bf16 v[50:53], v[190:193], v[220:223], v[26:29]
	v_mfma_f32_16x16x32_bf16 v[22:25], v[182:185], v[228:231], v[22:25]
	v_mfma_f32_16x16x32_bf16 v[18:21], v[190:193], v[228:231], v[18:21]
	v_mfma_f32_16x16x32_bf16 v[6:9], v[182:185], v[236:239], v[6:9]
	v_mfma_f32_16x16x32_bf16 v[2:5], v[190:193], v[236:239], v[2:5]
	s_setprio 0
	s_barrier
	s_add_i32 s48, s48, 2
	s_add_u32 s18, s18, 0x100
	s_addc_u32 s19, s19, 0
	s_add_u32 s46, s46, 0x100
	s_addc_u32 s47, s47, 0
	s_cmp_gt_u32 s48, 61
	s_cbranch_scc0 .LBB0_3585
	s_and_b64 vcc, exec, s[6:7]
	s_cbranch_vccz .LBB0_3588
	s_barrier

; #define PG8_STAGE(bufoff, gbase, voff) do { _Pragma("unroll") for (int _i = 0; _i < 2; ++_i) \
;         __builtin_amdgcn_global_load_lds((const unsigned*)((const char*)(gbase) + (voff)[_i]), (LAS unsigned*)(lds + (bufoff) + ldsw + _i * 8192), 16, 0, 0); } while (0)
; #define PG8_LDA(dst, b, h) do { _Pragma("unroll") for (int m = 0; m < 4; ++m) _Pragma("unroll") for (int k = 0; k < 2; ++k) dst[m][k] = *(const LAS bf16x8*)(lds + PG8_SA(b, h) + aoff + m * 2048 + k * 1024); } while (0)
; #define PG8_LDB(dst, b, h) do { _Pragma("unroll") for (int n = 0; n < 2; ++n) _Pragma("unroll") for (int k = 0; k < 2; ++k) dst[n][k] = *(const LAS bf16x8*)(lds + PG8_SB(b, h) + boff + n * 2048 + k * 1024); } while (0)
; #define PG8_MMA(ai, bj, At, Bt) do { __builtin_amdgcn_s_setprio(1); _Pragma("unroll") for (int m = 0; m < 4; ++m) _Pragma("unroll") for (int n = 0; n < 2; ++n) _Pragma("unroll") for (int k = 0; k < 2; ++k) \
;         acc[ai][bj][m][n] = __builtin_amdgcn_mfma_f32_16x16x32_bf16(Bt[n][k], At[m][k], acc[ai][bj][m][n], 0, 0, 0); __builtin_amdgcn_s_setprio(0); } while (0)
; #define PG8_WAIT_V(n) asm volatile("s_waitcnt vmcnt(" #n ")" ::: "memory")
; #define PG8_WAIT_L(n) asm volatile("s_waitcnt lgkmcnt(" #n ")" ::: "memory")
; #define PG8_BAR __builtin_amdgcn_s_barrier()
; #define PG8_SCHED __builtin_amdgcn_sched_barrier(0)
; template <class Epi, class Sched>
; __device__ __forceinline__ void gemm_phase(LAS unsigned char* lds, const Gemm g, const Sched& S, const Epi& E) {
;     ...
;         for (int t = 0; t < nt; t += 2) {
;             const bool last = (t == nt - 2);
;             const char* a1 = cA + (size_t)(t + 1) * kstep;
;             const char* a2 = last ? nA : cA + (size_t)(t + 2) * kstep; const char* b2 = last ? nB : cB + (size_t)(t + 2) * kstep;
;             const char* a3 = a2 + kstep; const char* b3 = b2 + kstep;
;             PG8_LDB(B0, 0, 0); PG8_LDB(B1, 0, 1); PG8_SCHED; PG8_LDA(At, 0, 0); PG8_STAGE(PG8_SA(1, 1), a1 + hstepA, voffA);
;             PG8_WAIT_V(8); PG8_WAIT_L(0); PG8_BAR; PG8_MMA(0, 0, At, B0); PG8_MMA(0, 1, At, B1); PG8_BAR; PG8_SCHED;
;             PG8_LDA(At, 0, 1); PG8_STAGE(PG8_SB(0, 0), b2, voffB); PG8_STAGE(PG8_SB(0, 1), b2 + hstepB, voffB); PG8_STAGE(PG8_SA(0, 0), a2, voffA);
;             PG8_WAIT_V(8); PG8_WAIT_L(0); PG8_BAR; PG8_MMA(1, 0, At, B0); PG8_MMA(1, 1, At, B1); PG8_BAR; PG8_SCHED;
.LBB0_3676:
	s_add_u32 s20, s18, 0xfffe0080
	s_addc_u32 s21, s19, -1
	s_add_i32 s50, 0, 0x10000
	v_add_u32_e32 v79, s50, v1
	ds_read_b128 v[80:83], v79
	ds_read_b128 v[84:87], v79 offset:1024
	ds_read_b128 v[88:91], v79 offset:2048
	ds_read_b128 v[92:95], v79 offset:3072
	s_cmp_eq_u32 s49, 4
	s_cselect_b32 s23, s13, s21
	s_cselect_b32 s22, s45, s20
	s_cselect_b32 s21, s11, s48
	s_cselect_b32 s20, s46, s47
	v_lshl_add_u64 v[128:129], s[18:19], 0, v[74:75]
	s_add_i32 m0, s29, 0xc000
	ds_read_b128 v[96:99], v78
	ds_read_b128 v[100:103], v78 offset:1024
	ds_read_b128 v[104:107], v78 offset:2048
	ds_read_b128 v[108:111], v78 offset:3072
	ds_read_b128 v[112:115], v78 offset:4096
	ds_read_b128 v[116:119], v78 offset:5120
	ds_read_b128 v[120:123], v78 offset:6144
	ds_read_b128 v[124:127], v78 offset:7168
	global_load_lds_dwordx4 v[128:129], off
	v_lshl_add_u64 v[128:129], s[18:19], 0, v[76:77]
	s_add_i32 m0, s29, 0xe000
	s_nop 0
	global_load_lds_dwordx4 v[128:129], off
	s_nop 0
	s_nop 0
	s_waitcnt vmcnt(8)
	s_waitcnt lgkmcnt(0)
	v_mfma_f32_16x16x32_bf16 v[62:65], v[80:83], v[96:99], v[62:65]
	v_mfma_f32_16x16x32_bf16 v[58:61], v[88:91], v[96:99], v[58:61]
	s_barrier
	s_setprio 1
	s_waitcnt lgkmcnt(0)
	v_mfma_f32_16x16x32_bf16 v[54:57], v[80:83], v[104:107], v[54:57]
	v_mfma_f32_16x16x32_bf16 v[50:53], v[88:91], v[104:107], v[50:53]
	v_mfma_f32_16x16x32_bf16 v[46:49], v[80:83], v[112:115], v[46:49]
	v_mfma_f32_16x16x32_bf16 v[42:45], v[88:91], v[112:115], v[42:45]
	v_mfma_f32_16x16x32_bf16 v[38:41], v[80:83], v[120:123], v[38:41]
	v_mfma_f32_16x16x32_bf16 v[34:37], v[88:91], v[120:123], v[34:37]
	v_mfma_f32_16x16x32_bf16 v[62:65], v[84:87], v[100:103], v[62:65]
	v_mfma_f32_16x16x32_bf16 v[58:61], v[92:95], v[100:103], v[58:61]
	v_mfma_f32_16x16x32_bf16 v[54:57], v[84:87], v[108:111], v[54:57]
	v_mfma_f32_16x16x32_bf16 v[50:53], v[92:95], v[108:111], v[50:53]
	v_mfma_f32_16x16x32_bf16 v[46:49], v[84:87], v[116:119], v[46:49]
	v_mfma_f32_16x16x32_bf16 v[42:45], v[92:95], v[116:119], v[42:45]
	v_mfma_f32_16x16x32_bf16 v[38:41], v[84:87], v[124:127], v[38:41]
	v_mfma_f32_16x16x32_bf16 v[34:37], v[92:95], v[124:127], v[34:37]
	s_setprio 0
	s_setprio 1
	s_setprio 0
	s_barrier
	s_add_i32 s50, s50, s28
	v_lshl_add_u64 v[128:129], s[20:21], 0, v[70:71]
	s_mov_b32 m0, s50
	ds_read_b128 v[96:99], v78 offset:16384
	ds_read_b128 v[100:103], v78 offset:17408
	ds_read_b128 v[104:107], v78 offset:18432
	ds_read_b128 v[108:111], v78 offset:19456
	ds_read_b128 v[112:115], v78 offset:20480
	ds_read_b128 v[116:119], v78 offset:21504
	ds_read_b128 v[120:123], v78 offset:22528
	ds_read_b128 v[124:127], v78 offset:23552
	global_load_lds_dwordx4 v[128:129], off
	s_add_i32 m0, s50, 0x2000
	s_add_u32 s50, s20, 0x20000
	v_lshl_add_u64 v[130:131], s[20:21], 0, v[66:67]
	s_addc_u32 s51, s21, 0
	global_load_lds_dwordx4 v[130:131], off
	v_lshl_add_u64 v[132:133], s[50:51], 0, v[70:71]
	s_mov_b32 m0, s30
	v_lshl_add_u64 v[134:135], s[22:23], 0, v[68:69]
	global_load_lds_dwordx4 v[132:133], off
	v_lshl_add_u64 v[132:133], s[50:51], 0, v[66:67]
	s_mov_b32 m0, s31
	s_nop 0
	global_load_lds_dwordx4 v[132:133], off
	v_lshl_add_u64 v[132:133], s[22:23], 0, v[72:73]
	s_mov_b32 m0, s29
	s_nop 0
	global_load_lds_dwordx4 v[132:133], off
	s_mov_b32 m0, s33
	s_nop 0
	global_load_lds_dwordx4 v[134:135], off
	s_nop 0
	s_waitcnt vmcnt(8)
	s_waitcnt lgkmcnt(0)
	v_mfma_f32_16x16x32_bf16 v[30:33], v[80:83], v[96:99], v[30:33]
	v_mfma_f32_16x16x32_bf16 v[26:29], v[88:91], v[96:99], v[26:29]
	s_barrier
	s_setprio 1
	s_waitcnt lgkmcnt(0)
	v_mfma_f32_16x16x32_bf16 v[22:25], v[80:83], v[104:107], v[22:25]
	v_mfma_f32_16x16x32_bf16 v[18:21], v[88:91], v[104:107], v[18:21]
	v_mfma_f32_16x16x32_bf16 v[14:17], v[80:83], v[112:115], v[14:17]
	v_mfma_f32_16x16x32_bf16 v[10:13], v[88:91], v[112:115], v[10:13]
	v_mfma_f32_16x16x32_bf16 v[6:9], v[80:83], v[120:123], v[6:9]
	v_mfma_f32_16x16x32_bf16 v[2:5], v[88:91], v[120:123], v[2:5]
	v_mfma_f32_16x16x32_bf16 v[30:33], v[84:87], v[100:103], v[30:33]
	v_mfma_f32_16x16x32_bf16 v[26:29], v[92:95], v[100:103], v[26:29]
	v_mfma_f32_16x16x32_bf16 v[22:25], v[84:87], v[108:111], v[22:25]
	v_mfma_f32_16x16x32_bf16 v[18:21], v[92:95], v[108:111], v[18:21]
	v_mfma_f32_16x16x32_bf16 v[14:17], v[84:87], v[116:119], v[14:17]
	v_mfma_f32_16x16x32_bf16 v[10:13], v[92:95], v[116:119], v[10:13]
	v_mfma_f32_16x16x32_bf16 v[6:9], v[84:87], v[124:127], v[6:9]
	v_mfma_f32_16x16x32_bf16 v[2:5], v[92:95], v[124:127], v[2:5]
	s_setprio 0
	s_setprio 1
	s_setprio 0
	s_barrier
; #define PG8_STAGE(bufoff, gbase, voff) do { _Pragma("unroll") for (int _i = 0; _i < 2; ++_i) \
;         __builtin_amdgcn_global_load_lds((const unsigned*)((const char*)(gbase) + (voff)[_i]), (LAS unsigned*)(lds + (bufoff) + ldsw + _i * 8192), 16, 0, 0); } while (0)
; #define PG8_LDA(dst, b, h) do { _Pragma("unroll") for (int m = 0; m < 4; ++m) _Pragma("unroll") for (int k = 0; k < 2; ++k) dst[m][k] = *(const LAS bf16x8*)(lds + PG8_SA(b, h) + aoff + m * 2048 + k * 1024); } while (0)
; #define PG8_LDB(dst, b, h) do { _Pragma("unroll") for (int n = 0; n < 2; ++n) _Pragma("unroll") for (int k = 0; k < 2; ++k) dst[n][k] = *(const LAS bf16x8*)(lds + PG8_SB(b, h) + boff + n * 2048 + k * 1024); } while (0)
; #define PG8_MMA(ai, bj, At, Bt) do { __builtin_amdgcn_s_setprio(1); _Pragma("unroll") for (int m = 0; m < 4; ++m) _Pragma("unroll") for (int n = 0; n < 2; ++n) _Pragma("unroll") for (int k = 0; k < 2; ++k) \
;         acc[ai][bj][m][n] = __builtin_amdgcn_mfma_f32_16x16x32_bf16(Bt[n][k], At[m][k], acc[ai][bj][m][n], 0, 0, 0); __builtin_amdgcn_s_setprio(0); } while (0)
; #define PG8_WAIT_V(n) asm volatile("s_waitcnt vmcnt(" #n ")" ::: "memory")
; #define PG8_WAIT_L(n) asm volatile("s_waitcnt lgkmcnt(" #n ")" ::: "memory")
; #define PG8_BAR __builtin_amdgcn_s_barrier()
; #define PG8_SCHED __builtin_amdgcn_sched_barrier(0)
; template <class Epi, class Sched>
; __device__ __forceinline__ void gemm_phase(LAS unsigned char* lds, const Gemm g, const Sched& S, const Epi& E) {
;     ...
;             PG8_LDB(B0, 1, 0); PG8_LDB(B1, 1, 1); PG8_SCHED; PG8_LDA(At, 1, 0); PG8_STAGE(PG8_SA(0, 1), a2 + hstepA, voffA);
;             PG8_WAIT_V(8); PG8_WAIT_L(0); PG8_BAR; PG8_MMA(0, 0, At, B0); PG8_MMA(0, 1, At, B1); PG8_BAR; PG8_SCHED;
;             PG8_LDA(At, 1, 1); PG8_STAGE(PG8_SB(1, 0), b3, voffB); PG8_STAGE(PG8_SB(1, 1), b3 + hstepB, voffB); PG8_STAGE(PG8_SA(1, 0), a3, voffA);
;             PG8_WAIT_V(8); PG8_WAIT_L(0); PG8_BAR; PG8_MMA(1, 0, At, B0); PG8_MMA(1, 1, At, B1); PG8_BAR; PG8_SCHED;
;         }
;         if (wr == 0) PG8_BAR;
	s_add_i32 s50, 0, 0x18000
	v_add_u32_e32 v79, s50, v1
	ds_read_b128 v[80:83], v79
	ds_read_b128 v[84:87], v79 offset:1024
	ds_read_b128 v[88:91], v79 offset:2048
	ds_read_b128 v[92:95], v79 offset:3072
	s_add_u32 s22, s22, 0x20000
	s_addc_u32 s23, s23, 0
	s_mov_b32 m0, s34
	v_lshl_add_u64 v[136:137], s[22:23], 0, v[72:73]
	ds_read_b128 v[96:99], v78 offset:32768
	ds_read_b128 v[100:103], v78 offset:33792
	ds_read_b128 v[104:107], v78 offset:34816
	ds_read_b128 v[108:111], v78 offset:35840
	ds_read_b128 v[112:115], v78 offset:36864
	ds_read_b128 v[116:119], v78 offset:37888
	ds_read_b128 v[120:123], v78 offset:38912
	ds_read_b128 v[124:127], v78 offset:39936
	global_load_lds_dwordx4 v[136:137], off
	v_lshl_add_u64 v[136:137], s[22:23], 0, v[68:69]
	s_mov_b32 m0, s35
	s_nop 0
	global_load_lds_dwordx4 v[136:137], off
	s_nop 0
	s_nop 0
	s_waitcnt vmcnt(8)
	s_waitcnt lgkmcnt(0)
	v_mfma_f32_16x16x32_bf16 v[62:65], v[80:83], v[96:99], v[62:65]
	v_mfma_f32_16x16x32_bf16 v[58:61], v[88:91], v[96:99], v[58:61]
	s_barrier
	s_setprio 1
	s_waitcnt lgkmcnt(0)
	v_mfma_f32_16x16x32_bf16 v[54:57], v[80:83], v[104:107], v[54:57]
	v_mfma_f32_16x16x32_bf16 v[50:53], v[88:91], v[104:107], v[50:53]
	v_mfma_f32_16x16x32_bf16 v[46:49], v[80:83], v[112:115], v[46:49]
	v_mfma_f32_16x16x32_bf16 v[42:45], v[88:91], v[112:115], v[42:45]
	v_mfma_f32_16x16x32_bf16 v[38:41], v[80:83], v[120:123], v[38:41]
	v_mfma_f32_16x16x32_bf16 v[34:37], v[88:91], v[120:123], v[34:37]
	v_mfma_f32_16x16x32_bf16 v[62:65], v[84:87], v[100:103], v[62:65]
	v_mfma_f32_16x16x32_bf16 v[58:61], v[92:95], v[100:103], v[58:61]
	v_mfma_f32_16x16x32_bf16 v[54:57], v[84:87], v[108:111], v[54:57]
	v_mfma_f32_16x16x32_bf16 v[50:53], v[92:95], v[108:111], v[50:53]
	v_mfma_f32_16x16x32_bf16 v[46:49], v[84:87], v[116:119], v[46:49]
	v_mfma_f32_16x16x32_bf16 v[42:45], v[92:95], v[116:119], v[42:45]
	v_mfma_f32_16x16x32_bf16 v[38:41], v[84:87], v[124:127], v[38:41]
	v_mfma_f32_16x16x32_bf16 v[34:37], v[92:95], v[124:127], v[34:37]
	s_setprio 0
	s_setprio 1
	s_setprio 0
	s_barrier
	s_add_i32 s22, s50, s28
	v_lshl_add_u64 v[128:129], v[128:129], 0, s[56:57]
	s_mov_b32 m0, s22
	ds_read_b128 v[96:99], v78 offset:49152
	ds_read_b128 v[100:103], v78 offset:50176
	ds_read_b128 v[104:107], v78 offset:51200
	ds_read_b128 v[108:111], v78 offset:52224
	ds_read_b128 v[112:115], v78 offset:53248
	ds_read_b128 v[116:119], v78 offset:54272
	ds_read_b128 v[120:123], v78 offset:55296
	ds_read_b128 v[124:127], v78 offset:56320
	global_load_lds_dwordx4 v[128:129], off
	s_add_i32 m0, s22, 0x2000
	s_add_u32 s20, s20, 0x20080
	v_lshl_add_u64 v[128:129], v[130:131], 0, s[56:57]
	s_addc_u32 s21, s21, 0
	global_load_lds_dwordx4 v[128:129], off
	v_lshl_add_u64 v[128:129], s[20:21], 0, v[70:71]
	s_mov_b32 m0, s40
	s_nop 0
	global_load_lds_dwordx4 v[128:129], off
	v_lshl_add_u64 v[128:129], s[20:21], 0, v[66:67]
	s_mov_b32 m0, s41
	s_nop 0
	global_load_lds_dwordx4 v[128:129], off
	v_lshl_add_u64 v[128:129], v[132:133], 0, s[56:57]
	s_mov_b32 m0, s38
	s_nop 0
	global_load_lds_dwordx4 v[128:129], off
	v_lshl_add_u64 v[128:129], v[134:135], 0, s[56:57]
	s_mov_b32 m0, s39
	s_nop 0
	global_load_lds_dwordx4 v[128:129], off
	s_waitcnt vmcnt(8)
	s_waitcnt lgkmcnt(0)
	v_mfma_f32_16x16x32_bf16 v[30:33], v[80:83], v[96:99], v[30:33]
	v_mfma_f32_16x16x32_bf16 v[26:29], v[88:91], v[96:99], v[26:29]
	s_barrier
	s_setprio 1
	s_waitcnt lgkmcnt(0)
	v_mfma_f32_16x16x32_bf16 v[22:25], v[80:83], v[104:107], v[22:25]
	v_mfma_f32_16x16x32_bf16 v[18:21], v[88:91], v[104:107], v[18:21]
	v_mfma_f32_16x16x32_bf16 v[14:17], v[80:83], v[112:115], v[14:17]
	v_mfma_f32_16x16x32_bf16 v[10:13], v[88:91], v[112:115], v[10:13]
	v_mfma_f32_16x16x32_bf16 v[6:9], v[80:83], v[120:123], v[6:9]
	v_mfma_f32_16x16x32_bf16 v[2:5], v[88:91], v[120:123], v[2:5]
	v_mfma_f32_16x16x32_bf16 v[30:33], v[84:87], v[100:103], v[30:33]
	v_mfma_f32_16x16x32_bf16 v[26:29], v[92:95], v[100:103], v[26:29]
	v_mfma_f32_16x16x32_bf16 v[22:25], v[84:87], v[108:111], v[22:25]
	v_mfma_f32_16x16x32_bf16 v[18:21], v[92:95], v[108:111], v[18:21]
	v_mfma_f32_16x16x32_bf16 v[14:17], v[84:87], v[116:119], v[14:17]
	v_mfma_f32_16x16x32_bf16 v[10:13], v[92:95], v[116:119], v[10:13]
	v_mfma_f32_16x16x32_bf16 v[6:9], v[84:87], v[124:127], v[6:9]
	v_mfma_f32_16x16x32_bf16 v[2:5], v[92:95], v[124:127], v[2:5]
	s_setprio 0
	s_setprio 1
	s_setprio 0
	s_barrier
	s_add_i32 s49, s49, 2
	s_add_u32 s18, s18, 0x100
	s_addc_u32 s19, s19, 0
	s_add_u32 s47, s47, 0x100
	s_addc_u32 s48, s48, 0
	s_cmp_gt_u32 s49, 5
	s_cbranch_scc0 .LBB0_3676
	s_and_b64 vcc, exec, s[6:7]
	s_cbranch_vccz .LBB0_3679
	s_barrier

; #define PG8_STAGE(bufoff, gbase, voff) do { _Pragma("unroll") for (int _i = 0; _i < 2; ++_i) \
;         __builtin_amdgcn_global_load_lds((const unsigned*)((const char*)(gbase) + (voff)[_i]), (LAS unsigned*)(lds + (bufoff) + ldsw + _i * 8192), 16, 0, 0); } while (0)
; #define PG8_LDA(dst, b, h) do { _Pragma("unroll") for (int m = 0; m < 4; ++m) _Pragma("unroll") for (int k = 0; k < 2; ++k) dst[m][k] = *(const LAS bf16x8*)(lds + PG8_SA(b, h) + aoff + m * 2048 + k * 1024); } while (0)
; #define PG8_LDB(dst, b, h) do { _Pragma("unroll") for (int n = 0; n < 2; ++n) _Pragma("unroll") for (int k = 0; k < 2; ++k) dst[n][k] = *(const LAS bf16x8*)(lds + PG8_SB(b, h) + boff + n * 2048 + k * 1024); } while (0)
; #define PG8_MMA(ai, bj, At, Bt) do { __builtin_amdgcn_s_setprio(1); _Pragma("unroll") for (int m = 0; m < 4; ++m) _Pragma("unroll") for (int n = 0; n < 2; ++n) _Pragma("unroll") for (int k = 0; k < 2; ++k) \
;         acc[ai][bj][m][n] = __builtin_amdgcn_mfma_f32_16x16x32_bf16(Bt[n][k], At[m][k], acc[ai][bj][m][n], 0, 0, 0); __builtin_amdgcn_s_setprio(0); } while (0)
; #define PG8_WAIT_V(n) asm volatile("s_waitcnt vmcnt(" #n ")" ::: "memory")
; #define PG8_WAIT_L(n) asm volatile("s_waitcnt lgkmcnt(" #n ")" ::: "memory")
; #define PG8_BAR __builtin_amdgcn_s_barrier()
; #define PG8_SCHED __builtin_amdgcn_sched_barrier(0)
; template <class Epi, class Sched>
; __device__ __forceinline__ void gemm_phase(LAS unsigned char* lds, const Gemm g, const Sched& S, const Epi& E) {
;     ...
;         for (int t = 0; t < nt; t += 2) {
;             const bool last = (t == nt - 2);
;             const char* a1 = cA + (size_t)(t + 1) * kstep;
;             const char* a2 = last ? nA : cA + (size_t)(t + 2) * kstep; const char* b2 = last ? nB : cB + (size_t)(t + 2) * kstep;
;             const char* a3 = a2 + kstep; const char* b3 = b2 + kstep;
;             PG8_LDB(B0, 0, 0); PG8_LDB(B1, 0, 1); PG8_SCHED; PG8_LDA(At, 0, 0); PG8_STAGE(PG8_SA(1, 1), a1 + hstepA, voffA);
;             PG8_WAIT_V(8); PG8_WAIT_L(0); PG8_BAR; PG8_MMA(0, 0, At, B0); PG8_MMA(0, 1, At, B1); PG8_BAR; PG8_SCHED;
;             PG8_LDA(At, 0, 1); PG8_STAGE(PG8_SB(0, 0), b2, voffB); PG8_STAGE(PG8_SB(0, 1), b2 + hstepB, voffB); PG8_STAGE(PG8_SA(0, 0), a2, voffA);
;             PG8_WAIT_V(8); PG8_WAIT_L(0); PG8_BAR; PG8_MMA(1, 0, At, B0); PG8_MMA(1, 1, At, B1); PG8_BAR; PG8_SCHED;
.LBB0_3698:
	s_add_u32 s20, s18, 0xfffe0080
	s_addc_u32 s21, s19, -1
	s_add_i32 s50, 0, 0x10000
	v_add_u32_e32 v79, s50, v1
	ds_read_b128 v[80:83], v79
	ds_read_b128 v[84:87], v79 offset:1024
	ds_read_b128 v[88:91], v79 offset:2048
	ds_read_b128 v[92:95], v79 offset:3072
	s_cmp_eq_u32 s49, 4
	s_cselect_b32 s23, s13, s21
	s_cselect_b32 s22, s45, s20
	s_cselect_b32 s21, s11, s48
	s_cselect_b32 s20, s46, s47
	v_lshl_add_u64 v[128:129], s[18:19], 0, v[74:75]
	s_add_i32 m0, s29, 0xc000
	ds_read_b128 v[96:99], v78
	ds_read_b128 v[100:103], v78 offset:1024
	ds_read_b128 v[104:107], v78 offset:2048
	ds_read_b128 v[108:111], v78 offset:3072
	ds_read_b128 v[112:115], v78 offset:4096
	ds_read_b128 v[116:119], v78 offset:5120
	ds_read_b128 v[120:123], v78 offset:6144
	ds_read_b128 v[124:127], v78 offset:7168
	global_load_lds_dwordx4 v[128:129], off
	v_lshl_add_u64 v[128:129], s[18:19], 0, v[76:77]
	s_add_i32 m0, s29, 0xe000
	s_nop 0
	global_load_lds_dwordx4 v[128:129], off
	s_nop 0
	s_nop 0
	s_nop 0
	s_waitcnt vmcnt(8)
	s_waitcnt lgkmcnt(0)
	v_mfma_f32_16x16x32_bf16 v[62:65], v[80:83], v[96:99], v[62:65]
	v_mfma_f32_16x16x32_bf16 v[58:61], v[88:91], v[96:99], v[58:61]
	s_barrier
	s_setprio 1
	s_waitcnt lgkmcnt(0)
	v_mfma_f32_16x16x32_bf16 v[54:57], v[80:83], v[104:107], v[54:57]
	v_mfma_f32_16x16x32_bf16 v[50:53], v[88:91], v[104:107], v[50:53]
	v_mfma_f32_16x16x32_bf16 v[46:49], v[80:83], v[112:115], v[46:49]
	v_mfma_f32_16x16x32_bf16 v[42:45], v[88:91], v[112:115], v[42:45]
	v_mfma_f32_16x16x32_bf16 v[38:41], v[80:83], v[120:123], v[38:41]
	v_mfma_f32_16x16x32_bf16 v[34:37], v[88:91], v[120:123], v[34:37]
	v_mfma_f32_16x16x32_bf16 v[62:65], v[84:87], v[100:103], v[62:65]
	v_mfma_f32_16x16x32_bf16 v[58:61], v[92:95], v[100:103], v[58:61]
	v_mfma_f32_16x16x32_bf16 v[54:57], v[84:87], v[108:111], v[54:57]
	v_mfma_f32_16x16x32_bf16 v[50:53], v[92:95], v[108:111], v[50:53]
	v_mfma_f32_16x16x32_bf16 v[46:49], v[84:87], v[116:119], v[46:49]
	v_mfma_f32_16x16x32_bf16 v[42:45], v[92:95], v[116:119], v[42:45]
	v_mfma_f32_16x16x32_bf16 v[38:41], v[84:87], v[124:127], v[38:41]
	v_mfma_f32_16x16x32_bf16 v[34:37], v[92:95], v[124:127], v[34:37]
	s_setprio 0
	s_setprio 1
	s_setprio 0
	s_barrier
	s_add_i32 s50, s50, s28
	v_lshl_add_u64 v[128:129], s[20:21], 0, v[70:71]
	s_mov_b32 m0, s50
	ds_read_b128 v[96:99], v78 offset:16384
	ds_read_b128 v[100:103], v78 offset:17408
	ds_read_b128 v[104:107], v78 offset:18432
	ds_read_b128 v[108:111], v78 offset:19456
	ds_read_b128 v[112:115], v78 offset:20480
	ds_read_b128 v[116:119], v78 offset:21504
	ds_read_b128 v[120:123], v78 offset:22528
	ds_read_b128 v[124:127], v78 offset:23552
	global_load_lds_dwordx4 v[128:129], off
	s_add_i32 m0, s50, 0x2000
	s_add_u32 s50, s20, 0x20000
	v_lshl_add_u64 v[130:131], s[20:21], 0, v[66:67]
	s_addc_u32 s51, s21, 0
	global_load_lds_dwordx4 v[130:131], off
	v_lshl_add_u64 v[132:133], s[50:51], 0, v[70:71]
	s_mov_b32 m0, s30
	v_lshl_add_u64 v[134:135], s[22:23], 0, v[68:69]
	global_load_lds_dwordx4 v[132:133], off
	v_lshl_add_u64 v[132:133], s[50:51], 0, v[66:67]
	s_mov_b32 m0, s31
	s_nop 0
	global_load_lds_dwordx4 v[132:133], off
	v_lshl_add_u64 v[132:133], s[22:23], 0, v[72:73]
	s_mov_b32 m0, s29
	s_nop 0
	global_load_lds_dwordx4 v[132:133], off
	s_mov_b32 m0, s33
	s_nop 0
	global_load_lds_dwordx4 v[134:135], off
	s_nop 0
	s_waitcnt vmcnt(8)
	s_waitcnt lgkmcnt(0)
	v_mfma_f32_16x16x32_bf16 v[30:33], v[80:83], v[96:99], v[30:33]
	v_mfma_f32_16x16x32_bf16 v[26:29], v[88:91], v[96:99], v[26:29]
	s_barrier
	s_setprio 1
	s_waitcnt lgkmcnt(0)
	v_mfma_f32_16x16x32_bf16 v[22:25], v[80:83], v[104:107], v[22:25]
	v_mfma_f32_16x16x32_bf16 v[18:21], v[88:91], v[104:107], v[18:21]
	v_mfma_f32_16x16x32_bf16 v[14:17], v[80:83], v[112:115], v[14:17]
	v_mfma_f32_16x16x32_bf16 v[10:13], v[88:91], v[112:115], v[10:13]
	v_mfma_f32_16x16x32_bf16 v[6:9], v[80:83], v[120:123], v[6:9]
	v_mfma_f32_16x16x32_bf16 v[2:5], v[88:91], v[120:123], v[2:5]
	v_mfma_f32_16x16x32_bf16 v[30:33], v[84:87], v[100:103], v[30:33]
	v_mfma_f32_16x16x32_bf16 v[26:29], v[92:95], v[100:103], v[26:29]
	v_mfma_f32_16x16x32_bf16 v[22:25], v[84:87], v[108:111], v[22:25]
	v_mfma_f32_16x16x32_bf16 v[18:21], v[92:95], v[108:111], v[18:21]
	v_mfma_f32_16x16x32_bf16 v[14:17], v[84:87], v[116:119], v[14:17]
	v_mfma_f32_16x16x32_bf16 v[10:13], v[92:95], v[116:119], v[10:13]
	v_mfma_f32_16x16x32_bf16 v[6:9], v[84:87], v[124:127], v[6:9]
	v_mfma_f32_16x16x32_bf16 v[2:5], v[92:95], v[124:127], v[2:5]
	s_setprio 0
	s_setprio 1
	s_setprio 0
	s_barrier
; #define PG8_STAGE(bufoff, gbase, voff) do { _Pragma("unroll") for (int _i = 0; _i < 2; ++_i) \
;         __builtin_amdgcn_global_load_lds((const unsigned*)((const char*)(gbase) + (voff)[_i]), (LAS unsigned*)(lds + (bufoff) + ldsw + _i * 8192), 16, 0, 0); } while (0)
; #define PG8_LDA(dst, b, h) do { _Pragma("unroll") for (int m = 0; m < 4; ++m) _Pragma("unroll") for (int k = 0; k < 2; ++k) dst[m][k] = *(const LAS bf16x8*)(lds + PG8_SA(b, h) + aoff + m * 2048 + k * 1024); } while (0)
; #define PG8_LDB(dst, b, h) do { _Pragma("unroll") for (int n = 0; n < 2; ++n) _Pragma("unroll") for (int k = 0; k < 2; ++k) dst[n][k] = *(const LAS bf16x8*)(lds + PG8_SB(b, h) + boff + n * 2048 + k * 1024); } while (0)
; #define PG8_MMA(ai, bj, At, Bt) do { __builtin_amdgcn_s_setprio(1); _Pragma("unroll") for (int m = 0; m < 4; ++m) _Pragma("unroll") for (int n = 0; n < 2; ++n) _Pragma("unroll") for (int k = 0; k < 2; ++k) \
;         acc[ai][bj][m][n] = __builtin_amdgcn_mfma_f32_16x16x32_bf16(Bt[n][k], At[m][k], acc[ai][bj][m][n], 0, 0, 0); __builtin_amdgcn_s_setprio(0); } while (0)
; #define PG8_WAIT_V(n) asm volatile("s_waitcnt vmcnt(" #n ")" ::: "memory")
; #define PG8_WAIT_L(n) asm volatile("s_waitcnt lgkmcnt(" #n ")" ::: "memory")
; #define PG8_BAR __builtin_amdgcn_s_barrier()
; #define PG8_SCHED __builtin_amdgcn_sched_barrier(0)
; template <class Epi, class Sched>
; __device__ __forceinline__ void gemm_phase(LAS unsigned char* lds, const Gemm g, const Sched& S, const Epi& E) {
;     ...
;             PG8_LDB(B0, 1, 0); PG8_LDB(B1, 1, 1); PG8_SCHED; PG8_LDA(At, 1, 0); PG8_STAGE(PG8_SA(0, 1), a2 + hstepA, voffA);
;             PG8_WAIT_V(8); PG8_WAIT_L(0); PG8_BAR; PG8_MMA(0, 0, At, B0); PG8_MMA(0, 1, At, B1); PG8_BAR; PG8_SCHED;
;             PG8_LDA(At, 1, 1); PG8_STAGE(PG8_SB(1, 0), b3, voffB); PG8_STAGE(PG8_SB(1, 1), b3 + hstepB, voffB); PG8_STAGE(PG8_SA(1, 0), a3, voffA);
;             PG8_WAIT_V(8); PG8_WAIT_L(0); PG8_BAR; PG8_MMA(1, 0, At, B0); PG8_MMA(1, 1, At, B1); PG8_BAR; PG8_SCHED;
;         }
;         if (wr == 0) PG8_BAR;
	s_add_i32 s50, 0, 0x18000
	v_add_u32_e32 v79, s50, v1
	ds_read_b128 v[80:83], v79
	ds_read_b128 v[84:87], v79 offset:1024
	ds_read_b128 v[88:91], v79 offset:2048
	ds_read_b128 v[92:95], v79 offset:3072
	s_add_u32 s22, s22, 0x20000
	s_addc_u32 s23, s23, 0
	s_mov_b32 m0, s34
	v_lshl_add_u64 v[136:137], s[22:23], 0, v[72:73]
	ds_read_b128 v[96:99], v78 offset:32768
	ds_read_b128 v[100:103], v78 offset:33792
	ds_read_b128 v[104:107], v78 offset:34816
	ds_read_b128 v[108:111], v78 offset:35840
	ds_read_b128 v[112:115], v78 offset:36864
	ds_read_b128 v[116:119], v78 offset:37888
	ds_read_b128 v[120:123], v78 offset:38912
	ds_read_b128 v[124:127], v78 offset:39936
	global_load_lds_dwordx4 v[136:137], off
	v_lshl_add_u64 v[136:137], s[22:23], 0, v[68:69]
	s_mov_b32 m0, s35
	s_nop 0
	global_load_lds_dwordx4 v[136:137], off
	s_nop 0
	s_nop 0
	s_waitcnt vmcnt(8)
	s_waitcnt lgkmcnt(0)
	v_mfma_f32_16x16x32_bf16 v[62:65], v[80:83], v[96:99], v[62:65]
	v_mfma_f32_16x16x32_bf16 v[58:61], v[88:91], v[96:99], v[58:61]
	s_barrier
	s_setprio 1
	s_waitcnt lgkmcnt(0)
	v_mfma_f32_16x16x32_bf16 v[54:57], v[80:83], v[104:107], v[54:57]
	v_mfma_f32_16x16x32_bf16 v[50:53], v[88:91], v[104:107], v[50:53]
	v_mfma_f32_16x16x32_bf16 v[46:49], v[80:83], v[112:115], v[46:49]
	v_mfma_f32_16x16x32_bf16 v[42:45], v[88:91], v[112:115], v[42:45]
	v_mfma_f32_16x16x32_bf16 v[38:41], v[80:83], v[120:123], v[38:41]
	v_mfma_f32_16x16x32_bf16 v[34:37], v[88:91], v[120:123], v[34:37]
	v_mfma_f32_16x16x32_bf16 v[62:65], v[84:87], v[100:103], v[62:65]
	v_mfma_f32_16x16x32_bf16 v[58:61], v[92:95], v[100:103], v[58:61]
	v_mfma_f32_16x16x32_bf16 v[54:57], v[84:87], v[108:111], v[54:57]
	v_mfma_f32_16x16x32_bf16 v[50:53], v[92:95], v[108:111], v[50:53]
	v_mfma_f32_16x16x32_bf16 v[46:49], v[84:87], v[116:119], v[46:49]
	v_mfma_f32_16x16x32_bf16 v[42:45], v[92:95], v[116:119], v[42:45]
	v_mfma_f32_16x16x32_bf16 v[38:41], v[84:87], v[124:127], v[38:41]
	v_mfma_f32_16x16x32_bf16 v[34:37], v[92:95], v[124:127], v[34:37]
	s_setprio 0
	s_setprio 1
	s_setprio 0
	s_barrier
	s_add_i32 s22, s50, s28
	v_lshl_add_u64 v[128:129], v[128:129], 0, s[56:57]
	s_mov_b32 m0, s22
	ds_read_b128 v[96:99], v78 offset:49152
	ds_read_b128 v[100:103], v78 offset:50176
	ds_read_b128 v[104:107], v78 offset:51200
	ds_read_b128 v[108:111], v78 offset:52224
	ds_read_b128 v[112:115], v78 offset:53248
	ds_read_b128 v[116:119], v78 offset:54272
	ds_read_b128 v[120:123], v78 offset:55296
	ds_read_b128 v[124:127], v78 offset:56320
	global_load_lds_dwordx4 v[128:129], off
	s_add_i32 m0, s22, 0x2000
	s_add_u32 s20, s20, 0x20080
	v_lshl_add_u64 v[128:129], v[130:131], 0, s[56:57]
	s_addc_u32 s21, s21, 0
	global_load_lds_dwordx4 v[128:129], off
	v_lshl_add_u64 v[128:129], s[20:21], 0, v[70:71]
	s_mov_b32 m0, s40
	s_nop 0
	global_load_lds_dwordx4 v[128:129], off
	v_lshl_add_u64 v[128:129], s[20:21], 0, v[66:67]
	s_mov_b32 m0, s41
	s_nop 0
	global_load_lds_dwordx4 v[128:129], off
	v_lshl_add_u64 v[128:129], v[132:133], 0, s[56:57]
	s_mov_b32 m0, s38
	s_nop 0
	global_load_lds_dwordx4 v[128:129], off
	v_lshl_add_u64 v[128:129], v[134:135], 0, s[56:57]
	s_mov_b32 m0, s39
	s_nop 0
	global_load_lds_dwordx4 v[128:129], off
	s_waitcnt vmcnt(8)
	s_waitcnt lgkmcnt(0)
	v_mfma_f32_16x16x32_bf16 v[30:33], v[80:83], v[96:99], v[30:33]
	v_mfma_f32_16x16x32_bf16 v[26:29], v[88:91], v[96:99], v[26:29]
	s_barrier
	s_setprio 1
	s_waitcnt lgkmcnt(0)
	v_mfma_f32_16x16x32_bf16 v[22:25], v[80:83], v[104:107], v[22:25]
	v_mfma_f32_16x16x32_bf16 v[18:21], v[88:91], v[104:107], v[18:21]
	v_mfma_f32_16x16x32_bf16 v[14:17], v[80:83], v[112:115], v[14:17]
	v_mfma_f32_16x16x32_bf16 v[10:13], v[88:91], v[112:115], v[10:13]
	v_mfma_f32_16x16x32_bf16 v[6:9], v[80:83], v[120:123], v[6:9]
	v_mfma_f32_16x16x32_bf16 v[2:5], v[88:91], v[120:123], v[2:5]
	v_mfma_f32_16x16x32_bf16 v[30:33], v[84:87], v[100:103], v[30:33]
	v_mfma_f32_16x16x32_bf16 v[26:29], v[92:95], v[100:103], v[26:29]
	v_mfma_f32_16x16x32_bf16 v[22:25], v[84:87], v[108:111], v[22:25]
	v_mfma_f32_16x16x32_bf16 v[18:21], v[92:95], v[108:111], v[18:21]
	v_mfma_f32_16x16x32_bf16 v[14:17], v[84:87], v[116:119], v[14:17]
	v_mfma_f32_16x16x32_bf16 v[10:13], v[92:95], v[116:119], v[10:13]
	v_mfma_f32_16x16x32_bf16 v[6:9], v[84:87], v[124:127], v[6:9]
	v_mfma_f32_16x16x32_bf16 v[2:5], v[92:95], v[124:127], v[2:5]
	s_setprio 0
	s_setprio 1
	s_setprio 0
	s_barrier
	s_add_i32 s49, s49, 2
	s_add_u32 s18, s18, 0x100
	s_addc_u32 s19, s19, 0
	s_add_u32 s47, s47, 0x100
	s_addc_u32 s48, s48, 0
	s_cmp_gt_u32 s49, 5
	s_cbranch_scc0 .LBB0_3698
	s_and_b64 vcc, exec, s[6:7]
	s_cbranch_vccz .LBB0_3701
	s_barrier

; #define PG8_STAGE(bufoff, gbase, voff) do { _Pragma("unroll") for (int _i = 0; _i < 2; ++_i) \
;         __builtin_amdgcn_global_load_lds((const unsigned*)((const char*)(gbase) + (voff)[_i]), (LAS unsigned*)(lds + (bufoff) + ldsw + _i * 8192), 16, 0, 0); } while (0)
; #define PG8_LDA(dst, b, h) do { _Pragma("unroll") for (int m = 0; m < 4; ++m) _Pragma("unroll") for (int k = 0; k < 2; ++k) dst[m][k] = *(const LAS bf16x8*)(lds + PG8_SA(b, h) + aoff + m * 2048 + k * 1024); } while (0)
; #define PG8_LDB(dst, b, h) do { _Pragma("unroll") for (int n = 0; n < 2; ++n) _Pragma("unroll") for (int k = 0; k < 2; ++k) dst[n][k] = *(const LAS bf16x8*)(lds + PG8_SB(b, h) + boff + n * 2048 + k * 1024); } while (0)
; #define PG8_MMA(ai, bj, At, Bt) do { __builtin_amdgcn_s_setprio(1); _Pragma("unroll") for (int m = 0; m < 4; ++m) _Pragma("unroll") for (int n = 0; n < 2; ++n) _Pragma("unroll") for (int k = 0; k < 2; ++k) \
;         acc[ai][bj][m][n] = __builtin_amdgcn_mfma_f32_16x16x32_bf16(Bt[n][k], At[m][k], acc[ai][bj][m][n], 0, 0, 0); __builtin_amdgcn_s_setprio(0); } while (0)
; #define PG8_WAIT_V(n) asm volatile("s_waitcnt vmcnt(" #n ")" ::: "memory")
; template <class Epi, class Sched>
; __device__ __forceinline__ void gemm_phase(LAS unsigned char* lds, const Gemm g, const Sched& S, const Epi& E) {
;     ...
;         const bool has_next = S.next(ui + 1, nxt);
;         const char* nA = has_next ? (const char*)g.A + (size_t)nxt.pm * tstepA : cA; const char* nB = has_next ? (const char*)g.Bt + (size_t)nxt.pn * tstepB : cB;
;         for (int t = 0; t < nt; t += 2) {
;             const bool last = (t == nt - 2);
;             const char* a1 = cA + (size_t)(t + 1) * kstep;
;             const char* a2 = last ? nA : cA + (size_t)(t + 2) * kstep; const char* b2 = last ? nB : cB + (size_t)(t + 2) * kstep;
;             const char* a3 = a2 + kstep; const char* b3 = b2 + kstep;
;             PG8_LDB(B0, 0, 0); PG8_LDB(B1, 0, 1); PG8_SCHED; PG8_LDA(At, 0, 0); PG8_STAGE(PG8_SA(1, 1), a1 + hstepA, voffA);
;             PG8_WAIT_V(8); PG8_WAIT_L(0); PG8_BAR; PG8_MMA(0, 0, At, B0); PG8_MMA(0, 1, At, B1); PG8_BAR; PG8_SCHED;
;             PG8_LDA(At, 0, 1); PG8_STAGE(PG8_SB(0, 0), b2, voffB); PG8_STAGE(PG8_SB(0, 1), b2 + hstepB, voffB); PG8_STAGE(PG8_SA(0, 0), a2, voffA);
;             PG8_WAIT_V(8); PG8_WAIT_L(0); PG8_BAR; PG8_MMA(1, 0, At, B0); PG8_MMA(1, 1, At, B1); PG8_BAR; PG8_SCHED;
.LBB0_4095:
	s_add_u32 s22, s20, 0xfff80080
	s_addc_u32 s23, s21, -1
	s_add_i32 s46, 0, 0x10000
	s_cmp_eq_u32 s45, 28
	s_cselect_b32 s25, s11, s23
	s_cselect_b32 s24, s17, s22
	s_cselect_b32 s23, s7, s44
	s_cselect_b32 s22, s19, s43
	s_add_i32 s49, 0, 0x14000
	v_add_u32_e32 v170, s46, v1
	v_add_u32_e32 v174, s49, v1
	ds_read_b128 v[130:133], v170
	ds_read_b128 v[134:137], v170 offset:1024
	ds_read_b128 v[166:169], v170 offset:2048
	ds_read_b128 v[170:173], v170 offset:3072
	ds_read_b128 v[178:181], v174
	ds_read_b128 v[182:185], v174 offset:1024
	ds_read_b128 v[186:189], v174 offset:2048
	ds_read_b128 v[190:193], v174 offset:3072
	v_lshl_add_u64 v[174:175], s[20:21], 0, v[162:163]
	s_add_i32 m0, s31, 0xc000
	ds_read_b128 v[208:211], v176
	ds_read_b128 v[212:215], v176 offset:1024
	ds_read_b128 v[216:219], v176 offset:2048
	ds_read_b128 v[220:223], v176 offset:3072
	ds_read_b128 v[224:227], v176 offset:4096
	ds_read_b128 v[228:231], v176 offset:5120
	ds_read_b128 v[232:235], v176 offset:6144
	ds_read_b128 v[236:239], v176 offset:7168
	global_load_lds_dwordx4 v[174:175], off
	v_lshl_add_u64 v[174:175], s[20:21], 0, v[164:165]
	s_add_i32 m0, s31, 0xe000
	s_nop 0
	global_load_lds_dwordx4 v[174:175], off
	s_nop 0
	s_nop 0
	s_waitcnt vmcnt(8)
	s_waitcnt lgkmcnt(0)
	v_mfma_f32_16x16x32_bf16 v[126:129], v[130:133], v[208:211], v[126:129]
	v_mfma_f32_16x16x32_bf16 v[122:125], v[166:169], v[208:211], v[122:125]
	s_barrier
	s_setprio 1
	s_waitcnt lgkmcnt(0)
	v_mfma_f32_16x16x32_bf16 v[110:113], v[130:133], v[216:219], v[110:113]
	v_mfma_f32_16x16x32_bf16 v[106:109], v[166:169], v[216:219], v[106:109]
	v_mfma_f32_16x16x32_bf16 v[94:97], v[130:133], v[224:227], v[94:97]
	v_mfma_f32_16x16x32_bf16 v[90:93], v[166:169], v[224:227], v[90:93]
	v_mfma_f32_16x16x32_bf16 v[78:81], v[130:133], v[232:235], v[78:81]
	v_mfma_f32_16x16x32_bf16 v[74:77], v[166:169], v[232:235], v[74:77]
	v_mfma_f32_16x16x32_bf16 v[126:129], v[134:137], v[212:215], v[126:129]
	v_mfma_f32_16x16x32_bf16 v[122:125], v[170:173], v[212:215], v[122:125]
	v_mfma_f32_16x16x32_bf16 v[110:113], v[134:137], v[220:223], v[110:113]
	v_mfma_f32_16x16x32_bf16 v[106:109], v[170:173], v[220:223], v[106:109]
	v_mfma_f32_16x16x32_bf16 v[94:97], v[134:137], v[228:231], v[94:97]
	v_mfma_f32_16x16x32_bf16 v[90:93], v[170:173], v[228:231], v[90:93]
	v_mfma_f32_16x16x32_bf16 v[78:81], v[134:137], v[236:239], v[78:81]
	v_mfma_f32_16x16x32_bf16 v[74:77], v[170:173], v[236:239], v[74:77]
	s_setprio 0
	s_setprio 1
	v_mfma_f32_16x16x32_bf16 v[118:121], v[178:181], v[208:211], v[118:121]
	v_mfma_f32_16x16x32_bf16 v[114:117], v[186:189], v[208:211], v[114:117]
	v_mfma_f32_16x16x32_bf16 v[102:105], v[178:181], v[216:219], v[102:105]
	v_mfma_f32_16x16x32_bf16 v[98:101], v[186:189], v[216:219], v[98:101]
	v_mfma_f32_16x16x32_bf16 v[86:89], v[178:181], v[224:227], v[86:89]
	v_mfma_f32_16x16x32_bf16 v[82:85], v[186:189], v[224:227], v[82:85]
	v_mfma_f32_16x16x32_bf16 v[70:73], v[178:181], v[232:235], v[70:73]
	v_mfma_f32_16x16x32_bf16 v[66:69], v[186:189], v[232:235], v[66:69]
	v_mfma_f32_16x16x32_bf16 v[118:121], v[182:185], v[212:215], v[118:121]
	v_mfma_f32_16x16x32_bf16 v[114:117], v[190:193], v[212:215], v[114:117]
	v_mfma_f32_16x16x32_bf16 v[102:105], v[182:185], v[220:223], v[102:105]
	v_mfma_f32_16x16x32_bf16 v[98:101], v[190:193], v[220:223], v[98:101]
	v_mfma_f32_16x16x32_bf16 v[86:89], v[182:185], v[228:231], v[86:89]
	v_mfma_f32_16x16x32_bf16 v[82:85], v[190:193], v[228:231], v[82:85]
	v_mfma_f32_16x16x32_bf16 v[70:73], v[182:185], v[236:239], v[70:73]
	v_mfma_f32_16x16x32_bf16 v[66:69], v[190:193], v[236:239], v[66:69]
	s_setprio 0
	s_barrier
	s_add_i32 s46, s46, s30
	v_lshl_add_u64 v[174:175], s[22:23], 0, v[140:141]
	s_mov_b32 m0, s46
	ds_read_b128 v[208:211], v176 offset:16384
	ds_read_b128 v[212:215], v176 offset:17408
	ds_read_b128 v[216:219], v176 offset:18432
	ds_read_b128 v[220:223], v176 offset:19456
	ds_read_b128 v[224:227], v176 offset:20480
	ds_read_b128 v[228:231], v176 offset:21504
	ds_read_b128 v[232:235], v176 offset:22528
	ds_read_b128 v[236:239], v176 offset:23552
	global_load_lds_dwordx4 v[174:175], off
	s_add_i32 m0, s46, 0x2000
	s_add_u32 s46, s22, 0x80000
	v_lshl_add_u64 v[240:241], s[22:23], 0, v[144:145]
	s_addc_u32 s47, s23, 0
	s_add_i32 s49, s49, s30
	global_load_lds_dwordx4 v[240:241], off
	v_lshl_add_u64 v[242:243], s[46:47], 0, v[140:141]
	s_mov_b32 m0, s49
	v_lshl_add_u64 v[244:245], s[24:25], 0, v[142:143]
	global_load_lds_dwordx4 v[242:243], off
	v_lshl_add_u64 v[242:243], s[46:47], 0, v[144:145]
	s_add_i32 m0, s49, 0x2000
	s_nop 0
	global_load_lds_dwordx4 v[242:243], off
	v_lshl_add_u64 v[242:243], s[24:25], 0, v[138:139]
	s_mov_b32 m0, s31
	s_nop 0
	global_load_lds_dwordx4 v[242:243], off
	s_mov_b32 m0, s33
	s_nop 0
	global_load_lds_dwordx4 v[244:245], off
	s_nop 0
	s_nop 0
	s_nop 0
	s_waitcnt vmcnt(8)
	s_waitcnt lgkmcnt(0)
	v_mfma_f32_16x16x32_bf16 v[62:65], v[130:133], v[208:211], v[62:65]
	v_mfma_f32_16x16x32_bf16 v[58:61], v[166:169], v[208:211], v[58:61]
	s_barrier
; #define PG8_STAGE(bufoff, gbase, voff) do { _Pragma("unroll") for (int _i = 0; _i < 2; ++_i) \
;         __builtin_amdgcn_global_load_lds((const unsigned*)((const char*)(gbase) + (voff)[_i]), (LAS unsigned*)(lds + (bufoff) + ldsw + _i * 8192), 16, 0, 0); } while (0)
; #define PG8_LDA(dst, b, h) do { _Pragma("unroll") for (int m = 0; m < 4; ++m) _Pragma("unroll") for (int k = 0; k < 2; ++k) dst[m][k] = *(const LAS bf16x8*)(lds + PG8_SA(b, h) + aoff + m * 2048 + k * 1024); } while (0)
; #define PG8_LDB(dst, b, h) do { _Pragma("unroll") for (int n = 0; n < 2; ++n) _Pragma("unroll") for (int k = 0; k < 2; ++k) dst[n][k] = *(const LAS bf16x8*)(lds + PG8_SB(b, h) + boff + n * 2048 + k * 1024); } while (0)
; #define PG8_MMA(ai, bj, At, Bt) do { __builtin_amdgcn_s_setprio(1); _Pragma("unroll") for (int m = 0; m < 4; ++m) _Pragma("unroll") for (int n = 0; n < 2; ++n) _Pragma("unroll") for (int k = 0; k < 2; ++k) \
;         acc[ai][bj][m][n] = __builtin_amdgcn_mfma_f32_16x16x32_bf16(Bt[n][k], At[m][k], acc[ai][bj][m][n], 0, 0, 0); __builtin_amdgcn_s_setprio(0); } while (0)
; #define PG8_WAIT_V(n) asm volatile("s_waitcnt vmcnt(" #n ")" ::: "memory")
; #define PG8_WAIT_L(n) asm volatile("s_waitcnt lgkmcnt(" #n ")" ::: "memory")
; #define PG8_BAR __builtin_amdgcn_s_barrier()
; #define PG8_SCHED __builtin_amdgcn_sched_barrier(0)
; template <class Epi, class Sched>
; __device__ __forceinline__ void gemm_phase(LAS unsigned char* lds, const Gemm g, const Sched& S, const Epi& E) {
;     ...
;             PG8_WAIT_V(8); PG8_WAIT_L(0); PG8_BAR; PG8_MMA(1, 0, At, B0); PG8_MMA(1, 1, At, B1); PG8_BAR; PG8_SCHED;
;             PG8_LDB(B0, 1, 0); PG8_LDB(B1, 1, 1); PG8_SCHED; PG8_LDA(At, 1, 0); PG8_STAGE(PG8_SA(0, 1), a2 + hstepA, voffA);
;             PG8_WAIT_V(8); PG8_WAIT_L(0); PG8_BAR; PG8_MMA(0, 0, At, B0); PG8_MMA(0, 1, At, B1); PG8_BAR; PG8_SCHED;
	s_setprio 1
	s_waitcnt lgkmcnt(0)
	v_mfma_f32_16x16x32_bf16 v[46:49], v[130:133], v[216:219], v[46:49]
	v_mfma_f32_16x16x32_bf16 v[42:45], v[166:169], v[216:219], v[42:45]
	v_mfma_f32_16x16x32_bf16 v[30:33], v[130:133], v[224:227], v[30:33]
	v_mfma_f32_16x16x32_bf16 v[26:29], v[166:169], v[224:227], v[26:29]
	v_mfma_f32_16x16x32_bf16 v[14:17], v[130:133], v[232:235], v[14:17]
	v_mfma_f32_16x16x32_bf16 v[10:13], v[166:169], v[232:235], v[10:13]
	v_mfma_f32_16x16x32_bf16 v[62:65], v[134:137], v[212:215], v[62:65]
	v_mfma_f32_16x16x32_bf16 v[58:61], v[170:173], v[212:215], v[58:61]
	v_mfma_f32_16x16x32_bf16 v[46:49], v[134:137], v[220:223], v[46:49]
	v_mfma_f32_16x16x32_bf16 v[42:45], v[170:173], v[220:223], v[42:45]
	v_mfma_f32_16x16x32_bf16 v[30:33], v[134:137], v[228:231], v[30:33]
	v_mfma_f32_16x16x32_bf16 v[26:29], v[170:173], v[228:231], v[26:29]
	v_mfma_f32_16x16x32_bf16 v[14:17], v[134:137], v[236:239], v[14:17]
	v_mfma_f32_16x16x32_bf16 v[10:13], v[170:173], v[236:239], v[10:13]
	s_setprio 0
	s_setprio 1
	v_mfma_f32_16x16x32_bf16 v[54:57], v[178:181], v[208:211], v[54:57]
	v_mfma_f32_16x16x32_bf16 v[50:53], v[186:189], v[208:211], v[50:53]
	v_mfma_f32_16x16x32_bf16 v[38:41], v[178:181], v[216:219], v[38:41]
	v_mfma_f32_16x16x32_bf16 v[34:37], v[186:189], v[216:219], v[34:37]
	v_mfma_f32_16x16x32_bf16 v[22:25], v[178:181], v[224:227], v[22:25]
	v_mfma_f32_16x16x32_bf16 v[18:21], v[186:189], v[224:227], v[18:21]
	v_mfma_f32_16x16x32_bf16 v[6:9], v[178:181], v[232:235], v[6:9]
	v_mfma_f32_16x16x32_bf16 v[2:5], v[186:189], v[232:235], v[2:5]
	v_mfma_f32_16x16x32_bf16 v[54:57], v[182:185], v[212:215], v[54:57]
	v_mfma_f32_16x16x32_bf16 v[50:53], v[190:193], v[212:215], v[50:53]
	v_mfma_f32_16x16x32_bf16 v[38:41], v[182:185], v[220:223], v[38:41]
	v_mfma_f32_16x16x32_bf16 v[34:37], v[190:193], v[220:223], v[34:37]
	v_mfma_f32_16x16x32_bf16 v[22:25], v[182:185], v[228:231], v[22:25]
	v_mfma_f32_16x16x32_bf16 v[18:21], v[190:193], v[228:231], v[18:21]
	v_mfma_f32_16x16x32_bf16 v[6:9], v[182:185], v[236:239], v[6:9]
	v_mfma_f32_16x16x32_bf16 v[2:5], v[190:193], v[236:239], v[2:5]
	s_setprio 0
	s_barrier
	s_add_i32 s46, 0, 0x18000
	s_add_i32 s47, 0, 0x1c000
	v_add_u32_e32 v170, s46, v1
	v_add_u32_e32 v177, s47, v1
	ds_read_b128 v[130:133], v170
	ds_read_b128 v[134:137], v170 offset:1024
	ds_read_b128 v[166:169], v170 offset:2048
	ds_read_b128 v[170:173], v170 offset:3072
	ds_read_b128 v[178:181], v177
	ds_read_b128 v[182:185], v177 offset:1024
	ds_read_b128 v[186:189], v177 offset:2048
	ds_read_b128 v[190:193], v177 offset:3072
	s_add_u32 s24, s24, 0x80000
	s_addc_u32 s25, s25, 0
	s_mov_b32 m0, s34
	v_lshl_add_u64 v[246:247], s[24:25], 0, v[138:139]
	ds_read_b128 v[208:211], v176 offset:32768
	ds_read_b128 v[212:215], v176 offset:33792
	ds_read_b128 v[216:219], v176 offset:34816
	ds_read_b128 v[220:223], v176 offset:35840
	ds_read_b128 v[224:227], v176 offset:36864
	ds_read_b128 v[228:231], v176 offset:37888
	ds_read_b128 v[232:235], v176 offset:38912
	ds_read_b128 v[236:239], v176 offset:39936
	global_load_lds_dwordx4 v[246:247], off
	v_lshl_add_u64 v[246:247], s[24:25], 0, v[142:143]
	s_mov_b32 m0, s35
	s_nop 0
	global_load_lds_dwordx4 v[246:247], off
	s_nop 0
	s_nop 0
	s_nop 0
	s_waitcnt vmcnt(8)
	s_waitcnt lgkmcnt(0)
	v_mfma_f32_16x16x32_bf16 v[126:129], v[130:133], v[208:211], v[126:129]
	v_mfma_f32_16x16x32_bf16 v[122:125], v[166:169], v[208:211], v[122:125]
	s_barrier
	s_setprio 1
	s_waitcnt lgkmcnt(0)
	v_mfma_f32_16x16x32_bf16 v[110:113], v[130:133], v[216:219], v[110:113]
	v_mfma_f32_16x16x32_bf16 v[106:109], v[166:169], v[216:219], v[106:109]
	v_mfma_f32_16x16x32_bf16 v[94:97], v[130:133], v[224:227], v[94:97]
	v_mfma_f32_16x16x32_bf16 v[90:93], v[166:169], v[224:227], v[90:93]
	v_mfma_f32_16x16x32_bf16 v[78:81], v[130:133], v[232:235], v[78:81]
	v_mfma_f32_16x16x32_bf16 v[74:77], v[166:169], v[232:235], v[74:77]
	v_mfma_f32_16x16x32_bf16 v[126:129], v[134:137], v[212:215], v[126:129]
	v_mfma_f32_16x16x32_bf16 v[122:125], v[170:173], v[212:215], v[122:125]
	v_mfma_f32_16x16x32_bf16 v[110:113], v[134:137], v[220:223], v[110:113]
	v_mfma_f32_16x16x32_bf16 v[106:109], v[170:173], v[220:223], v[106:109]
	v_mfma_f32_16x16x32_bf16 v[94:97], v[134:137], v[228:231], v[94:97]
	v_mfma_f32_16x16x32_bf16 v[90:93], v[170:173], v[228:231], v[90:93]
	v_mfma_f32_16x16x32_bf16 v[78:81], v[134:137], v[236:239], v[78:81]
	v_mfma_f32_16x16x32_bf16 v[74:77], v[170:173], v[236:239], v[74:77]
	s_setprio 0
	s_setprio 1
	v_mfma_f32_16x16x32_bf16 v[118:121], v[178:181], v[208:211], v[118:121]
	v_mfma_f32_16x16x32_bf16 v[114:117], v[186:189], v[208:211], v[114:117]
	v_mfma_f32_16x16x32_bf16 v[102:105], v[178:181], v[216:219], v[102:105]
	v_mfma_f32_16x16x32_bf16 v[98:101], v[186:189], v[216:219], v[98:101]
	v_mfma_f32_16x16x32_bf16 v[86:89], v[178:181], v[224:227], v[86:89]
	v_mfma_f32_16x16x32_bf16 v[82:85], v[186:189], v[224:227], v[82:85]
	v_mfma_f32_16x16x32_bf16 v[70:73], v[178:181], v[232:235], v[70:73]
	v_mfma_f32_16x16x32_bf16 v[66:69], v[186:189], v[232:235], v[66:69]
	v_mfma_f32_16x16x32_bf16 v[118:121], v[182:185], v[212:215], v[118:121]
	v_mfma_f32_16x16x32_bf16 v[114:117], v[190:193], v[212:215], v[114:117]
	v_mfma_f32_16x16x32_bf16 v[102:105], v[182:185], v[220:223], v[102:105]
	v_mfma_f32_16x16x32_bf16 v[98:101], v[190:193], v[220:223], v[98:101]
	v_mfma_f32_16x16x32_bf16 v[86:89], v[182:185], v[228:231], v[86:89]
	v_mfma_f32_16x16x32_bf16 v[82:85], v[190:193], v[228:231], v[82:85]
	v_mfma_f32_16x16x32_bf16 v[70:73], v[182:185], v[236:239], v[70:73]
	v_mfma_f32_16x16x32_bf16 v[66:69], v[190:193], v[236:239], v[66:69]
	s_setprio 0
	s_barrier
; #define PG8_STAGE(bufoff, gbase, voff) do { _Pragma("unroll") for (int _i = 0; _i < 2; ++_i) \
;         __builtin_amdgcn_global_load_lds((const unsigned*)((const char*)(gbase) + (voff)[_i]), (LAS unsigned*)(lds + (bufoff) + ldsw + _i * 8192), 16, 0, 0); } while (0)
; #define PG8_LDA(dst, b, h) do { _Pragma("unroll") for (int m = 0; m < 4; ++m) _Pragma("unroll") for (int k = 0; k < 2; ++k) dst[m][k] = *(const LAS bf16x8*)(lds + PG8_SA(b, h) + aoff + m * 2048 + k * 1024); } while (0)
; #define PG8_MMA(ai, bj, At, Bt) do { __builtin_amdgcn_s_setprio(1); _Pragma("unroll") for (int m = 0; m < 4; ++m) _Pragma("unroll") for (int n = 0; n < 2; ++n) _Pragma("unroll") for (int k = 0; k < 2; ++k) \
;         acc[ai][bj][m][n] = __builtin_amdgcn_mfma_f32_16x16x32_bf16(Bt[n][k], At[m][k], acc[ai][bj][m][n], 0, 0, 0); __builtin_amdgcn_s_setprio(0); } while (0)
; #define PG8_WAIT_V(n) asm volatile("s_waitcnt vmcnt(" #n ")" ::: "memory")
; #define PG8_WAIT_L(n) asm volatile("s_waitcnt lgkmcnt(" #n ")" ::: "memory")
; #define PG8_BAR __builtin_amdgcn_s_barrier()
; #define PG8_SCHED __builtin_amdgcn_sched_barrier(0)
; template <class Epi, class Sched>
; __device__ __forceinline__ void gemm_phase(LAS unsigned char* lds, const Gemm g, const Sched& S, const Epi& E) {
;     ...
;             PG8_LDA(At, 1, 1); PG8_STAGE(PG8_SB(1, 0), b3, voffB); PG8_STAGE(PG8_SB(1, 1), b3 + hstepB, voffB); PG8_STAGE(PG8_SA(1, 0), a3, voffA);
;             PG8_WAIT_V(8); PG8_WAIT_L(0); PG8_BAR; PG8_MMA(1, 0, At, B0); PG8_MMA(1, 1, At, B1); PG8_BAR; PG8_SCHED;
;         }
;         if (wr == 0) PG8_BAR;
	s_add_i32 s24, s46, s30
	v_lshl_add_u64 v[174:175], v[174:175], 0, s[56:57]
	s_mov_b32 m0, s24
	ds_read_b128 v[208:211], v176 offset:49152
	ds_read_b128 v[212:215], v176 offset:50176
	ds_read_b128 v[216:219], v176 offset:51200
	ds_read_b128 v[220:223], v176 offset:52224
	ds_read_b128 v[224:227], v176 offset:53248
	ds_read_b128 v[228:231], v176 offset:54272
	ds_read_b128 v[232:235], v176 offset:55296
	ds_read_b128 v[236:239], v176 offset:56320
	global_load_lds_dwordx4 v[174:175], off
	s_add_i32 m0, s24, 0x2000
	s_add_u32 s22, s22, 0x80080
	v_lshl_add_u64 v[174:175], v[240:241], 0, s[56:57]
	s_addc_u32 s23, s23, 0
	s_add_i32 s24, s47, s30
	global_load_lds_dwordx4 v[174:175], off
	v_lshl_add_u64 v[174:175], s[22:23], 0, v[140:141]
	s_mov_b32 m0, s24
	s_nop 0
	global_load_lds_dwordx4 v[174:175], off
	v_lshl_add_u64 v[174:175], s[22:23], 0, v[144:145]
	s_add_i32 m0, s24, 0x2000
	s_nop 0
	global_load_lds_dwordx4 v[174:175], off
	v_lshl_add_u64 v[174:175], v[242:243], 0, s[56:57]
	s_mov_b32 m0, s39
	s_nop 0
	global_load_lds_dwordx4 v[174:175], off
	v_lshl_add_u64 v[174:175], v[244:245], 0, s[56:57]
	s_mov_b32 m0, s40
	s_nop 0
	global_load_lds_dwordx4 v[174:175], off
	s_nop 0
	s_nop 0
	s_waitcnt vmcnt(8)
	s_waitcnt lgkmcnt(0)
	v_mfma_f32_16x16x32_bf16 v[62:65], v[130:133], v[208:211], v[62:65]
	v_mfma_f32_16x16x32_bf16 v[58:61], v[166:169], v[208:211], v[58:61]
	s_barrier
	s_setprio 1
	s_waitcnt lgkmcnt(0)
	v_mfma_f32_16x16x32_bf16 v[46:49], v[130:133], v[216:219], v[46:49]
	v_mfma_f32_16x16x32_bf16 v[42:45], v[166:169], v[216:219], v[42:45]
	v_mfma_f32_16x16x32_bf16 v[30:33], v[130:133], v[224:227], v[30:33]
	v_mfma_f32_16x16x32_bf16 v[26:29], v[166:169], v[224:227], v[26:29]
	v_mfma_f32_16x16x32_bf16 v[14:17], v[130:133], v[232:235], v[14:17]
	v_mfma_f32_16x16x32_bf16 v[10:13], v[166:169], v[232:235], v[10:13]
	v_mfma_f32_16x16x32_bf16 v[62:65], v[134:137], v[212:215], v[62:65]
	v_mfma_f32_16x16x32_bf16 v[58:61], v[170:173], v[212:215], v[58:61]
	v_mfma_f32_16x16x32_bf16 v[46:49], v[134:137], v[220:223], v[46:49]
	v_mfma_f32_16x16x32_bf16 v[42:45], v[170:173], v[220:223], v[42:45]
	v_mfma_f32_16x16x32_bf16 v[30:33], v[134:137], v[228:231], v[30:33]
	v_mfma_f32_16x16x32_bf16 v[26:29], v[170:173], v[228:231], v[26:29]
	v_mfma_f32_16x16x32_bf16 v[14:17], v[134:137], v[236:239], v[14:17]
	v_mfma_f32_16x16x32_bf16 v[10:13], v[170:173], v[236:239], v[10:13]
	s_setprio 0
	s_setprio 1
	v_mfma_f32_16x16x32_bf16 v[54:57], v[178:181], v[208:211], v[54:57]
	v_mfma_f32_16x16x32_bf16 v[50:53], v[186:189], v[208:211], v[50:53]
	v_mfma_f32_16x16x32_bf16 v[38:41], v[178:181], v[216:219], v[38:41]
	v_mfma_f32_16x16x32_bf16 v[34:37], v[186:189], v[216:219], v[34:37]
	v_mfma_f32_16x16x32_bf16 v[22:25], v[178:181], v[224:227], v[22:25]
	v_mfma_f32_16x16x32_bf16 v[18:21], v[186:189], v[224:227], v[18:21]
	v_mfma_f32_16x16x32_bf16 v[6:9], v[178:181], v[232:235], v[6:9]
	v_mfma_f32_16x16x32_bf16 v[2:5], v[186:189], v[232:235], v[2:5]
	v_mfma_f32_16x16x32_bf16 v[54:57], v[182:185], v[212:215], v[54:57]
	v_mfma_f32_16x16x32_bf16 v[50:53], v[190:193], v[212:215], v[50:53]
	v_mfma_f32_16x16x32_bf16 v[38:41], v[182:185], v[220:223], v[38:41]
	v_mfma_f32_16x16x32_bf16 v[34:37], v[190:193], v[220:223], v[34:37]
	v_mfma_f32_16x16x32_bf16 v[22:25], v[182:185], v[228:231], v[22:25]
	v_mfma_f32_16x16x32_bf16 v[18:21], v[190:193], v[228:231], v[18:21]
	v_mfma_f32_16x16x32_bf16 v[6:9], v[182:185], v[236:239], v[6:9]
	v_mfma_f32_16x16x32_bf16 v[2:5], v[190:193], v[236:239], v[2:5]
	s_setprio 0
	s_barrier
	s_add_i32 s45, s45, 2
	s_add_u32 s20, s20, 0x100
	s_addc_u32 s21, s21, 0
	s_add_u32 s43, s43, 0x100
	s_addc_u32 s44, s44, 0
	s_cmp_gt_u32 s45, 29
	s_cbranch_scc0 .LBB0_4095
	s_and_b64 vcc, exec, s[4:5]
	s_cbranch_vccz .LBB0_4098
	s_barrier

; #define PG8_STAGE(bufoff, gbase, voff) do { _Pragma("unroll") for (int _i = 0; _i < 2; ++_i) \
;         __builtin_amdgcn_global_load_lds((const unsigned*)((const char*)(gbase) + (voff)[_i]), (LAS unsigned*)(lds + (bufoff) + ldsw + _i * 8192), 16, 0, 0); } while (0)
; #define PG8_LDA(dst, b, h) do { _Pragma("unroll") for (int m = 0; m < 4; ++m) _Pragma("unroll") for (int k = 0; k < 2; ++k) dst[m][k] = *(const LAS bf16x8*)(lds + PG8_SA(b, h) + aoff + m * 2048 + k * 1024); } while (0)
; #define PG8_LDB(dst, b, h) do { _Pragma("unroll") for (int n = 0; n < 2; ++n) _Pragma("unroll") for (int k = 0; k < 2; ++k) dst[n][k] = *(const LAS bf16x8*)(lds + PG8_SB(b, h) + boff + n * 2048 + k * 1024); } while (0)
; #define PG8_MMA(ai, bj, At, Bt) do { __builtin_amdgcn_s_setprio(1); _Pragma("unroll") for (int m = 0; m < 4; ++m) _Pragma("unroll") for (int n = 0; n < 2; ++n) _Pragma("unroll") for (int k = 0; k < 2; ++k) \
;         acc[ai][bj][m][n] = __builtin_amdgcn_mfma_f32_16x16x32_bf16(Bt[n][k], At[m][k], acc[ai][bj][m][n], 0, 0, 0); __builtin_amdgcn_s_setprio(0); } while (0)
; #define PG8_WAIT_V(n) asm volatile("s_waitcnt vmcnt(" #n ")" ::: "memory")
; template <class Epi, class Sched>
; __device__ __forceinline__ void gemm_phase(LAS unsigned char* lds, const Gemm g, const Sched& S, const Epi& E) {
;     ...
;         const bool has_next = S.next(ui + 1, nxt);
;         const char* nA = has_next ? (const char*)g.A + (size_t)nxt.pm * tstepA : cA; const char* nB = has_next ? (const char*)g.Bt + (size_t)nxt.pn * tstepB : cB;
;         for (int t = 0; t < nt; t += 2) {
;             const bool last = (t == nt - 2);
;             const char* a1 = cA + (size_t)(t + 1) * kstep;
;             const char* a2 = last ? nA : cA + (size_t)(t + 2) * kstep; const char* b2 = last ? nB : cB + (size_t)(t + 2) * kstep;
;             const char* a3 = a2 + kstep; const char* b3 = b2 + kstep;
;             PG8_LDB(B0, 0, 0); PG8_LDB(B1, 0, 1); PG8_SCHED; PG8_LDA(At, 0, 0); PG8_STAGE(PG8_SA(1, 1), a1 + hstepA, voffA);
;             PG8_WAIT_V(8); PG8_WAIT_L(0); PG8_BAR; PG8_MMA(0, 0, At, B0); PG8_MMA(0, 1, At, B1); PG8_BAR; PG8_SCHED;
;             PG8_LDA(At, 0, 1); PG8_STAGE(PG8_SB(0, 0), b2, voffB); PG8_STAGE(PG8_SB(0, 1), b2 + hstepB, voffB); PG8_STAGE(PG8_SA(0, 0), a2, voffA);
;             PG8_WAIT_V(8); PG8_WAIT_L(0); PG8_BAR; PG8_MMA(1, 0, At, B0); PG8_MMA(1, 1, At, B1); PG8_BAR; PG8_SCHED;
.LBB0_4132:
	s_add_u32 s23, s16, s22
	s_addc_u32 s28, s17, 0
	s_add_u32 s26, s23, 0x100
	s_addc_u32 s27, s28, 0
	s_and_b64 s[24:25], s[20:21], exec
	s_cselect_b32 s25, s9, s27
	s_cselect_b32 s24, s53, s26
	s_add_u32 s22, s14, s22
	s_addc_u32 s26, s15, 0
	s_add_u32 s22, s22, 0x100
	s_addc_u32 s26, s26, 0
	s_add_i32 s63, 0, 0x10000
	s_and_b64 s[20:21], s[20:21], exec
	s_cselect_b32 s27, s7, s26
	s_cselect_b32 s26, s54, s22
	s_add_i32 s21, 0, 0x14000
	s_add_u32 s30, s23, 0x10080
	s_addc_u32 s31, s28, 0
	s_add_i32 s62, s63, s39
	s_add_i32 m0, s40, 0xc000
	s_add_i32 s65, s40, 0xe000
	s_add_i32 s59, s62, 0x2000
	v_add_u32_e32 v138, s63, v1
	s_add_u32 s28, s26, 0x10000
	ds_read_b128 v[142:145], v138
	ds_read_b128 v[162:165], v138 offset:1024
	ds_read_b128 v[166:169], v138 offset:2048
	ds_read_b128 v[170:173], v138 offset:3072
	v_add_u32_e32 v138, s21, v1
	s_addc_u32 s29, s27, 0
	s_add_i32 s61, s21, s39
	ds_read_b128 v[174:177], v138
	ds_read_b128 v[178:181], v138 offset:1024
	ds_read_b128 v[182:185], v138 offset:2048
	ds_read_b128 v[186:189], v138 offset:3072
	s_add_i32 s60, s61, 0x2000
	s_add_i32 s58, 0, 0x18000
	s_add_i32 s57, 0, 0x1c000
	s_add_u32 s22, s24, 0x10000
	s_addc_u32 s23, s25, 0
	s_add_i32 s56, s58, s39
	s_add_i32 s55, s56, 0x2000
	s_add_u32 s20, s26, 0x10080
	s_addc_u32 s21, s27, 0
	s_add_i32 s64, s57, s39
	s_add_i32 s63, s64, 0x2000
	v_lshl_add_u64 v[138:139], s[30:31], 0, v[136:137]
	ds_read_b128 v[190:193], v140
	ds_read_b128 v[208:211], v140 offset:1024
	ds_read_b128 v[212:215], v140 offset:2048
	ds_read_b128 v[216:219], v140 offset:3072
	ds_read_b128 v[220:223], v140 offset:4096
	ds_read_b128 v[224:227], v140 offset:5120
	ds_read_b128 v[228:231], v140 offset:6144
	ds_read_b128 v[232:235], v140 offset:7168
	global_load_lds_dwordx4 v[138:139], off
	v_lshl_add_u64 v[138:139], s[30:31], 0, v[132:133]
	s_mov_b32 m0, s65
	s_nop 0
	global_load_lds_dwordx4 v[138:139], off
	s_nop 0
	s_nop 0
	s_waitcnt vmcnt(8)
	s_waitcnt lgkmcnt(0)
	v_mfma_f32_16x16x32_bf16 v[126:129], v[142:145], v[190:193], v[126:129]
	v_mfma_f32_16x16x32_bf16 v[122:125], v[166:169], v[190:193], v[122:125]
	s_barrier
	s_setprio 1
	s_waitcnt lgkmcnt(0)
	v_mfma_f32_16x16x32_bf16 v[114:117], v[142:145], v[212:215], v[114:117]
	v_mfma_f32_16x16x32_bf16 v[106:109], v[166:169], v[212:215], v[106:109]
	v_mfma_f32_16x16x32_bf16 v[98:101], v[142:145], v[220:223], v[98:101]
	v_mfma_f32_16x16x32_bf16 v[90:93], v[166:169], v[220:223], v[90:93]
	v_mfma_f32_16x16x32_bf16 v[78:81], v[142:145], v[228:231], v[78:81]
	v_mfma_f32_16x16x32_bf16 v[74:77], v[166:169], v[228:231], v[74:77]
	v_mfma_f32_16x16x32_bf16 v[126:129], v[162:165], v[208:211], v[126:129]
	v_mfma_f32_16x16x32_bf16 v[122:125], v[170:173], v[208:211], v[122:125]
	v_mfma_f32_16x16x32_bf16 v[114:117], v[162:165], v[216:219], v[114:117]
	v_mfma_f32_16x16x32_bf16 v[106:109], v[170:173], v[216:219], v[106:109]
	v_mfma_f32_16x16x32_bf16 v[98:101], v[162:165], v[224:227], v[98:101]
	v_mfma_f32_16x16x32_bf16 v[90:93], v[170:173], v[224:227], v[90:93]
	v_mfma_f32_16x16x32_bf16 v[78:81], v[162:165], v[232:235], v[78:81]
	v_mfma_f32_16x16x32_bf16 v[74:77], v[170:173], v[232:235], v[74:77]
	s_setprio 0
	s_setprio 1
	v_mfma_f32_16x16x32_bf16 v[118:121], v[174:177], v[190:193], v[118:121]
	v_mfma_f32_16x16x32_bf16 v[110:113], v[182:185], v[190:193], v[110:113]
	v_mfma_f32_16x16x32_bf16 v[102:105], v[174:177], v[212:215], v[102:105]
	v_mfma_f32_16x16x32_bf16 v[94:97], v[182:185], v[212:215], v[94:97]
	v_mfma_f32_16x16x32_bf16 v[86:89], v[174:177], v[220:223], v[86:89]
	v_mfma_f32_16x16x32_bf16 v[82:85], v[182:185], v[220:223], v[82:85]
	v_mfma_f32_16x16x32_bf16 v[70:73], v[174:177], v[228:231], v[70:73]
	v_mfma_f32_16x16x32_bf16 v[66:69], v[182:185], v[228:231], v[66:69]
	v_mfma_f32_16x16x32_bf16 v[118:121], v[178:181], v[208:211], v[118:121]
	v_mfma_f32_16x16x32_bf16 v[110:113], v[186:189], v[208:211], v[110:113]
	v_mfma_f32_16x16x32_bf16 v[102:105], v[178:181], v[216:219], v[102:105]
	v_mfma_f32_16x16x32_bf16 v[94:97], v[186:189], v[216:219], v[94:97]
	v_mfma_f32_16x16x32_bf16 v[86:89], v[178:181], v[224:227], v[86:89]
	v_mfma_f32_16x16x32_bf16 v[82:85], v[186:189], v[224:227], v[82:85]
	v_mfma_f32_16x16x32_bf16 v[70:73], v[178:181], v[232:235], v[70:73]
	v_mfma_f32_16x16x32_bf16 v[66:69], v[186:189], v[232:235], v[66:69]
	s_setprio 0
	s_barrier
	s_mov_b32 m0, s62
	v_lshl_add_u64 v[138:139], s[26:27], 0, v[134:135]
	ds_read_b128 v[190:193], v140 offset:16384
	ds_read_b128 v[208:211], v140 offset:17408
	ds_read_b128 v[212:215], v140 offset:18432
	ds_read_b128 v[216:219], v140 offset:19456
	ds_read_b128 v[220:223], v140 offset:20480
	ds_read_b128 v[224:227], v140 offset:21504
	ds_read_b128 v[228:231], v140 offset:22528
	ds_read_b128 v[232:235], v140 offset:23552
	global_load_lds_dwordx4 v[138:139], off
	v_lshl_add_u64 v[236:237], s[26:27], 0, v[130:131]
	s_mov_b32 m0, s59
	v_lshl_add_u64 v[238:239], s[28:29], 0, v[134:135]
	global_load_lds_dwordx4 v[236:237], off
	s_mov_b32 m0, s61
	v_lshl_add_u64 v[240:241], s[24:25], 0, v[132:133]
	global_load_lds_dwordx4 v[238:239], off
	v_lshl_add_u64 v[238:239], s[28:29], 0, v[130:131]
	s_mov_b32 m0, s60
	s_nop 0
	global_load_lds_dwordx4 v[238:239], off
	v_lshl_add_u64 v[238:239], s[24:25], 0, v[136:137]
	s_mov_b32 m0, s40
	s_nop 0
	global_load_lds_dwordx4 v[238:239], off
	s_mov_b32 m0, s41
	s_nop 0
	global_load_lds_dwordx4 v[240:241], off
	s_nop 0
	s_nop 0
	s_waitcnt vmcnt(8)
	s_waitcnt lgkmcnt(0)
	v_mfma_f32_16x16x32_bf16 v[62:65], v[142:145], v[190:193], v[62:65]
	v_mfma_f32_16x16x32_bf16 v[58:61], v[166:169], v[190:193], v[58:61]
	s_barrier
; #define PG8_STAGE(bufoff, gbase, voff) do { _Pragma("unroll") for (int _i = 0; _i < 2; ++_i) \
;         __builtin_amdgcn_global_load_lds((const unsigned*)((const char*)(gbase) + (voff)[_i]), (LAS unsigned*)(lds + (bufoff) + ldsw + _i * 8192), 16, 0, 0); } while (0)
; #define PG8_LDA(dst, b, h) do { _Pragma("unroll") for (int m = 0; m < 4; ++m) _Pragma("unroll") for (int k = 0; k < 2; ++k) dst[m][k] = *(const LAS bf16x8*)(lds + PG8_SA(b, h) + aoff + m * 2048 + k * 1024); } while (0)
; #define PG8_LDB(dst, b, h) do { _Pragma("unroll") for (int n = 0; n < 2; ++n) _Pragma("unroll") for (int k = 0; k < 2; ++k) dst[n][k] = *(const LAS bf16x8*)(lds + PG8_SB(b, h) + boff + n * 2048 + k * 1024); } while (0)
; #define PG8_MMA(ai, bj, At, Bt) do { __builtin_amdgcn_s_setprio(1); _Pragma("unroll") for (int m = 0; m < 4; ++m) _Pragma("unroll") for (int n = 0; n < 2; ++n) _Pragma("unroll") for (int k = 0; k < 2; ++k) \
;         acc[ai][bj][m][n] = __builtin_amdgcn_mfma_f32_16x16x32_bf16(Bt[n][k], At[m][k], acc[ai][bj][m][n], 0, 0, 0); __builtin_amdgcn_s_setprio(0); } while (0)
; #define PG8_WAIT_V(n) asm volatile("s_waitcnt vmcnt(" #n ")" ::: "memory")
; #define PG8_WAIT_L(n) asm volatile("s_waitcnt lgkmcnt(" #n ")" ::: "memory")
; #define PG8_BAR __builtin_amdgcn_s_barrier()
; #define PG8_SCHED __builtin_amdgcn_sched_barrier(0)
; template <class Epi, class Sched>
; __device__ __forceinline__ void gemm_phase(LAS unsigned char* lds, const Gemm g, const Sched& S, const Epi& E) {
;     ...
;             PG8_WAIT_V(8); PG8_WAIT_L(0); PG8_BAR; PG8_MMA(1, 0, At, B0); PG8_MMA(1, 1, At, B1); PG8_BAR; PG8_SCHED;
;             PG8_LDB(B0, 1, 0); PG8_LDB(B1, 1, 1); PG8_SCHED; PG8_LDA(At, 1, 0); PG8_STAGE(PG8_SA(0, 1), a2 + hstepA, voffA);
;             PG8_WAIT_V(8); PG8_WAIT_L(0); PG8_BAR; PG8_MMA(0, 0, At, B0); PG8_MMA(0, 1, At, B1); PG8_BAR; PG8_SCHED;
	s_setprio 1
	s_waitcnt lgkmcnt(0)
	v_mfma_f32_16x16x32_bf16 v[50:53], v[142:145], v[212:215], v[50:53]
	v_mfma_f32_16x16x32_bf16 v[42:45], v[166:169], v[212:215], v[42:45]
	v_mfma_f32_16x16x32_bf16 v[34:37], v[142:145], v[220:223], v[34:37]
	v_mfma_f32_16x16x32_bf16 v[26:29], v[166:169], v[220:223], v[26:29]
	v_mfma_f32_16x16x32_bf16 v[18:21], v[142:145], v[228:231], v[18:21]
	v_mfma_f32_16x16x32_bf16 v[10:13], v[166:169], v[228:231], v[10:13]
	v_mfma_f32_16x16x32_bf16 v[62:65], v[162:165], v[208:211], v[62:65]
	v_mfma_f32_16x16x32_bf16 v[58:61], v[170:173], v[208:211], v[58:61]
	v_mfma_f32_16x16x32_bf16 v[50:53], v[162:165], v[216:219], v[50:53]
	v_mfma_f32_16x16x32_bf16 v[42:45], v[170:173], v[216:219], v[42:45]
	v_mfma_f32_16x16x32_bf16 v[34:37], v[162:165], v[224:227], v[34:37]
	v_mfma_f32_16x16x32_bf16 v[26:29], v[170:173], v[224:227], v[26:29]
	v_mfma_f32_16x16x32_bf16 v[18:21], v[162:165], v[232:235], v[18:21]
	v_mfma_f32_16x16x32_bf16 v[10:13], v[170:173], v[232:235], v[10:13]
	s_setprio 0
	s_setprio 1
	v_mfma_f32_16x16x32_bf16 v[54:57], v[174:177], v[190:193], v[54:57]
	v_mfma_f32_16x16x32_bf16 v[46:49], v[182:185], v[190:193], v[46:49]
	v_mfma_f32_16x16x32_bf16 v[38:41], v[174:177], v[212:215], v[38:41]
	v_mfma_f32_16x16x32_bf16 v[30:33], v[182:185], v[212:215], v[30:33]
	v_mfma_f32_16x16x32_bf16 v[22:25], v[174:177], v[220:223], v[22:25]
	v_mfma_f32_16x16x32_bf16 v[14:17], v[182:185], v[220:223], v[14:17]
	v_mfma_f32_16x16x32_bf16 v[6:9], v[174:177], v[228:231], v[6:9]
	v_mfma_f32_16x16x32_bf16 v[2:5], v[182:185], v[228:231], v[2:5]
	v_mfma_f32_16x16x32_bf16 v[54:57], v[178:181], v[208:211], v[54:57]
	v_mfma_f32_16x16x32_bf16 v[46:49], v[186:189], v[208:211], v[46:49]
	v_mfma_f32_16x16x32_bf16 v[38:41], v[178:181], v[216:219], v[38:41]
	v_mfma_f32_16x16x32_bf16 v[30:33], v[186:189], v[216:219], v[30:33]
	v_mfma_f32_16x16x32_bf16 v[22:25], v[178:181], v[224:227], v[22:25]
	v_mfma_f32_16x16x32_bf16 v[14:17], v[186:189], v[224:227], v[14:17]
	v_mfma_f32_16x16x32_bf16 v[6:9], v[178:181], v[232:235], v[6:9]
	v_mfma_f32_16x16x32_bf16 v[2:5], v[186:189], v[232:235], v[2:5]
	s_setprio 0
	s_barrier
	v_add_u32_e32 v141, s58, v1
	ds_read_b128 v[142:145], v141
	ds_read_b128 v[162:165], v141 offset:1024
	ds_read_b128 v[166:169], v141 offset:2048
	ds_read_b128 v[170:173], v141 offset:3072
	v_add_u32_e32 v141, s57, v1
	ds_read_b128 v[174:177], v141
	ds_read_b128 v[178:181], v141 offset:1024
	ds_read_b128 v[182:185], v141 offset:2048
	ds_read_b128 v[186:189], v141 offset:3072
	s_mov_b32 m0, s42
	v_lshl_add_u64 v[242:243], s[22:23], 0, v[136:137]
	ds_read_b128 v[190:193], v140 offset:32768
	ds_read_b128 v[208:211], v140 offset:33792
	ds_read_b128 v[212:215], v140 offset:34816
	ds_read_b128 v[216:219], v140 offset:35840
	ds_read_b128 v[220:223], v140 offset:36864
	ds_read_b128 v[224:227], v140 offset:37888
	ds_read_b128 v[228:231], v140 offset:38912
	ds_read_b128 v[232:235], v140 offset:39936
	global_load_lds_dwordx4 v[242:243], off
	v_lshl_add_u64 v[242:243], s[22:23], 0, v[132:133]
	s_mov_b32 m0, s43
	s_nop 0
	global_load_lds_dwordx4 v[242:243], off
	s_nop 0
	s_nop 0
	s_waitcnt vmcnt(8)
	s_waitcnt lgkmcnt(0)
	v_mfma_f32_16x16x32_bf16 v[126:129], v[142:145], v[190:193], v[126:129]
	v_mfma_f32_16x16x32_bf16 v[122:125], v[166:169], v[190:193], v[122:125]
	s_barrier
	s_setprio 1
	s_waitcnt lgkmcnt(0)
	v_mfma_f32_16x16x32_bf16 v[114:117], v[142:145], v[212:215], v[114:117]
	v_mfma_f32_16x16x32_bf16 v[106:109], v[166:169], v[212:215], v[106:109]
	v_mfma_f32_16x16x32_bf16 v[98:101], v[142:145], v[220:223], v[98:101]
	v_mfma_f32_16x16x32_bf16 v[90:93], v[166:169], v[220:223], v[90:93]
	v_mfma_f32_16x16x32_bf16 v[78:81], v[142:145], v[228:231], v[78:81]
	v_mfma_f32_16x16x32_bf16 v[74:77], v[166:169], v[228:231], v[74:77]
	v_mfma_f32_16x16x32_bf16 v[126:129], v[162:165], v[208:211], v[126:129]
	v_mfma_f32_16x16x32_bf16 v[122:125], v[170:173], v[208:211], v[122:125]
	v_mfma_f32_16x16x32_bf16 v[114:117], v[162:165], v[216:219], v[114:117]
	v_mfma_f32_16x16x32_bf16 v[106:109], v[170:173], v[216:219], v[106:109]
	v_mfma_f32_16x16x32_bf16 v[98:101], v[162:165], v[224:227], v[98:101]
	v_mfma_f32_16x16x32_bf16 v[90:93], v[170:173], v[224:227], v[90:93]
	v_mfma_f32_16x16x32_bf16 v[78:81], v[162:165], v[232:235], v[78:81]
	v_mfma_f32_16x16x32_bf16 v[74:77], v[170:173], v[232:235], v[74:77]
	s_setprio 0
	s_setprio 1
	v_mfma_f32_16x16x32_bf16 v[118:121], v[174:177], v[190:193], v[118:121]
	v_mfma_f32_16x16x32_bf16 v[110:113], v[182:185], v[190:193], v[110:113]
	v_mfma_f32_16x16x32_bf16 v[102:105], v[174:177], v[212:215], v[102:105]
	v_mfma_f32_16x16x32_bf16 v[94:97], v[182:185], v[212:215], v[94:97]
	v_mfma_f32_16x16x32_bf16 v[86:89], v[174:177], v[220:223], v[86:89]
	v_mfma_f32_16x16x32_bf16 v[82:85], v[182:185], v[220:223], v[82:85]
	v_mfma_f32_16x16x32_bf16 v[70:73], v[174:177], v[228:231], v[70:73]
	v_mfma_f32_16x16x32_bf16 v[66:69], v[182:185], v[228:231], v[66:69]
	v_mfma_f32_16x16x32_bf16 v[118:121], v[178:181], v[208:211], v[118:121]
	v_mfma_f32_16x16x32_bf16 v[110:113], v[186:189], v[208:211], v[110:113]
	v_mfma_f32_16x16x32_bf16 v[102:105], v[178:181], v[216:219], v[102:105]
	v_mfma_f32_16x16x32_bf16 v[94:97], v[186:189], v[216:219], v[94:97]
	v_mfma_f32_16x16x32_bf16 v[86:89], v[178:181], v[224:227], v[86:89]
	v_mfma_f32_16x16x32_bf16 v[82:85], v[186:189], v[224:227], v[82:85]
	v_mfma_f32_16x16x32_bf16 v[70:73], v[178:181], v[232:235], v[70:73]
	v_mfma_f32_16x16x32_bf16 v[66:69], v[186:189], v[232:235], v[66:69]
	s_setprio 0
	s_barrier
; #define PG8_STAGE(bufoff, gbase, voff) do { _Pragma("unroll") for (int _i = 0; _i < 2; ++_i) \
;         __builtin_amdgcn_global_load_lds((const unsigned*)((const char*)(gbase) + (voff)[_i]), (LAS unsigned*)(lds + (bufoff) + ldsw + _i * 8192), 16, 0, 0); } while (0)
; #define PG8_LDA(dst, b, h) do { _Pragma("unroll") for (int m = 0; m < 4; ++m) _Pragma("unroll") for (int k = 0; k < 2; ++k) dst[m][k] = *(const LAS bf16x8*)(lds + PG8_SA(b, h) + aoff + m * 2048 + k * 1024); } while (0)
; #define PG8_MMA(ai, bj, At, Bt) do { __builtin_amdgcn_s_setprio(1); _Pragma("unroll") for (int m = 0; m < 4; ++m) _Pragma("unroll") for (int n = 0; n < 2; ++n) _Pragma("unroll") for (int k = 0; k < 2; ++k) \
;         acc[ai][bj][m][n] = __builtin_amdgcn_mfma_f32_16x16x32_bf16(Bt[n][k], At[m][k], acc[ai][bj][m][n], 0, 0, 0); __builtin_amdgcn_s_setprio(0); } while (0)
; #define PG8_WAIT_V(n) asm volatile("s_waitcnt vmcnt(" #n ")" ::: "memory")
; #define PG8_WAIT_L(n) asm volatile("s_waitcnt lgkmcnt(" #n ")" ::: "memory")
; #define PG8_BAR __builtin_amdgcn_s_barrier()
; #define PG8_SCHED __builtin_amdgcn_sched_barrier(0)
; template <class Epi, class Sched>
; __device__ __forceinline__ void gemm_phase(LAS unsigned char* lds, const Gemm g, const Sched& S, const Epi& E) {
;     ...
;             PG8_LDA(At, 1, 1); PG8_STAGE(PG8_SB(1, 0), b3, voffB); PG8_STAGE(PG8_SB(1, 1), b3 + hstepB, voffB); PG8_STAGE(PG8_SA(1, 0), a3, voffA);
;             PG8_WAIT_V(8); PG8_WAIT_L(0); PG8_BAR; PG8_MMA(1, 0, At, B0); PG8_MMA(1, 1, At, B1); PG8_BAR; PG8_SCHED;
;         }
;         if (wr == 0) PG8_BAR;
	s_mov_b32 m0, s56
	v_lshl_add_u64 v[138:139], v[138:139], 0, s[68:69]
	ds_read_b128 v[190:193], v140 offset:49152
	ds_read_b128 v[208:211], v140 offset:50176
	ds_read_b128 v[212:215], v140 offset:51200
	ds_read_b128 v[216:219], v140 offset:52224
	ds_read_b128 v[220:223], v140 offset:53248
	ds_read_b128 v[224:227], v140 offset:54272
	ds_read_b128 v[228:231], v140 offset:55296
	ds_read_b128 v[232:235], v140 offset:56320
	global_load_lds_dwordx4 v[138:139], off
	v_lshl_add_u64 v[138:139], v[236:237], 0, s[68:69]
	s_mov_b32 m0, s55
	s_nop 0
	global_load_lds_dwordx4 v[138:139], off
	v_lshl_add_u64 v[138:139], s[20:21], 0, v[134:135]
	s_mov_b32 m0, s64
	s_nop 0
	global_load_lds_dwordx4 v[138:139], off
	v_lshl_add_u64 v[138:139], s[20:21], 0, v[130:131]
	s_mov_b32 m0, s63
	s_nop 0
	global_load_lds_dwordx4 v[138:139], off
	v_lshl_add_u64 v[138:139], v[238:239], 0, s[68:69]
	s_mov_b32 m0, s46
	s_nop 0
	global_load_lds_dwordx4 v[138:139], off
	v_lshl_add_u64 v[138:139], v[240:241], 0, s[68:69]
	s_mov_b32 m0, s47
	s_nop 0
	global_load_lds_dwordx4 v[138:139], off
	s_waitcnt vmcnt(8)
	s_waitcnt lgkmcnt(0)
	v_mfma_f32_16x16x32_bf16 v[62:65], v[142:145], v[190:193], v[62:65]
	v_mfma_f32_16x16x32_bf16 v[58:61], v[166:169], v[190:193], v[58:61]
	s_barrier
	s_setprio 1
	s_waitcnt lgkmcnt(0)
	v_mfma_f32_16x16x32_bf16 v[50:53], v[142:145], v[212:215], v[50:53]
	v_mfma_f32_16x16x32_bf16 v[42:45], v[166:169], v[212:215], v[42:45]
	v_mfma_f32_16x16x32_bf16 v[34:37], v[142:145], v[220:223], v[34:37]
	v_mfma_f32_16x16x32_bf16 v[26:29], v[166:169], v[220:223], v[26:29]
	v_mfma_f32_16x16x32_bf16 v[18:21], v[142:145], v[228:231], v[18:21]
	v_mfma_f32_16x16x32_bf16 v[10:13], v[166:169], v[228:231], v[10:13]
	v_mfma_f32_16x16x32_bf16 v[62:65], v[162:165], v[208:211], v[62:65]
	v_mfma_f32_16x16x32_bf16 v[58:61], v[170:173], v[208:211], v[58:61]
	v_mfma_f32_16x16x32_bf16 v[50:53], v[162:165], v[216:219], v[50:53]
	v_mfma_f32_16x16x32_bf16 v[42:45], v[170:173], v[216:219], v[42:45]
	v_mfma_f32_16x16x32_bf16 v[34:37], v[162:165], v[224:227], v[34:37]
	v_mfma_f32_16x16x32_bf16 v[26:29], v[170:173], v[224:227], v[26:29]
	v_mfma_f32_16x16x32_bf16 v[18:21], v[162:165], v[232:235], v[18:21]
	v_mfma_f32_16x16x32_bf16 v[10:13], v[170:173], v[232:235], v[10:13]
	s_setprio 0
	s_setprio 1
	v_mfma_f32_16x16x32_bf16 v[54:57], v[174:177], v[190:193], v[54:57]
	v_mfma_f32_16x16x32_bf16 v[46:49], v[182:185], v[190:193], v[46:49]
	v_mfma_f32_16x16x32_bf16 v[38:41], v[174:177], v[212:215], v[38:41]
	v_mfma_f32_16x16x32_bf16 v[30:33], v[182:185], v[212:215], v[30:33]
	v_mfma_f32_16x16x32_bf16 v[22:25], v[174:177], v[220:223], v[22:25]
	v_mfma_f32_16x16x32_bf16 v[14:17], v[182:185], v[220:223], v[14:17]
	v_mfma_f32_16x16x32_bf16 v[6:9], v[174:177], v[228:231], v[6:9]
	v_mfma_f32_16x16x32_bf16 v[2:5], v[182:185], v[228:231], v[2:5]
	v_mfma_f32_16x16x32_bf16 v[54:57], v[178:181], v[208:211], v[54:57]
	v_mfma_f32_16x16x32_bf16 v[46:49], v[186:189], v[208:211], v[46:49]
	v_mfma_f32_16x16x32_bf16 v[38:41], v[178:181], v[216:219], v[38:41]
	v_mfma_f32_16x16x32_bf16 v[30:33], v[186:189], v[216:219], v[30:33]
	v_mfma_f32_16x16x32_bf16 v[22:25], v[178:181], v[224:227], v[22:25]
	v_mfma_f32_16x16x32_bf16 v[14:17], v[186:189], v[224:227], v[14:17]
	v_mfma_f32_16x16x32_bf16 v[6:9], v[178:181], v[232:235], v[6:9]
	v_mfma_f32_16x16x32_bf16 v[2:5], v[186:189], v[232:235], v[2:5]
	s_setprio 0
	s_barrier
	s_movk_i32 s22, 0x100
	s_andn2_b64 vcc, exec, s[18:19]
	s_mov_b64 s[20:21], -1
	s_mov_b64 s[18:19], 0
	s_cbranch_vccz .LBB0_4132
	s_and_b64 vcc, exec, s[4:5]
	s_mov_b32 s55, s67
	s_cbranch_vccz .LBB0_4135
	s_barrier

; #define PG8_STAGE(bufoff, gbase, voff) do { _Pragma("unroll") for (int _i = 0; _i < 2; ++_i) \
;         __builtin_amdgcn_global_load_lds((const unsigned*)((const char*)(gbase) + (voff)[_i]), (LAS unsigned*)(lds + (bufoff) + ldsw + _i * 8192), 16, 0, 0); } while (0)
; #define PG8_LDA(dst, b, h) do { _Pragma("unroll") for (int m = 0; m < 4; ++m) _Pragma("unroll") for (int k = 0; k < 2; ++k) dst[m][k] = *(const LAS bf16x8*)(lds + PG8_SA(b, h) + aoff + m * 2048 + k * 1024); } while (0)
; #define PG8_LDB(dst, b, h) do { _Pragma("unroll") for (int n = 0; n < 2; ++n) _Pragma("unroll") for (int k = 0; k < 2; ++k) dst[n][k] = *(const LAS bf16x8*)(lds + PG8_SB(b, h) + boff + n * 2048 + k * 1024); } while (0)
; #define PG8_MMA(ai, bj, At, Bt) do { __builtin_amdgcn_s_setprio(1); _Pragma("unroll") for (int m = 0; m < 4; ++m) _Pragma("unroll") for (int n = 0; n < 2; ++n) _Pragma("unroll") for (int k = 0; k < 2; ++k) \
;         acc[ai][bj][m][n] = __builtin_amdgcn_mfma_f32_16x16x32_bf16(Bt[n][k], At[m][k], acc[ai][bj][m][n], 0, 0, 0); __builtin_amdgcn_s_setprio(0); } while (0)
; #define PG8_WAIT_V(n) asm volatile("s_waitcnt vmcnt(" #n ")" ::: "memory")
; template <class Epi, class Sched>
; __device__ __forceinline__ void gemm_phase(LAS unsigned char* lds, const Gemm g, const Sched& S, const Epi& E) {
;     ...
;         const bool has_next = S.next(ui + 1, nxt);
;         const char* nA = has_next ? (const char*)g.A + (size_t)nxt.pm * tstepA : cA; const char* nB = has_next ? (const char*)g.Bt + (size_t)nxt.pn * tstepB : cB;
;         for (int t = 0; t < nt; t += 2) {
;             const bool last = (t == nt - 2);
;             const char* a1 = cA + (size_t)(t + 1) * kstep;
;             const char* a2 = last ? nA : cA + (size_t)(t + 2) * kstep; const char* b2 = last ? nB : cB + (size_t)(t + 2) * kstep;
;             const char* a3 = a2 + kstep; const char* b3 = b2 + kstep;
;             PG8_LDB(B0, 0, 0); PG8_LDB(B1, 0, 1); PG8_SCHED; PG8_LDA(At, 0, 0); PG8_STAGE(PG8_SA(1, 1), a1 + hstepA, voffA);
;             PG8_WAIT_V(8); PG8_WAIT_L(0); PG8_BAR; PG8_MMA(0, 0, At, B0); PG8_MMA(0, 1, At, B1); PG8_BAR; PG8_SCHED;
;             PG8_LDA(At, 0, 1); PG8_STAGE(PG8_SB(0, 0), b2, voffB); PG8_STAGE(PG8_SB(0, 1), b2 + hstepB, voffB); PG8_STAGE(PG8_SA(0, 0), a2, voffA);
;             PG8_WAIT_V(8); PG8_WAIT_L(0); PG8_BAR; PG8_MMA(1, 0, At, B0); PG8_MMA(1, 1, At, B1); PG8_BAR; PG8_SCHED;
.LBB0_4223:
	s_add_u32 s16, s14, 0xfff80080
	s_addc_u32 s17, s15, -1
	s_add_i32 s44, 0, 0x10000
	s_cmp_eq_u32 s43, 28
	s_cselect_b32 s19, s7, s17
	s_cselect_b32 s18, s39, s16
	v_add_u32_e32 v167, s44, v1
	s_cselect_b32 s17, s5, s42
	s_cselect_b32 s16, s40, s41
	s_add_i32 s46, 0, 0x14000
	ds_read_b128 v[142:145], v167
	ds_read_b128 v[162:165], v167 offset:1024
	ds_read_b128 v[168:171], v167 offset:2048
	ds_read_b128 v[172:175], v167 offset:3072
	v_add_u32_e32 v167, s46, v1
	ds_read_b128 v[176:179], v167
	ds_read_b128 v[180:183], v167 offset:1024
	ds_read_b128 v[184:187], v167 offset:2048
	ds_read_b128 v[188:191], v167 offset:3072
	v_lshl_add_u64 v[192:193], s[14:15], 0, v[138:139]
	s_add_i32 m0, s25, 0xc000
	ds_read_b128 v[208:211], v166
	ds_read_b128 v[212:215], v166 offset:1024
	ds_read_b128 v[216:219], v166 offset:2048
	ds_read_b128 v[220:223], v166 offset:3072
	ds_read_b128 v[224:227], v166 offset:4096
	ds_read_b128 v[228:231], v166 offset:5120
	ds_read_b128 v[232:235], v166 offset:6144
	ds_read_b128 v[236:239], v166 offset:7168
	global_load_lds_dwordx4 v[192:193], off
	v_lshl_add_u64 v[192:193], s[14:15], 0, v[140:141]
	s_add_i32 m0, s25, 0xe000
	s_nop 0
	global_load_lds_dwordx4 v[192:193], off
	s_nop 0
	s_nop 0
	s_waitcnt vmcnt(8)
	s_waitcnt lgkmcnt(0)
	v_mfma_f32_16x16x32_bf16 v[126:129], v[142:145], v[208:211], v[126:129]
	v_mfma_f32_16x16x32_bf16 v[122:125], v[168:171], v[208:211], v[122:125]
	s_barrier
	s_setprio 1
	s_waitcnt lgkmcnt(0)
	v_mfma_f32_16x16x32_bf16 v[110:113], v[142:145], v[216:219], v[110:113]
	v_mfma_f32_16x16x32_bf16 v[106:109], v[168:171], v[216:219], v[106:109]
	v_mfma_f32_16x16x32_bf16 v[94:97], v[142:145], v[224:227], v[94:97]
	v_mfma_f32_16x16x32_bf16 v[90:93], v[168:171], v[224:227], v[90:93]
	v_mfma_f32_16x16x32_bf16 v[78:81], v[142:145], v[232:235], v[78:81]
	v_mfma_f32_16x16x32_bf16 v[74:77], v[168:171], v[232:235], v[74:77]
	v_mfma_f32_16x16x32_bf16 v[126:129], v[162:165], v[212:215], v[126:129]
	v_mfma_f32_16x16x32_bf16 v[122:125], v[172:175], v[212:215], v[122:125]
	v_mfma_f32_16x16x32_bf16 v[110:113], v[162:165], v[220:223], v[110:113]
	v_mfma_f32_16x16x32_bf16 v[106:109], v[172:175], v[220:223], v[106:109]
	v_mfma_f32_16x16x32_bf16 v[94:97], v[162:165], v[228:231], v[94:97]
	v_mfma_f32_16x16x32_bf16 v[90:93], v[172:175], v[228:231], v[90:93]
	v_mfma_f32_16x16x32_bf16 v[78:81], v[162:165], v[236:239], v[78:81]
	v_mfma_f32_16x16x32_bf16 v[74:77], v[172:175], v[236:239], v[74:77]
	s_setprio 0
	s_setprio 1
	v_mfma_f32_16x16x32_bf16 v[118:121], v[176:179], v[208:211], v[118:121]
	v_mfma_f32_16x16x32_bf16 v[114:117], v[184:187], v[208:211], v[114:117]
	v_mfma_f32_16x16x32_bf16 v[102:105], v[176:179], v[216:219], v[102:105]
	v_mfma_f32_16x16x32_bf16 v[98:101], v[184:187], v[216:219], v[98:101]
	v_mfma_f32_16x16x32_bf16 v[86:89], v[176:179], v[224:227], v[86:89]
	v_mfma_f32_16x16x32_bf16 v[82:85], v[184:187], v[224:227], v[82:85]
	v_mfma_f32_16x16x32_bf16 v[70:73], v[176:179], v[232:235], v[70:73]
	v_mfma_f32_16x16x32_bf16 v[66:69], v[184:187], v[232:235], v[66:69]
	v_mfma_f32_16x16x32_bf16 v[118:121], v[180:183], v[212:215], v[118:121]
	v_mfma_f32_16x16x32_bf16 v[114:117], v[188:191], v[212:215], v[114:117]
	v_mfma_f32_16x16x32_bf16 v[102:105], v[180:183], v[220:223], v[102:105]
	v_mfma_f32_16x16x32_bf16 v[98:101], v[188:191], v[220:223], v[98:101]
	v_mfma_f32_16x16x32_bf16 v[86:89], v[180:183], v[228:231], v[86:89]
	v_mfma_f32_16x16x32_bf16 v[82:85], v[188:191], v[228:231], v[82:85]
	v_mfma_f32_16x16x32_bf16 v[70:73], v[180:183], v[236:239], v[70:73]
	v_mfma_f32_16x16x32_bf16 v[66:69], v[188:191], v[236:239], v[66:69]
	s_setprio 0
	s_barrier
	s_add_i32 s44, s44, s22
	v_lshl_add_u64 v[192:193], s[16:17], 0, v[134:135]
	s_mov_b32 m0, s44
	ds_read_b128 v[208:211], v166 offset:16384
	ds_read_b128 v[212:215], v166 offset:17408
	ds_read_b128 v[216:219], v166 offset:18432
	ds_read_b128 v[220:223], v166 offset:19456
	ds_read_b128 v[224:227], v166 offset:20480
	ds_read_b128 v[228:231], v166 offset:21504
	ds_read_b128 v[232:235], v166 offset:22528
	ds_read_b128 v[236:239], v166 offset:23552
	global_load_lds_dwordx4 v[192:193], off
	s_add_i32 m0, s44, 0x2000
	s_add_u32 s44, s16, 0x80000
	v_lshl_add_u64 v[240:241], s[16:17], 0, v[130:131]
	s_addc_u32 s45, s17, 0
	s_add_i32 s46, s46, s22
	global_load_lds_dwordx4 v[240:241], off
	v_lshl_add_u64 v[242:243], s[44:45], 0, v[134:135]
	s_mov_b32 m0, s46
	v_lshl_add_u64 v[244:245], s[18:19], 0, v[132:133]
	global_load_lds_dwordx4 v[242:243], off
	v_lshl_add_u64 v[242:243], s[44:45], 0, v[130:131]
	s_add_i32 m0, s46, 0x2000
	s_nop 0
	global_load_lds_dwordx4 v[242:243], off
	v_lshl_add_u64 v[242:243], s[18:19], 0, v[136:137]
	s_mov_b32 m0, s25
	s_nop 0
	global_load_lds_dwordx4 v[242:243], off
	s_mov_b32 m0, s26
	s_nop 0
	global_load_lds_dwordx4 v[244:245], off
	s_nop 0
	s_nop 0
	s_nop 0
	s_waitcnt vmcnt(8)
	s_waitcnt lgkmcnt(0)
	v_mfma_f32_16x16x32_bf16 v[62:65], v[142:145], v[208:211], v[62:65]
	v_mfma_f32_16x16x32_bf16 v[58:61], v[168:171], v[208:211], v[58:61]
	s_barrier
; #define PG8_STAGE(bufoff, gbase, voff) do { _Pragma("unroll") for (int _i = 0; _i < 2; ++_i) \
;         __builtin_amdgcn_global_load_lds((const unsigned*)((const char*)(gbase) + (voff)[_i]), (LAS unsigned*)(lds + (bufoff) + ldsw + _i * 8192), 16, 0, 0); } while (0)
; #define PG8_LDA(dst, b, h) do { _Pragma("unroll") for (int m = 0; m < 4; ++m) _Pragma("unroll") for (int k = 0; k < 2; ++k) dst[m][k] = *(const LAS bf16x8*)(lds + PG8_SA(b, h) + aoff + m * 2048 + k * 1024); } while (0)
; #define PG8_LDB(dst, b, h) do { _Pragma("unroll") for (int n = 0; n < 2; ++n) _Pragma("unroll") for (int k = 0; k < 2; ++k) dst[n][k] = *(const LAS bf16x8*)(lds + PG8_SB(b, h) + boff + n * 2048 + k * 1024); } while (0)
; #define PG8_MMA(ai, bj, At, Bt) do { __builtin_amdgcn_s_setprio(1); _Pragma("unroll") for (int m = 0; m < 4; ++m) _Pragma("unroll") for (int n = 0; n < 2; ++n) _Pragma("unroll") for (int k = 0; k < 2; ++k) \
;         acc[ai][bj][m][n] = __builtin_amdgcn_mfma_f32_16x16x32_bf16(Bt[n][k], At[m][k], acc[ai][bj][m][n], 0, 0, 0); __builtin_amdgcn_s_setprio(0); } while (0)
; #define PG8_WAIT_V(n) asm volatile("s_waitcnt vmcnt(" #n ")" ::: "memory")
; #define PG8_WAIT_L(n) asm volatile("s_waitcnt lgkmcnt(" #n ")" ::: "memory")
; #define PG8_BAR __builtin_amdgcn_s_barrier()
; #define PG8_SCHED __builtin_amdgcn_sched_barrier(0)
; template <class Epi, class Sched>
; __device__ __forceinline__ void gemm_phase(LAS unsigned char* lds, const Gemm g, const Sched& S, const Epi& E) {
;     ...
;             PG8_WAIT_V(8); PG8_WAIT_L(0); PG8_BAR; PG8_MMA(1, 0, At, B0); PG8_MMA(1, 1, At, B1); PG8_BAR; PG8_SCHED;
;             PG8_LDB(B0, 1, 0); PG8_LDB(B1, 1, 1); PG8_SCHED; PG8_LDA(At, 1, 0); PG8_STAGE(PG8_SA(0, 1), a2 + hstepA, voffA);
;             PG8_WAIT_V(8); PG8_WAIT_L(0); PG8_BAR; PG8_MMA(0, 0, At, B0); PG8_MMA(0, 1, At, B1); PG8_BAR; PG8_SCHED;
	s_setprio 1
	s_waitcnt lgkmcnt(0)
	v_mfma_f32_16x16x32_bf16 v[46:49], v[142:145], v[216:219], v[46:49]
	v_mfma_f32_16x16x32_bf16 v[42:45], v[168:171], v[216:219], v[42:45]
	v_mfma_f32_16x16x32_bf16 v[30:33], v[142:145], v[224:227], v[30:33]
	v_mfma_f32_16x16x32_bf16 v[26:29], v[168:171], v[224:227], v[26:29]
	v_mfma_f32_16x16x32_bf16 v[14:17], v[142:145], v[232:235], v[14:17]
	v_mfma_f32_16x16x32_bf16 v[10:13], v[168:171], v[232:235], v[10:13]
	v_mfma_f32_16x16x32_bf16 v[62:65], v[162:165], v[212:215], v[62:65]
	v_mfma_f32_16x16x32_bf16 v[58:61], v[172:175], v[212:215], v[58:61]
	v_mfma_f32_16x16x32_bf16 v[46:49], v[162:165], v[220:223], v[46:49]
	v_mfma_f32_16x16x32_bf16 v[42:45], v[172:175], v[220:223], v[42:45]
	v_mfma_f32_16x16x32_bf16 v[30:33], v[162:165], v[228:231], v[30:33]
	v_mfma_f32_16x16x32_bf16 v[26:29], v[172:175], v[228:231], v[26:29]
	v_mfma_f32_16x16x32_bf16 v[14:17], v[162:165], v[236:239], v[14:17]
	v_mfma_f32_16x16x32_bf16 v[10:13], v[172:175], v[236:239], v[10:13]
	s_setprio 0
	s_setprio 1
	v_mfma_f32_16x16x32_bf16 v[54:57], v[176:179], v[208:211], v[54:57]
	v_mfma_f32_16x16x32_bf16 v[50:53], v[184:187], v[208:211], v[50:53]
	v_mfma_f32_16x16x32_bf16 v[38:41], v[176:179], v[216:219], v[38:41]
	v_mfma_f32_16x16x32_bf16 v[34:37], v[184:187], v[216:219], v[34:37]
	v_mfma_f32_16x16x32_bf16 v[22:25], v[176:179], v[224:227], v[22:25]
	v_mfma_f32_16x16x32_bf16 v[18:21], v[184:187], v[224:227], v[18:21]
	v_mfma_f32_16x16x32_bf16 v[6:9], v[176:179], v[232:235], v[6:9]
	v_mfma_f32_16x16x32_bf16 v[2:5], v[184:187], v[232:235], v[2:5]
	v_mfma_f32_16x16x32_bf16 v[54:57], v[180:183], v[212:215], v[54:57]
	v_mfma_f32_16x16x32_bf16 v[50:53], v[188:191], v[212:215], v[50:53]
	v_mfma_f32_16x16x32_bf16 v[38:41], v[180:183], v[220:223], v[38:41]
	v_mfma_f32_16x16x32_bf16 v[34:37], v[188:191], v[220:223], v[34:37]
	v_mfma_f32_16x16x32_bf16 v[22:25], v[180:183], v[228:231], v[22:25]
	v_mfma_f32_16x16x32_bf16 v[18:21], v[188:191], v[228:231], v[18:21]
	v_mfma_f32_16x16x32_bf16 v[6:9], v[180:183], v[236:239], v[6:9]
	v_mfma_f32_16x16x32_bf16 v[2:5], v[188:191], v[236:239], v[2:5]
	s_setprio 0
	s_barrier
	s_add_i32 s44, 0, 0x18000
	v_add_u32_e32 v167, s44, v1
	s_add_i32 s45, 0, 0x1c000
	ds_read_b128 v[142:145], v167
	ds_read_b128 v[162:165], v167 offset:1024
	ds_read_b128 v[168:171], v167 offset:2048
	ds_read_b128 v[172:175], v167 offset:3072
	v_add_u32_e32 v167, s45, v1
	ds_read_b128 v[176:179], v167
	ds_read_b128 v[180:183], v167 offset:1024
	ds_read_b128 v[184:187], v167 offset:2048
	ds_read_b128 v[188:191], v167 offset:3072
	s_add_u32 s18, s18, 0x80000
	s_addc_u32 s19, s19, 0
	s_mov_b32 m0, s27
	v_lshl_add_u64 v[246:247], s[18:19], 0, v[136:137]
	ds_read_b128 v[208:211], v166 offset:32768
	ds_read_b128 v[212:215], v166 offset:33792
	ds_read_b128 v[216:219], v166 offset:34816
	ds_read_b128 v[220:223], v166 offset:35840
	ds_read_b128 v[224:227], v166 offset:36864
	ds_read_b128 v[228:231], v166 offset:37888
	ds_read_b128 v[232:235], v166 offset:38912
	ds_read_b128 v[236:239], v166 offset:39936
	global_load_lds_dwordx4 v[246:247], off
	v_lshl_add_u64 v[246:247], s[18:19], 0, v[132:133]
	s_mov_b32 m0, s28
	s_nop 0
	global_load_lds_dwordx4 v[246:247], off
	s_nop 0
	s_nop 0
	s_nop 0
	s_waitcnt vmcnt(8)
	s_waitcnt lgkmcnt(0)
	v_mfma_f32_16x16x32_bf16 v[126:129], v[142:145], v[208:211], v[126:129]
	v_mfma_f32_16x16x32_bf16 v[122:125], v[168:171], v[208:211], v[122:125]
	s_barrier
	s_setprio 1
	s_waitcnt lgkmcnt(0)
	v_mfma_f32_16x16x32_bf16 v[110:113], v[142:145], v[216:219], v[110:113]
	v_mfma_f32_16x16x32_bf16 v[106:109], v[168:171], v[216:219], v[106:109]
	v_mfma_f32_16x16x32_bf16 v[94:97], v[142:145], v[224:227], v[94:97]
	v_mfma_f32_16x16x32_bf16 v[90:93], v[168:171], v[224:227], v[90:93]
	v_mfma_f32_16x16x32_bf16 v[78:81], v[142:145], v[232:235], v[78:81]
	v_mfma_f32_16x16x32_bf16 v[74:77], v[168:171], v[232:235], v[74:77]
	v_mfma_f32_16x16x32_bf16 v[126:129], v[162:165], v[212:215], v[126:129]
	v_mfma_f32_16x16x32_bf16 v[122:125], v[172:175], v[212:215], v[122:125]
	v_mfma_f32_16x16x32_bf16 v[110:113], v[162:165], v[220:223], v[110:113]
	v_mfma_f32_16x16x32_bf16 v[106:109], v[172:175], v[220:223], v[106:109]
	v_mfma_f32_16x16x32_bf16 v[94:97], v[162:165], v[228:231], v[94:97]
	v_mfma_f32_16x16x32_bf16 v[90:93], v[172:175], v[228:231], v[90:93]
	v_mfma_f32_16x16x32_bf16 v[78:81], v[162:165], v[236:239], v[78:81]
	v_mfma_f32_16x16x32_bf16 v[74:77], v[172:175], v[236:239], v[74:77]
	s_setprio 0
	s_setprio 1
	v_mfma_f32_16x16x32_bf16 v[118:121], v[176:179], v[208:211], v[118:121]
	v_mfma_f32_16x16x32_bf16 v[114:117], v[184:187], v[208:211], v[114:117]
	v_mfma_f32_16x16x32_bf16 v[102:105], v[176:179], v[216:219], v[102:105]
	v_mfma_f32_16x16x32_bf16 v[98:101], v[184:187], v[216:219], v[98:101]
	v_mfma_f32_16x16x32_bf16 v[86:89], v[176:179], v[224:227], v[86:89]
	v_mfma_f32_16x16x32_bf16 v[82:85], v[184:187], v[224:227], v[82:85]
	v_mfma_f32_16x16x32_bf16 v[70:73], v[176:179], v[232:235], v[70:73]
	v_mfma_f32_16x16x32_bf16 v[66:69], v[184:187], v[232:235], v[66:69]
	v_mfma_f32_16x16x32_bf16 v[118:121], v[180:183], v[212:215], v[118:121]
	v_mfma_f32_16x16x32_bf16 v[114:117], v[188:191], v[212:215], v[114:117]
	v_mfma_f32_16x16x32_bf16 v[102:105], v[180:183], v[220:223], v[102:105]
	v_mfma_f32_16x16x32_bf16 v[98:101], v[188:191], v[220:223], v[98:101]
	v_mfma_f32_16x16x32_bf16 v[86:89], v[180:183], v[228:231], v[86:89]
	v_mfma_f32_16x16x32_bf16 v[82:85], v[188:191], v[228:231], v[82:85]
	v_mfma_f32_16x16x32_bf16 v[70:73], v[180:183], v[236:239], v[70:73]
	v_mfma_f32_16x16x32_bf16 v[66:69], v[188:191], v[236:239], v[66:69]
	s_setprio 0
	s_barrier
; #define PG8_STAGE(bufoff, gbase, voff) do { _Pragma("unroll") for (int _i = 0; _i < 2; ++_i) \
;         __builtin_amdgcn_global_load_lds((const unsigned*)((const char*)(gbase) + (voff)[_i]), (LAS unsigned*)(lds + (bufoff) + ldsw + _i * 8192), 16, 0, 0); } while (0)
; #define PG8_LDA(dst, b, h) do { _Pragma("unroll") for (int m = 0; m < 4; ++m) _Pragma("unroll") for (int k = 0; k < 2; ++k) dst[m][k] = *(const LAS bf16x8*)(lds + PG8_SA(b, h) + aoff + m * 2048 + k * 1024); } while (0)
; #define PG8_MMA(ai, bj, At, Bt) do { __builtin_amdgcn_s_setprio(1); _Pragma("unroll") for (int m = 0; m < 4; ++m) _Pragma("unroll") for (int n = 0; n < 2; ++n) _Pragma("unroll") for (int k = 0; k < 2; ++k) \
;         acc[ai][bj][m][n] = __builtin_amdgcn_mfma_f32_16x16x32_bf16(Bt[n][k], At[m][k], acc[ai][bj][m][n], 0, 0, 0); __builtin_amdgcn_s_setprio(0); } while (0)
; #define PG8_WAIT_V(n) asm volatile("s_waitcnt vmcnt(" #n ")" ::: "memory")
; #define PG8_WAIT_L(n) asm volatile("s_waitcnt lgkmcnt(" #n ")" ::: "memory")
; #define PG8_BAR __builtin_amdgcn_s_barrier()
; #define PG8_SCHED __builtin_amdgcn_sched_barrier(0)
; template <class Epi, class Sched>
; __device__ __forceinline__ void gemm_phase(LAS unsigned char* lds, const Gemm g, const Sched& S, const Epi& E) {
;     ...
;             PG8_LDA(At, 1, 1); PG8_STAGE(PG8_SB(1, 0), b3, voffB); PG8_STAGE(PG8_SB(1, 1), b3 + hstepB, voffB); PG8_STAGE(PG8_SA(1, 0), a3, voffA);
;             PG8_WAIT_V(8); PG8_WAIT_L(0); PG8_BAR; PG8_MMA(1, 0, At, B0); PG8_MMA(1, 1, At, B1); PG8_BAR; PG8_SCHED;
;         }
;         if (wr == 0) PG8_BAR;
	s_add_i32 s18, s44, s22
	v_lshl_add_u64 v[192:193], v[192:193], 0, s[56:57]
	s_mov_b32 m0, s18
	ds_read_b128 v[208:211], v166 offset:49152
	ds_read_b128 v[212:215], v166 offset:50176
	ds_read_b128 v[216:219], v166 offset:51200
	ds_read_b128 v[220:223], v166 offset:52224
	ds_read_b128 v[224:227], v166 offset:53248
	ds_read_b128 v[228:231], v166 offset:54272
	ds_read_b128 v[232:235], v166 offset:55296
	ds_read_b128 v[236:239], v166 offset:56320
	global_load_lds_dwordx4 v[192:193], off
	s_add_i32 m0, s18, 0x2000
	s_add_u32 s16, s16, 0x80080
	v_lshl_add_u64 v[192:193], v[240:241], 0, s[56:57]
	s_addc_u32 s17, s17, 0
	s_add_i32 s18, s45, s22
	global_load_lds_dwordx4 v[192:193], off
	v_lshl_add_u64 v[192:193], s[16:17], 0, v[134:135]
	s_mov_b32 m0, s18
	s_nop 0
	global_load_lds_dwordx4 v[192:193], off
	v_lshl_add_u64 v[192:193], s[16:17], 0, v[130:131]
	s_add_i32 m0, s18, 0x2000
	s_nop 0
	global_load_lds_dwordx4 v[192:193], off
	v_lshl_add_u64 v[192:193], v[242:243], 0, s[56:57]
	s_mov_b32 m0, s31
	s_nop 0
	global_load_lds_dwordx4 v[192:193], off
	v_lshl_add_u64 v[192:193], v[244:245], 0, s[56:57]
	s_mov_b32 m0, s33
	s_nop 0
	global_load_lds_dwordx4 v[192:193], off
	s_nop 0
	s_nop 0
	s_waitcnt vmcnt(8)
	s_waitcnt lgkmcnt(0)
	v_mfma_f32_16x16x32_bf16 v[62:65], v[142:145], v[208:211], v[62:65]
	v_mfma_f32_16x16x32_bf16 v[58:61], v[168:171], v[208:211], v[58:61]
	s_barrier
	s_setprio 1
	s_waitcnt lgkmcnt(0)
	v_mfma_f32_16x16x32_bf16 v[46:49], v[142:145], v[216:219], v[46:49]
	v_mfma_f32_16x16x32_bf16 v[42:45], v[168:171], v[216:219], v[42:45]
	v_mfma_f32_16x16x32_bf16 v[30:33], v[142:145], v[224:227], v[30:33]
	v_mfma_f32_16x16x32_bf16 v[26:29], v[168:171], v[224:227], v[26:29]
	v_mfma_f32_16x16x32_bf16 v[14:17], v[142:145], v[232:235], v[14:17]
	v_mfma_f32_16x16x32_bf16 v[10:13], v[168:171], v[232:235], v[10:13]
	v_mfma_f32_16x16x32_bf16 v[62:65], v[162:165], v[212:215], v[62:65]
	v_mfma_f32_16x16x32_bf16 v[58:61], v[172:175], v[212:215], v[58:61]
	v_mfma_f32_16x16x32_bf16 v[46:49], v[162:165], v[220:223], v[46:49]
	v_mfma_f32_16x16x32_bf16 v[42:45], v[172:175], v[220:223], v[42:45]
	v_mfma_f32_16x16x32_bf16 v[30:33], v[162:165], v[228:231], v[30:33]
	v_mfma_f32_16x16x32_bf16 v[26:29], v[172:175], v[228:231], v[26:29]
	v_mfma_f32_16x16x32_bf16 v[14:17], v[162:165], v[236:239], v[14:17]
	v_mfma_f32_16x16x32_bf16 v[10:13], v[172:175], v[236:239], v[10:13]
	s_setprio 0
	s_setprio 1
	v_mfma_f32_16x16x32_bf16 v[54:57], v[176:179], v[208:211], v[54:57]
	v_mfma_f32_16x16x32_bf16 v[50:53], v[184:187], v[208:211], v[50:53]
	v_mfma_f32_16x16x32_bf16 v[38:41], v[176:179], v[216:219], v[38:41]
	v_mfma_f32_16x16x32_bf16 v[34:37], v[184:187], v[216:219], v[34:37]
	v_mfma_f32_16x16x32_bf16 v[22:25], v[176:179], v[224:227], v[22:25]
	v_mfma_f32_16x16x32_bf16 v[18:21], v[184:187], v[224:227], v[18:21]
	v_mfma_f32_16x16x32_bf16 v[6:9], v[176:179], v[232:235], v[6:9]
	v_mfma_f32_16x16x32_bf16 v[2:5], v[184:187], v[232:235], v[2:5]
	v_mfma_f32_16x16x32_bf16 v[54:57], v[180:183], v[212:215], v[54:57]
	v_mfma_f32_16x16x32_bf16 v[50:53], v[188:191], v[212:215], v[50:53]
	v_mfma_f32_16x16x32_bf16 v[38:41], v[180:183], v[220:223], v[38:41]
	v_mfma_f32_16x16x32_bf16 v[34:37], v[188:191], v[220:223], v[34:37]
	v_mfma_f32_16x16x32_bf16 v[22:25], v[180:183], v[228:231], v[22:25]
	v_mfma_f32_16x16x32_bf16 v[18:21], v[188:191], v[228:231], v[18:21]
	v_mfma_f32_16x16x32_bf16 v[6:9], v[180:183], v[236:239], v[6:9]
	v_mfma_f32_16x16x32_bf16 v[2:5], v[188:191], v[236:239], v[2:5]
	s_setprio 0
	s_barrier
	s_add_i32 s43, s43, 2
	s_add_u32 s14, s14, 0x100
	s_addc_u32 s15, s15, 0
	s_add_u32 s41, s41, 0x100
	s_addc_u32 s42, s42, 0
	s_cmp_gt_u32 s43, 29
	s_cbranch_scc0 .LBB0_4223
	s_and_b64 vcc, exec, s[2:3]
	s_cbranch_vccz .LBB0_4226
	s_barrier

; #define PG8_STAGE(bufoff, gbase, voff) do { _Pragma("unroll") for (int _i = 0; _i < 2; ++_i) \
;         __builtin_amdgcn_global_load_lds((const unsigned*)((const char*)(gbase) + (voff)[_i]), (LAS unsigned*)(lds + (bufoff) + ldsw + _i * 8192), 16, 0, 0); } while (0)
; #define PG8_LDA(dst, b, h) do { _Pragma("unroll") for (int m = 0; m < 4; ++m) _Pragma("unroll") for (int k = 0; k < 2; ++k) dst[m][k] = *(const LAS bf16x8*)(lds + PG8_SA(b, h) + aoff + m * 2048 + k * 1024); } while (0)
; #define PG8_LDB(dst, b, h) do { _Pragma("unroll") for (int n = 0; n < 2; ++n) _Pragma("unroll") for (int k = 0; k < 2; ++k) dst[n][k] = *(const LAS bf16x8*)(lds + PG8_SB(b, h) + boff + n * 2048 + k * 1024); } while (0)
; #define PG8_MMA(ai, bj, At, Bt) do { __builtin_amdgcn_s_setprio(1); _Pragma("unroll") for (int m = 0; m < 4; ++m) _Pragma("unroll") for (int n = 0; n < 2; ++n) _Pragma("unroll") for (int k = 0; k < 2; ++k) \
;         acc[ai][bj][m][n] = __builtin_amdgcn_mfma_f32_16x16x32_bf16(Bt[n][k], At[m][k], acc[ai][bj][m][n], 0, 0, 0); __builtin_amdgcn_s_setprio(0); } while (0)
; #define PG8_WAIT_V(n) asm volatile("s_waitcnt vmcnt(" #n ")" ::: "memory")
; template <class Epi, class Sched>
; __device__ __forceinline__ void gemm_phase(LAS unsigned char* lds, const Gemm g, const Sched& S, const Epi& E) {
;     ...
;         const bool has_next = S.next(ui + 1, nxt);
;         const char* nA = has_next ? (const char*)g.A + (size_t)nxt.pm * tstepA : cA; const char* nB = has_next ? (const char*)g.Bt + (size_t)nxt.pn * tstepB : cB;
;         for (int t = 0; t < nt; t += 2) {
;             const bool last = (t == nt - 2);
;             const char* a1 = cA + (size_t)(t + 1) * kstep;
;             const char* a2 = last ? nA : cA + (size_t)(t + 2) * kstep; const char* b2 = last ? nB : cB + (size_t)(t + 2) * kstep;
;             const char* a3 = a2 + kstep; const char* b3 = b2 + kstep;
;             PG8_LDB(B0, 0, 0); PG8_LDB(B1, 0, 1); PG8_SCHED; PG8_LDA(At, 0, 0); PG8_STAGE(PG8_SA(1, 1), a1 + hstepA, voffA);
;             PG8_WAIT_V(8); PG8_WAIT_L(0); PG8_BAR; PG8_MMA(0, 0, At, B0); PG8_MMA(0, 1, At, B1); PG8_BAR; PG8_SCHED;
;             PG8_LDA(At, 0, 1); PG8_STAGE(PG8_SB(0, 0), b2, voffB); PG8_STAGE(PG8_SB(0, 1), b2 + hstepB, voffB); PG8_STAGE(PG8_SA(0, 0), a2, voffA);
;             PG8_WAIT_V(8); PG8_WAIT_L(0); PG8_BAR; PG8_MMA(1, 0, At, B0); PG8_MMA(1, 1, At, B1); PG8_BAR; PG8_SCHED;
.LBB0_4314:
	s_add_u32 s22, s20, 0xffe00080
	s_addc_u32 s23, s21, -1
	s_add_i32 s46, 0, 0x10000
	s_cmpk_eq_i32 s45, 0x7c
	s_cselect_b32 s25, s11, s23
	s_cselect_b32 s24, s17, s22
	s_cselect_b32 s23, s7, s44
	s_cselect_b32 s22, s19, s43
	s_add_i32 s49, 0, 0x14000
	v_add_u32_e32 v170, s46, v1
	v_add_u32_e32 v174, s49, v1
	ds_read_b128 v[130:133], v170
	ds_read_b128 v[134:137], v170 offset:1024
	ds_read_b128 v[166:169], v170 offset:2048
	ds_read_b128 v[170:173], v170 offset:3072
	ds_read_b128 v[178:181], v174
	ds_read_b128 v[182:185], v174 offset:1024
	ds_read_b128 v[186:189], v174 offset:2048
	ds_read_b128 v[190:193], v174 offset:3072
	v_lshl_add_u64 v[174:175], s[20:21], 0, v[162:163]
	s_add_i32 m0, s31, 0xc000
	ds_read_b128 v[208:211], v176
	ds_read_b128 v[212:215], v176 offset:1024
	ds_read_b128 v[216:219], v176 offset:2048
	ds_read_b128 v[220:223], v176 offset:3072
	ds_read_b128 v[224:227], v176 offset:4096
	ds_read_b128 v[228:231], v176 offset:5120
	ds_read_b128 v[232:235], v176 offset:6144
	ds_read_b128 v[236:239], v176 offset:7168
	global_load_lds_dwordx4 v[174:175], off
	v_lshl_add_u64 v[174:175], s[20:21], 0, v[164:165]
	s_add_i32 m0, s31, 0xe000
	s_nop 0
	global_load_lds_dwordx4 v[174:175], off
	s_waitcnt vmcnt(8)
	s_waitcnt lgkmcnt(0)
	v_mfma_f32_16x16x32_bf16 v[126:129], v[130:133], v[208:211], v[126:129]
	v_mfma_f32_16x16x32_bf16 v[122:125], v[166:169], v[208:211], v[122:125]
	s_barrier
	s_setprio 1
	s_waitcnt lgkmcnt(0)
	v_mfma_f32_16x16x32_bf16 v[110:113], v[130:133], v[216:219], v[110:113]
	v_mfma_f32_16x16x32_bf16 v[106:109], v[166:169], v[216:219], v[106:109]
	v_mfma_f32_16x16x32_bf16 v[94:97], v[130:133], v[224:227], v[94:97]
	v_mfma_f32_16x16x32_bf16 v[90:93], v[166:169], v[224:227], v[90:93]
	v_mfma_f32_16x16x32_bf16 v[78:81], v[130:133], v[232:235], v[78:81]
	v_mfma_f32_16x16x32_bf16 v[74:77], v[166:169], v[232:235], v[74:77]
	v_mfma_f32_16x16x32_bf16 v[126:129], v[134:137], v[212:215], v[126:129]
	v_mfma_f32_16x16x32_bf16 v[122:125], v[170:173], v[212:215], v[122:125]
	v_mfma_f32_16x16x32_bf16 v[110:113], v[134:137], v[220:223], v[110:113]
	v_mfma_f32_16x16x32_bf16 v[106:109], v[170:173], v[220:223], v[106:109]
	v_mfma_f32_16x16x32_bf16 v[94:97], v[134:137], v[228:231], v[94:97]
	v_mfma_f32_16x16x32_bf16 v[90:93], v[170:173], v[228:231], v[90:93]
	v_mfma_f32_16x16x32_bf16 v[78:81], v[134:137], v[236:239], v[78:81]
	v_mfma_f32_16x16x32_bf16 v[74:77], v[170:173], v[236:239], v[74:77]
	s_setprio 0
	s_setprio 1
	v_mfma_f32_16x16x32_bf16 v[118:121], v[178:181], v[208:211], v[118:121]
	v_mfma_f32_16x16x32_bf16 v[114:117], v[186:189], v[208:211], v[114:117]
	v_mfma_f32_16x16x32_bf16 v[102:105], v[178:181], v[216:219], v[102:105]
	v_mfma_f32_16x16x32_bf16 v[98:101], v[186:189], v[216:219], v[98:101]
	v_mfma_f32_16x16x32_bf16 v[86:89], v[178:181], v[224:227], v[86:89]
	v_mfma_f32_16x16x32_bf16 v[82:85], v[186:189], v[224:227], v[82:85]
	v_mfma_f32_16x16x32_bf16 v[70:73], v[178:181], v[232:235], v[70:73]
	v_mfma_f32_16x16x32_bf16 v[66:69], v[186:189], v[232:235], v[66:69]
	v_mfma_f32_16x16x32_bf16 v[118:121], v[182:185], v[212:215], v[118:121]
	v_mfma_f32_16x16x32_bf16 v[114:117], v[190:193], v[212:215], v[114:117]
	v_mfma_f32_16x16x32_bf16 v[102:105], v[182:185], v[220:223], v[102:105]
	v_mfma_f32_16x16x32_bf16 v[98:101], v[190:193], v[220:223], v[98:101]
	v_mfma_f32_16x16x32_bf16 v[86:89], v[182:185], v[228:231], v[86:89]
	v_mfma_f32_16x16x32_bf16 v[82:85], v[190:193], v[228:231], v[82:85]
	v_mfma_f32_16x16x32_bf16 v[70:73], v[182:185], v[236:239], v[70:73]
	v_mfma_f32_16x16x32_bf16 v[66:69], v[190:193], v[236:239], v[66:69]
	s_setprio 0
	s_barrier
	s_add_i32 s46, s46, s30
	v_lshl_add_u64 v[174:175], s[22:23], 0, v[140:141]
	s_mov_b32 m0, s46
	ds_read_b128 v[208:211], v176 offset:16384
	ds_read_b128 v[212:215], v176 offset:17408
	ds_read_b128 v[216:219], v176 offset:18432
	ds_read_b128 v[220:223], v176 offset:19456
	ds_read_b128 v[224:227], v176 offset:20480
	ds_read_b128 v[228:231], v176 offset:21504
	ds_read_b128 v[232:235], v176 offset:22528
	ds_read_b128 v[236:239], v176 offset:23552
	global_load_lds_dwordx4 v[174:175], off
	s_add_i32 m0, s46, 0x2000
	s_add_u32 s46, s22, 0x200000
	v_lshl_add_u64 v[240:241], s[22:23], 0, v[144:145]
	s_addc_u32 s47, s23, 0
	s_add_i32 s49, s49, s30
	global_load_lds_dwordx4 v[240:241], off
	v_lshl_add_u64 v[242:243], s[46:47], 0, v[140:141]
	s_mov_b32 m0, s49
	v_lshl_add_u64 v[244:245], s[24:25], 0, v[142:143]
	global_load_lds_dwordx4 v[242:243], off
	v_lshl_add_u64 v[242:243], s[46:47], 0, v[144:145]
	s_add_i32 m0, s49, 0x2000
	s_nop 0
	global_load_lds_dwordx4 v[242:243], off
	v_lshl_add_u64 v[242:243], s[24:25], 0, v[138:139]
	s_mov_b32 m0, s31
	s_nop 0
	global_load_lds_dwordx4 v[242:243], off
	s_mov_b32 m0, s33
	s_nop 0
	global_load_lds_dwordx4 v[244:245], off
	s_nop 0
	s_nop 0
	s_nop 0
	s_waitcnt vmcnt(8)
	s_waitcnt lgkmcnt(0)
	v_mfma_f32_16x16x32_bf16 v[62:65], v[130:133], v[208:211], v[62:65]
	v_mfma_f32_16x16x32_bf16 v[58:61], v[166:169], v[208:211], v[58:61]
	s_barrier
; #define PG8_STAGE(bufoff, gbase, voff) do { _Pragma("unroll") for (int _i = 0; _i < 2; ++_i) \
;         __builtin_amdgcn_global_load_lds((const unsigned*)((const char*)(gbase) + (voff)[_i]), (LAS unsigned*)(lds + (bufoff) + ldsw + _i * 8192), 16, 0, 0); } while (0)
; #define PG8_LDA(dst, b, h) do { _Pragma("unroll") for (int m = 0; m < 4; ++m) _Pragma("unroll") for (int k = 0; k < 2; ++k) dst[m][k] = *(const LAS bf16x8*)(lds + PG8_SA(b, h) + aoff + m * 2048 + k * 1024); } while (0)
; #define PG8_LDB(dst, b, h) do { _Pragma("unroll") for (int n = 0; n < 2; ++n) _Pragma("unroll") for (int k = 0; k < 2; ++k) dst[n][k] = *(const LAS bf16x8*)(lds + PG8_SB(b, h) + boff + n * 2048 + k * 1024); } while (0)
; #define PG8_MMA(ai, bj, At, Bt) do { __builtin_amdgcn_s_setprio(1); _Pragma("unroll") for (int m = 0; m < 4; ++m) _Pragma("unroll") for (int n = 0; n < 2; ++n) _Pragma("unroll") for (int k = 0; k < 2; ++k) \
;         acc[ai][bj][m][n] = __builtin_amdgcn_mfma_f32_16x16x32_bf16(Bt[n][k], At[m][k], acc[ai][bj][m][n], 0, 0, 0); __builtin_amdgcn_s_setprio(0); } while (0)
; #define PG8_WAIT_V(n) asm volatile("s_waitcnt vmcnt(" #n ")" ::: "memory")
; #define PG8_WAIT_L(n) asm volatile("s_waitcnt lgkmcnt(" #n ")" ::: "memory")
; #define PG8_BAR __builtin_amdgcn_s_barrier()
; #define PG8_SCHED __builtin_amdgcn_sched_barrier(0)
; template <class Epi, class Sched>
; __device__ __forceinline__ void gemm_phase(LAS unsigned char* lds, const Gemm g, const Sched& S, const Epi& E) {
;     ...
;             PG8_WAIT_V(8); PG8_WAIT_L(0); PG8_BAR; PG8_MMA(1, 0, At, B0); PG8_MMA(1, 1, At, B1); PG8_BAR; PG8_SCHED;
;             PG8_LDB(B0, 1, 0); PG8_LDB(B1, 1, 1); PG8_SCHED; PG8_LDA(At, 1, 0); PG8_STAGE(PG8_SA(0, 1), a2 + hstepA, voffA);
;             PG8_WAIT_V(8); PG8_WAIT_L(0); PG8_BAR; PG8_MMA(0, 0, At, B0); PG8_MMA(0, 1, At, B1); PG8_BAR; PG8_SCHED;
	s_setprio 1
	s_waitcnt lgkmcnt(0)
	v_mfma_f32_16x16x32_bf16 v[46:49], v[130:133], v[216:219], v[46:49]
	v_mfma_f32_16x16x32_bf16 v[42:45], v[166:169], v[216:219], v[42:45]
	v_mfma_f32_16x16x32_bf16 v[30:33], v[130:133], v[224:227], v[30:33]
	v_mfma_f32_16x16x32_bf16 v[26:29], v[166:169], v[224:227], v[26:29]
	v_mfma_f32_16x16x32_bf16 v[14:17], v[130:133], v[232:235], v[14:17]
	v_mfma_f32_16x16x32_bf16 v[10:13], v[166:169], v[232:235], v[10:13]
	v_mfma_f32_16x16x32_bf16 v[62:65], v[134:137], v[212:215], v[62:65]
	v_mfma_f32_16x16x32_bf16 v[58:61], v[170:173], v[212:215], v[58:61]
	v_mfma_f32_16x16x32_bf16 v[46:49], v[134:137], v[220:223], v[46:49]
	v_mfma_f32_16x16x32_bf16 v[42:45], v[170:173], v[220:223], v[42:45]
	v_mfma_f32_16x16x32_bf16 v[30:33], v[134:137], v[228:231], v[30:33]
	v_mfma_f32_16x16x32_bf16 v[26:29], v[170:173], v[228:231], v[26:29]
	v_mfma_f32_16x16x32_bf16 v[14:17], v[134:137], v[236:239], v[14:17]
	v_mfma_f32_16x16x32_bf16 v[10:13], v[170:173], v[236:239], v[10:13]
	s_setprio 0
	s_setprio 1
	v_mfma_f32_16x16x32_bf16 v[54:57], v[178:181], v[208:211], v[54:57]
	v_mfma_f32_16x16x32_bf16 v[50:53], v[186:189], v[208:211], v[50:53]
	v_mfma_f32_16x16x32_bf16 v[38:41], v[178:181], v[216:219], v[38:41]
	v_mfma_f32_16x16x32_bf16 v[34:37], v[186:189], v[216:219], v[34:37]
	v_mfma_f32_16x16x32_bf16 v[22:25], v[178:181], v[224:227], v[22:25]
	v_mfma_f32_16x16x32_bf16 v[18:21], v[186:189], v[224:227], v[18:21]
	v_mfma_f32_16x16x32_bf16 v[6:9], v[178:181], v[232:235], v[6:9]
	v_mfma_f32_16x16x32_bf16 v[2:5], v[186:189], v[232:235], v[2:5]
	v_mfma_f32_16x16x32_bf16 v[54:57], v[182:185], v[212:215], v[54:57]
	v_mfma_f32_16x16x32_bf16 v[50:53], v[190:193], v[212:215], v[50:53]
	v_mfma_f32_16x16x32_bf16 v[38:41], v[182:185], v[220:223], v[38:41]
	v_mfma_f32_16x16x32_bf16 v[34:37], v[190:193], v[220:223], v[34:37]
	v_mfma_f32_16x16x32_bf16 v[22:25], v[182:185], v[228:231], v[22:25]
	v_mfma_f32_16x16x32_bf16 v[18:21], v[190:193], v[228:231], v[18:21]
	v_mfma_f32_16x16x32_bf16 v[6:9], v[182:185], v[236:239], v[6:9]
	v_mfma_f32_16x16x32_bf16 v[2:5], v[190:193], v[236:239], v[2:5]
	s_setprio 0
	s_barrier
	s_add_i32 s46, 0, 0x18000
	s_add_i32 s47, 0, 0x1c000
	v_add_u32_e32 v170, s46, v1
	v_add_u32_e32 v177, s47, v1
	ds_read_b128 v[130:133], v170
	ds_read_b128 v[134:137], v170 offset:1024
	ds_read_b128 v[166:169], v170 offset:2048
	ds_read_b128 v[170:173], v170 offset:3072
	ds_read_b128 v[178:181], v177
	ds_read_b128 v[182:185], v177 offset:1024
	ds_read_b128 v[186:189], v177 offset:2048
	ds_read_b128 v[190:193], v177 offset:3072
	s_add_u32 s24, s24, 0x200000
	s_addc_u32 s25, s25, 0
	s_mov_b32 m0, s34
	v_lshl_add_u64 v[246:247], s[24:25], 0, v[138:139]
	ds_read_b128 v[208:211], v176 offset:32768
	ds_read_b128 v[212:215], v176 offset:33792
	ds_read_b128 v[216:219], v176 offset:34816
	ds_read_b128 v[220:223], v176 offset:35840
	ds_read_b128 v[224:227], v176 offset:36864
	ds_read_b128 v[228:231], v176 offset:37888
	ds_read_b128 v[232:235], v176 offset:38912
	ds_read_b128 v[236:239], v176 offset:39936
	global_load_lds_dwordx4 v[246:247], off
	v_lshl_add_u64 v[246:247], s[24:25], 0, v[142:143]
	s_mov_b32 m0, s35
	s_nop 0
	global_load_lds_dwordx4 v[246:247], off
	s_nop 0
	s_nop 0
	s_nop 0
	s_waitcnt vmcnt(8)
	s_waitcnt lgkmcnt(0)
	v_mfma_f32_16x16x32_bf16 v[126:129], v[130:133], v[208:211], v[126:129]
	v_mfma_f32_16x16x32_bf16 v[122:125], v[166:169], v[208:211], v[122:125]
	s_barrier
	s_setprio 1
	s_waitcnt lgkmcnt(0)
	v_mfma_f32_16x16x32_bf16 v[110:113], v[130:133], v[216:219], v[110:113]
	v_mfma_f32_16x16x32_bf16 v[106:109], v[166:169], v[216:219], v[106:109]
	v_mfma_f32_16x16x32_bf16 v[94:97], v[130:133], v[224:227], v[94:97]
	v_mfma_f32_16x16x32_bf16 v[90:93], v[166:169], v[224:227], v[90:93]
	v_mfma_f32_16x16x32_bf16 v[78:81], v[130:133], v[232:235], v[78:81]
	v_mfma_f32_16x16x32_bf16 v[74:77], v[166:169], v[232:235], v[74:77]
	v_mfma_f32_16x16x32_bf16 v[126:129], v[134:137], v[212:215], v[126:129]
	v_mfma_f32_16x16x32_bf16 v[122:125], v[170:173], v[212:215], v[122:125]
	v_mfma_f32_16x16x32_bf16 v[110:113], v[134:137], v[220:223], v[110:113]
	v_mfma_f32_16x16x32_bf16 v[106:109], v[170:173], v[220:223], v[106:109]
	v_mfma_f32_16x16x32_bf16 v[94:97], v[134:137], v[228:231], v[94:97]
	v_mfma_f32_16x16x32_bf16 v[90:93], v[170:173], v[228:231], v[90:93]
	v_mfma_f32_16x16x32_bf16 v[78:81], v[134:137], v[236:239], v[78:81]
	v_mfma_f32_16x16x32_bf16 v[74:77], v[170:173], v[236:239], v[74:77]
	s_setprio 0
	s_setprio 1
	v_mfma_f32_16x16x32_bf16 v[118:121], v[178:181], v[208:211], v[118:121]
	v_mfma_f32_16x16x32_bf16 v[114:117], v[186:189], v[208:211], v[114:117]
	v_mfma_f32_16x16x32_bf16 v[102:105], v[178:181], v[216:219], v[102:105]
	v_mfma_f32_16x16x32_bf16 v[98:101], v[186:189], v[216:219], v[98:101]
	v_mfma_f32_16x16x32_bf16 v[86:89], v[178:181], v[224:227], v[86:89]
	v_mfma_f32_16x16x32_bf16 v[82:85], v[186:189], v[224:227], v[82:85]
	v_mfma_f32_16x16x32_bf16 v[70:73], v[178:181], v[232:235], v[70:73]
	v_mfma_f32_16x16x32_bf16 v[66:69], v[186:189], v[232:235], v[66:69]
	v_mfma_f32_16x16x32_bf16 v[118:121], v[182:185], v[212:215], v[118:121]
	v_mfma_f32_16x16x32_bf16 v[114:117], v[190:193], v[212:215], v[114:117]
	v_mfma_f32_16x16x32_bf16 v[102:105], v[182:185], v[220:223], v[102:105]
	v_mfma_f32_16x16x32_bf16 v[98:101], v[190:193], v[220:223], v[98:101]
	v_mfma_f32_16x16x32_bf16 v[86:89], v[182:185], v[228:231], v[86:89]
	v_mfma_f32_16x16x32_bf16 v[82:85], v[190:193], v[228:231], v[82:85]
	v_mfma_f32_16x16x32_bf16 v[70:73], v[182:185], v[236:239], v[70:73]
	v_mfma_f32_16x16x32_bf16 v[66:69], v[190:193], v[236:239], v[66:69]
	s_setprio 0
	s_barrier
; #define PG8_STAGE(bufoff, gbase, voff) do { _Pragma("unroll") for (int _i = 0; _i < 2; ++_i) \
;         __builtin_amdgcn_global_load_lds((const unsigned*)((const char*)(gbase) + (voff)[_i]), (LAS unsigned*)(lds + (bufoff) + ldsw + _i * 8192), 16, 0, 0); } while (0)
; #define PG8_LDA(dst, b, h) do { _Pragma("unroll") for (int m = 0; m < 4; ++m) _Pragma("unroll") for (int k = 0; k < 2; ++k) dst[m][k] = *(const LAS bf16x8*)(lds + PG8_SA(b, h) + aoff + m * 2048 + k * 1024); } while (0)
; #define PG8_MMA(ai, bj, At, Bt) do { __builtin_amdgcn_s_setprio(1); _Pragma("unroll") for (int m = 0; m < 4; ++m) _Pragma("unroll") for (int n = 0; n < 2; ++n) _Pragma("unroll") for (int k = 0; k < 2; ++k) \
;         acc[ai][bj][m][n] = __builtin_amdgcn_mfma_f32_16x16x32_bf16(Bt[n][k], At[m][k], acc[ai][bj][m][n], 0, 0, 0); __builtin_amdgcn_s_setprio(0); } while (0)
; #define PG8_WAIT_V(n) asm volatile("s_waitcnt vmcnt(" #n ")" ::: "memory")
; #define PG8_WAIT_L(n) asm volatile("s_waitcnt lgkmcnt(" #n ")" ::: "memory")
; #define PG8_BAR __builtin_amdgcn_s_barrier()
; #define PG8_SCHED __builtin_amdgcn_sched_barrier(0)
; template <class Epi, class Sched>
; __device__ __forceinline__ void gemm_phase(LAS unsigned char* lds, const Gemm g, const Sched& S, const Epi& E) {
;     ...
;             PG8_LDA(At, 1, 1); PG8_STAGE(PG8_SB(1, 0), b3, voffB); PG8_STAGE(PG8_SB(1, 1), b3 + hstepB, voffB); PG8_STAGE(PG8_SA(1, 0), a3, voffA);
;             PG8_WAIT_V(8); PG8_WAIT_L(0); PG8_BAR; PG8_MMA(1, 0, At, B0); PG8_MMA(1, 1, At, B1); PG8_BAR; PG8_SCHED;
;         }
;         if (wr == 0) PG8_BAR;
	s_add_i32 s24, s46, s30
	v_lshl_add_u64 v[174:175], v[174:175], 0, s[56:57]
	s_mov_b32 m0, s24
	ds_read_b128 v[208:211], v176 offset:49152
	ds_read_b128 v[212:215], v176 offset:50176
	ds_read_b128 v[216:219], v176 offset:51200
	ds_read_b128 v[220:223], v176 offset:52224
	ds_read_b128 v[224:227], v176 offset:53248
	ds_read_b128 v[228:231], v176 offset:54272
	ds_read_b128 v[232:235], v176 offset:55296
	ds_read_b128 v[236:239], v176 offset:56320
	global_load_lds_dwordx4 v[174:175], off
	s_add_i32 m0, s24, 0x2000
	s_add_u32 s22, s22, 0x200080
	v_lshl_add_u64 v[174:175], v[240:241], 0, s[56:57]
	s_addc_u32 s23, s23, 0
	s_add_i32 s24, s47, s30
	global_load_lds_dwordx4 v[174:175], off
	v_lshl_add_u64 v[174:175], s[22:23], 0, v[140:141]
	s_mov_b32 m0, s24
	s_nop 0
	global_load_lds_dwordx4 v[174:175], off
	v_lshl_add_u64 v[174:175], s[22:23], 0, v[144:145]
	s_add_i32 m0, s24, 0x2000
	s_nop 0
	global_load_lds_dwordx4 v[174:175], off
	v_lshl_add_u64 v[174:175], v[242:243], 0, s[56:57]
	s_mov_b32 m0, s39
	s_nop 0
	global_load_lds_dwordx4 v[174:175], off
	v_lshl_add_u64 v[174:175], v[244:245], 0, s[56:57]
	s_mov_b32 m0, s40
	s_nop 0
	global_load_lds_dwordx4 v[174:175], off
	s_nop 0
	s_nop 0
	s_waitcnt vmcnt(8)
	s_waitcnt lgkmcnt(0)
	v_mfma_f32_16x16x32_bf16 v[62:65], v[130:133], v[208:211], v[62:65]
	v_mfma_f32_16x16x32_bf16 v[58:61], v[166:169], v[208:211], v[58:61]
	s_barrier
	s_setprio 1
	s_waitcnt lgkmcnt(0)
	v_mfma_f32_16x16x32_bf16 v[46:49], v[130:133], v[216:219], v[46:49]
	v_mfma_f32_16x16x32_bf16 v[42:45], v[166:169], v[216:219], v[42:45]
	v_mfma_f32_16x16x32_bf16 v[30:33], v[130:133], v[224:227], v[30:33]
	v_mfma_f32_16x16x32_bf16 v[26:29], v[166:169], v[224:227], v[26:29]
	v_mfma_f32_16x16x32_bf16 v[14:17], v[130:133], v[232:235], v[14:17]
	v_mfma_f32_16x16x32_bf16 v[10:13], v[166:169], v[232:235], v[10:13]
	v_mfma_f32_16x16x32_bf16 v[62:65], v[134:137], v[212:215], v[62:65]
	v_mfma_f32_16x16x32_bf16 v[58:61], v[170:173], v[212:215], v[58:61]
	v_mfma_f32_16x16x32_bf16 v[46:49], v[134:137], v[220:223], v[46:49]
	v_mfma_f32_16x16x32_bf16 v[42:45], v[170:173], v[220:223], v[42:45]
	v_mfma_f32_16x16x32_bf16 v[30:33], v[134:137], v[228:231], v[30:33]
	v_mfma_f32_16x16x32_bf16 v[26:29], v[170:173], v[228:231], v[26:29]
	v_mfma_f32_16x16x32_bf16 v[14:17], v[134:137], v[236:239], v[14:17]
	v_mfma_f32_16x16x32_bf16 v[10:13], v[170:173], v[236:239], v[10:13]
	s_setprio 0
	s_setprio 1
	v_mfma_f32_16x16x32_bf16 v[54:57], v[178:181], v[208:211], v[54:57]
	v_mfma_f32_16x16x32_bf16 v[50:53], v[186:189], v[208:211], v[50:53]
	v_mfma_f32_16x16x32_bf16 v[38:41], v[178:181], v[216:219], v[38:41]
	v_mfma_f32_16x16x32_bf16 v[34:37], v[186:189], v[216:219], v[34:37]
	v_mfma_f32_16x16x32_bf16 v[22:25], v[178:181], v[224:227], v[22:25]
	v_mfma_f32_16x16x32_bf16 v[18:21], v[186:189], v[224:227], v[18:21]
	v_mfma_f32_16x16x32_bf16 v[6:9], v[178:181], v[232:235], v[6:9]
	v_mfma_f32_16x16x32_bf16 v[2:5], v[186:189], v[232:235], v[2:5]
	v_mfma_f32_16x16x32_bf16 v[54:57], v[182:185], v[212:215], v[54:57]
	v_mfma_f32_16x16x32_bf16 v[50:53], v[190:193], v[212:215], v[50:53]
	v_mfma_f32_16x16x32_bf16 v[38:41], v[182:185], v[220:223], v[38:41]
	v_mfma_f32_16x16x32_bf16 v[34:37], v[190:193], v[220:223], v[34:37]
	v_mfma_f32_16x16x32_bf16 v[22:25], v[182:185], v[228:231], v[22:25]
	v_mfma_f32_16x16x32_bf16 v[18:21], v[190:193], v[228:231], v[18:21]
	v_mfma_f32_16x16x32_bf16 v[6:9], v[182:185], v[236:239], v[6:9]
	v_mfma_f32_16x16x32_bf16 v[2:5], v[190:193], v[236:239], v[2:5]
	s_setprio 0
	s_barrier
	s_add_i32 s45, s45, 2
	s_add_u32 s20, s20, 0x100
	s_addc_u32 s21, s21, 0
	s_add_u32 s43, s43, 0x100
	s_addc_u32 s44, s44, 0
	s_cmpk_gt_u32 s45, 0x7d
	s_cbranch_scc0 .LBB0_4314
	s_and_b64 vcc, exec, s[4:5]
	s_cbranch_vccz .LBB0_4317
	s_barrier

; #define PG8_STAGE(bufoff, gbase, voff) do { _Pragma("unroll") for (int _i = 0; _i < 2; ++_i) \
;         __builtin_amdgcn_global_load_lds((const unsigned*)((const char*)(gbase) + (voff)[_i]), (LAS unsigned*)(lds + (bufoff) + ldsw + _i * 8192), 16, 0, 0); } while (0)
; #define PG8_LDA(dst, b, h) do { _Pragma("unroll") for (int m = 0; m < 4; ++m) _Pragma("unroll") for (int k = 0; k < 2; ++k) dst[m][k] = *(const LAS bf16x8*)(lds + PG8_SA(b, h) + aoff + m * 2048 + k * 1024); } while (0)
; #define PG8_LDB(dst, b, h) do { _Pragma("unroll") for (int n = 0; n < 2; ++n) _Pragma("unroll") for (int k = 0; k < 2; ++k) dst[n][k] = *(const LAS bf16x8*)(lds + PG8_SB(b, h) + boff + n * 2048 + k * 1024); } while (0)
; #define PG8_MMA(ai, bj, At, Bt) do { __builtin_amdgcn_s_setprio(1); _Pragma("unroll") for (int m = 0; m < 4; ++m) _Pragma("unroll") for (int n = 0; n < 2; ++n) _Pragma("unroll") for (int k = 0; k < 2; ++k) \
;         acc[ai][bj][m][n] = __builtin_amdgcn_mfma_f32_16x16x32_bf16(Bt[n][k], At[m][k], acc[ai][bj][m][n], 0, 0, 0); __builtin_amdgcn_s_setprio(0); } while (0)
; #define PG8_WAIT_V(n) asm volatile("s_waitcnt vmcnt(" #n ")" ::: "memory")
; #define PG8_WAIT_L(n) asm volatile("s_waitcnt lgkmcnt(" #n ")" ::: "memory")
; #define PG8_BAR __builtin_amdgcn_s_barrier()
; #define PG8_SCHED __builtin_amdgcn_sched_barrier(0)
; template <class Epi, class Sched>
; __device__ __forceinline__ void gemm_phase(LAS unsigned char* lds, const Gemm g, const Sched& S, const Epi& E) {
;     ...
;             const bool last = (t == nt - 2);
;             const char* a1 = cA + (size_t)(t + 1) * kstep;
;             const char* a2 = last ? nA : cA + (size_t)(t + 2) * kstep; const char* b2 = last ? nB : cB + (size_t)(t + 2) * kstep;
;             const char* a3 = a2 + kstep; const char* b3 = b2 + kstep;
;             PG8_LDB(B0, 0, 0); PG8_LDB(B1, 0, 1); PG8_SCHED; PG8_LDA(At, 0, 0); PG8_STAGE(PG8_SA(1, 1), a1 + hstepA, voffA);
;             PG8_WAIT_V(8); PG8_WAIT_L(0); PG8_BAR; PG8_MMA(0, 0, At, B0); PG8_MMA(0, 1, At, B1); PG8_BAR; PG8_SCHED;
;             PG8_LDA(At, 0, 1); PG8_STAGE(PG8_SB(0, 0), b2, voffB); PG8_STAGE(PG8_SB(0, 1), b2 + hstepB, voffB); PG8_STAGE(PG8_SA(0, 0), a2, voffA);
;             PG8_WAIT_V(8); PG8_WAIT_L(0); PG8_BAR; PG8_MMA(1, 0, At, B0); PG8_MMA(1, 1, At, B1); PG8_BAR; PG8_SCHED;
.LBB0_4423:
	s_add_u32 s24, s22, 0xfff80080
	s_addc_u32 s25, s23, -1
	s_add_i32 s50, 0, 0x10000
	s_cmp_eq_u32 s49, 28
	s_cselect_b32 s27, s13, s25
	s_cselect_b32 s26, s19, s24
	s_cselect_b32 s25, s11, s47
	s_cselect_b32 s24, s21, s46
	s_add_i32 s52, 0, 0x14000
	v_add_u32_e32 v142, s50, v1
	v_add_u32_e32 v186, s52, v1
	ds_read_b128 v[130:133], v142
	ds_read_b128 v[134:137], v142 offset:1024
	ds_read_b128 v[138:141], v142 offset:2048
	ds_read_b128 v[142:145], v142 offset:3072
	ds_read_b128 v[174:177], v186
	ds_read_b128 v[178:181], v186 offset:1024
	ds_read_b128 v[182:185], v186 offset:2048
	ds_read_b128 v[186:189], v186 offset:3072
	v_lshl_add_u64 v[192:193], s[22:23], 0, v[170:171]
	s_add_i32 m0, s34, 0xc000
	ds_read_b128 v[208:211], v190
	ds_read_b128 v[212:215], v190 offset:1024
	ds_read_b128 v[216:219], v190 offset:2048
	ds_read_b128 v[220:223], v190 offset:3072
	ds_read_b128 v[224:227], v190 offset:4096
	ds_read_b128 v[228:231], v190 offset:5120
	ds_read_b128 v[232:235], v190 offset:6144
	ds_read_b128 v[236:239], v190 offset:7168
	global_load_lds_dwordx4 v[192:193], off
	v_lshl_add_u64 v[192:193], s[22:23], 0, v[172:173]
	s_add_i32 m0, s34, 0xe000
	s_nop 0
	global_load_lds_dwordx4 v[192:193], off
	s_nop 0
	s_nop 0
	s_waitcnt vmcnt(8)
	s_waitcnt lgkmcnt(0)
	v_mfma_f32_16x16x32_bf16 v[126:129], v[130:133], v[208:211], v[126:129]
	v_mfma_f32_16x16x32_bf16 v[122:125], v[138:141], v[208:211], v[122:125]
	s_barrier
	s_setprio 1
	s_waitcnt lgkmcnt(0)
	v_mfma_f32_16x16x32_bf16 v[110:113], v[130:133], v[216:219], v[110:113]
	v_mfma_f32_16x16x32_bf16 v[106:109], v[138:141], v[216:219], v[106:109]
	v_mfma_f32_16x16x32_bf16 v[94:97], v[130:133], v[224:227], v[94:97]
	v_mfma_f32_16x16x32_bf16 v[90:93], v[138:141], v[224:227], v[90:93]
	v_mfma_f32_16x16x32_bf16 v[78:81], v[130:133], v[232:235], v[78:81]
	v_mfma_f32_16x16x32_bf16 v[74:77], v[138:141], v[232:235], v[74:77]
	v_mfma_f32_16x16x32_bf16 v[126:129], v[134:137], v[212:215], v[126:129]
	v_mfma_f32_16x16x32_bf16 v[122:125], v[142:145], v[212:215], v[122:125]
	v_mfma_f32_16x16x32_bf16 v[110:113], v[134:137], v[220:223], v[110:113]
	v_mfma_f32_16x16x32_bf16 v[106:109], v[142:145], v[220:223], v[106:109]
	v_mfma_f32_16x16x32_bf16 v[94:97], v[134:137], v[228:231], v[94:97]
	v_mfma_f32_16x16x32_bf16 v[90:93], v[142:145], v[228:231], v[90:93]
	v_mfma_f32_16x16x32_bf16 v[78:81], v[134:137], v[236:239], v[78:81]
	v_mfma_f32_16x16x32_bf16 v[74:77], v[142:145], v[236:239], v[74:77]
	s_setprio 0
	s_setprio 1
	v_mfma_f32_16x16x32_bf16 v[118:121], v[174:177], v[208:211], v[118:121]
	v_mfma_f32_16x16x32_bf16 v[114:117], v[182:185], v[208:211], v[114:117]
	v_mfma_f32_16x16x32_bf16 v[102:105], v[174:177], v[216:219], v[102:105]
	v_mfma_f32_16x16x32_bf16 v[98:101], v[182:185], v[216:219], v[98:101]
	v_mfma_f32_16x16x32_bf16 v[86:89], v[174:177], v[224:227], v[86:89]
	v_mfma_f32_16x16x32_bf16 v[82:85], v[182:185], v[224:227], v[82:85]
	v_mfma_f32_16x16x32_bf16 v[70:73], v[174:177], v[232:235], v[70:73]
	v_mfma_f32_16x16x32_bf16 v[66:69], v[182:185], v[232:235], v[66:69]
	v_mfma_f32_16x16x32_bf16 v[118:121], v[178:181], v[212:215], v[118:121]
	v_mfma_f32_16x16x32_bf16 v[114:117], v[186:189], v[212:215], v[114:117]
	v_mfma_f32_16x16x32_bf16 v[102:105], v[178:181], v[220:223], v[102:105]
	v_mfma_f32_16x16x32_bf16 v[98:101], v[186:189], v[220:223], v[98:101]
	v_mfma_f32_16x16x32_bf16 v[86:89], v[178:181], v[228:231], v[86:89]
	v_mfma_f32_16x16x32_bf16 v[82:85], v[186:189], v[228:231], v[82:85]
	v_mfma_f32_16x16x32_bf16 v[70:73], v[178:181], v[236:239], v[70:73]
	v_mfma_f32_16x16x32_bf16 v[66:69], v[186:189], v[236:239], v[66:69]
	s_setprio 0
	s_barrier
	s_add_i32 s50, s50, s33
	v_lshl_add_u64 v[192:193], s[24:25], 0, v[164:165]
	s_mov_b32 m0, s50
	ds_read_b128 v[208:211], v190 offset:16384
	ds_read_b128 v[212:215], v190 offset:17408
	ds_read_b128 v[216:219], v190 offset:18432
	ds_read_b128 v[220:223], v190 offset:19456
	ds_read_b128 v[224:227], v190 offset:20480
	ds_read_b128 v[228:231], v190 offset:21504
	ds_read_b128 v[232:235], v190 offset:22528
	ds_read_b128 v[236:239], v190 offset:23552
	global_load_lds_dwordx4 v[192:193], off
	s_add_i32 m0, s50, 0x2000
	s_add_u32 s50, s24, 0x80000
	v_lshl_add_u64 v[240:241], s[24:25], 0, v[168:169]
	s_addc_u32 s51, s25, 0
	s_add_i32 s52, s52, s33
	global_load_lds_dwordx4 v[240:241], off
	v_lshl_add_u64 v[242:243], s[50:51], 0, v[164:165]
	s_mov_b32 m0, s52
	v_lshl_add_u64 v[244:245], s[26:27], 0, v[166:167]
	global_load_lds_dwordx4 v[242:243], off
	v_lshl_add_u64 v[242:243], s[50:51], 0, v[168:169]
	s_add_i32 m0, s52, 0x2000
	s_nop 0
	global_load_lds_dwordx4 v[242:243], off
	v_lshl_add_u64 v[242:243], s[26:27], 0, v[162:163]
	s_mov_b32 m0, s34
	s_nop 0
	global_load_lds_dwordx4 v[242:243], off
	s_mov_b32 m0, s35
	s_nop 0
	global_load_lds_dwordx4 v[244:245], off
	s_nop 0
	s_nop 0
	s_nop 0
	s_waitcnt vmcnt(8)
	s_waitcnt lgkmcnt(0)
	v_mfma_f32_16x16x32_bf16 v[62:65], v[130:133], v[208:211], v[62:65]
	v_mfma_f32_16x16x32_bf16 v[58:61], v[138:141], v[208:211], v[58:61]
	s_barrier
; #define PG8_STAGE(bufoff, gbase, voff) do { _Pragma("unroll") for (int _i = 0; _i < 2; ++_i) \
;         __builtin_amdgcn_global_load_lds((const unsigned*)((const char*)(gbase) + (voff)[_i]), (LAS unsigned*)(lds + (bufoff) + ldsw + _i * 8192), 16, 0, 0); } while (0)
; #define PG8_LDA(dst, b, h) do { _Pragma("unroll") for (int m = 0; m < 4; ++m) _Pragma("unroll") for (int k = 0; k < 2; ++k) dst[m][k] = *(const LAS bf16x8*)(lds + PG8_SA(b, h) + aoff + m * 2048 + k * 1024); } while (0)
; #define PG8_LDB(dst, b, h) do { _Pragma("unroll") for (int n = 0; n < 2; ++n) _Pragma("unroll") for (int k = 0; k < 2; ++k) dst[n][k] = *(const LAS bf16x8*)(lds + PG8_SB(b, h) + boff + n * 2048 + k * 1024); } while (0)
; #define PG8_MMA(ai, bj, At, Bt) do { __builtin_amdgcn_s_setprio(1); _Pragma("unroll") for (int m = 0; m < 4; ++m) _Pragma("unroll") for (int n = 0; n < 2; ++n) _Pragma("unroll") for (int k = 0; k < 2; ++k) \
;         acc[ai][bj][m][n] = __builtin_amdgcn_mfma_f32_16x16x32_bf16(Bt[n][k], At[m][k], acc[ai][bj][m][n], 0, 0, 0); __builtin_amdgcn_s_setprio(0); } while (0)
; #define PG8_WAIT_V(n) asm volatile("s_waitcnt vmcnt(" #n ")" ::: "memory")
; #define PG8_WAIT_L(n) asm volatile("s_waitcnt lgkmcnt(" #n ")" ::: "memory")
; #define PG8_BAR __builtin_amdgcn_s_barrier()
; #define PG8_SCHED __builtin_amdgcn_sched_barrier(0)
; template <class Epi, class Sched>
; __device__ __forceinline__ void gemm_phase(LAS unsigned char* lds, const Gemm g, const Sched& S, const Epi& E) {
;     ...
;             PG8_WAIT_V(8); PG8_WAIT_L(0); PG8_BAR; PG8_MMA(1, 0, At, B0); PG8_MMA(1, 1, At, B1); PG8_BAR; PG8_SCHED;
;             PG8_LDB(B0, 1, 0); PG8_LDB(B1, 1, 1); PG8_SCHED; PG8_LDA(At, 1, 0); PG8_STAGE(PG8_SA(0, 1), a2 + hstepA, voffA);
;             PG8_WAIT_V(8); PG8_WAIT_L(0); PG8_BAR; PG8_MMA(0, 0, At, B0); PG8_MMA(0, 1, At, B1); PG8_BAR; PG8_SCHED;
	s_setprio 1
	s_waitcnt lgkmcnt(0)
	v_mfma_f32_16x16x32_bf16 v[46:49], v[130:133], v[216:219], v[46:49]
	v_mfma_f32_16x16x32_bf16 v[42:45], v[138:141], v[216:219], v[42:45]
	v_mfma_f32_16x16x32_bf16 v[30:33], v[130:133], v[224:227], v[30:33]
	v_mfma_f32_16x16x32_bf16 v[26:29], v[138:141], v[224:227], v[26:29]
	v_mfma_f32_16x16x32_bf16 v[14:17], v[130:133], v[232:235], v[14:17]
	v_mfma_f32_16x16x32_bf16 v[10:13], v[138:141], v[232:235], v[10:13]
	v_mfma_f32_16x16x32_bf16 v[62:65], v[134:137], v[212:215], v[62:65]
	v_mfma_f32_16x16x32_bf16 v[58:61], v[142:145], v[212:215], v[58:61]
	v_mfma_f32_16x16x32_bf16 v[46:49], v[134:137], v[220:223], v[46:49]
	v_mfma_f32_16x16x32_bf16 v[42:45], v[142:145], v[220:223], v[42:45]
	v_mfma_f32_16x16x32_bf16 v[30:33], v[134:137], v[228:231], v[30:33]
	v_mfma_f32_16x16x32_bf16 v[26:29], v[142:145], v[228:231], v[26:29]
	v_mfma_f32_16x16x32_bf16 v[14:17], v[134:137], v[236:239], v[14:17]
	v_mfma_f32_16x16x32_bf16 v[10:13], v[142:145], v[236:239], v[10:13]
	s_setprio 0
	s_setprio 1
	v_mfma_f32_16x16x32_bf16 v[54:57], v[174:177], v[208:211], v[54:57]
	v_mfma_f32_16x16x32_bf16 v[50:53], v[182:185], v[208:211], v[50:53]
	v_mfma_f32_16x16x32_bf16 v[38:41], v[174:177], v[216:219], v[38:41]
	v_mfma_f32_16x16x32_bf16 v[34:37], v[182:185], v[216:219], v[34:37]
	v_mfma_f32_16x16x32_bf16 v[22:25], v[174:177], v[224:227], v[22:25]
	v_mfma_f32_16x16x32_bf16 v[18:21], v[182:185], v[224:227], v[18:21]
	v_mfma_f32_16x16x32_bf16 v[6:9], v[174:177], v[232:235], v[6:9]
	v_mfma_f32_16x16x32_bf16 v[2:5], v[182:185], v[232:235], v[2:5]
	v_mfma_f32_16x16x32_bf16 v[54:57], v[178:181], v[212:215], v[54:57]
	v_mfma_f32_16x16x32_bf16 v[50:53], v[186:189], v[212:215], v[50:53]
	v_mfma_f32_16x16x32_bf16 v[38:41], v[178:181], v[220:223], v[38:41]
	v_mfma_f32_16x16x32_bf16 v[34:37], v[186:189], v[220:223], v[34:37]
	v_mfma_f32_16x16x32_bf16 v[22:25], v[178:181], v[228:231], v[22:25]
	v_mfma_f32_16x16x32_bf16 v[18:21], v[186:189], v[228:231], v[18:21]
	v_mfma_f32_16x16x32_bf16 v[6:9], v[178:181], v[236:239], v[6:9]
	v_mfma_f32_16x16x32_bf16 v[2:5], v[186:189], v[236:239], v[2:5]
	s_setprio 0
	s_barrier
	s_add_i32 s50, 0, 0x18000
	s_add_i32 s51, 0, 0x1c000
	v_add_u32_e32 v142, s50, v1
	v_add_u32_e32 v186, s51, v1
	ds_read_b128 v[130:133], v142
	ds_read_b128 v[134:137], v142 offset:1024
	ds_read_b128 v[138:141], v142 offset:2048
	ds_read_b128 v[142:145], v142 offset:3072
	ds_read_b128 v[174:177], v186
	ds_read_b128 v[178:181], v186 offset:1024
	ds_read_b128 v[182:185], v186 offset:2048
	ds_read_b128 v[186:189], v186 offset:3072
	s_add_u32 s26, s26, 0x80000
	s_addc_u32 s27, s27, 0
	s_mov_b32 m0, s36
	v_lshl_add_u64 v[246:247], s[26:27], 0, v[162:163]
	ds_read_b128 v[208:211], v190 offset:32768
	ds_read_b128 v[212:215], v190 offset:33792
	ds_read_b128 v[216:219], v190 offset:34816
	ds_read_b128 v[220:223], v190 offset:35840
	ds_read_b128 v[224:227], v190 offset:36864
	ds_read_b128 v[228:231], v190 offset:37888
	ds_read_b128 v[232:235], v190 offset:38912
	ds_read_b128 v[236:239], v190 offset:39936
	global_load_lds_dwordx4 v[246:247], off
	v_lshl_add_u64 v[246:247], s[26:27], 0, v[166:167]
	s_mov_b32 m0, s37
	s_nop 0
	global_load_lds_dwordx4 v[246:247], off
	s_nop 0
	s_nop 0
	s_nop 0
	s_waitcnt vmcnt(8)
	s_waitcnt lgkmcnt(0)
	v_mfma_f32_16x16x32_bf16 v[126:129], v[130:133], v[208:211], v[126:129]
	v_mfma_f32_16x16x32_bf16 v[122:125], v[138:141], v[208:211], v[122:125]
	s_barrier
	s_setprio 1
	s_waitcnt lgkmcnt(0)
	v_mfma_f32_16x16x32_bf16 v[110:113], v[130:133], v[216:219], v[110:113]
	v_mfma_f32_16x16x32_bf16 v[106:109], v[138:141], v[216:219], v[106:109]
	v_mfma_f32_16x16x32_bf16 v[94:97], v[130:133], v[224:227], v[94:97]
	v_mfma_f32_16x16x32_bf16 v[90:93], v[138:141], v[224:227], v[90:93]
	v_mfma_f32_16x16x32_bf16 v[78:81], v[130:133], v[232:235], v[78:81]
	v_mfma_f32_16x16x32_bf16 v[74:77], v[138:141], v[232:235], v[74:77]
	v_mfma_f32_16x16x32_bf16 v[126:129], v[134:137], v[212:215], v[126:129]
	v_mfma_f32_16x16x32_bf16 v[122:125], v[142:145], v[212:215], v[122:125]
	v_mfma_f32_16x16x32_bf16 v[110:113], v[134:137], v[220:223], v[110:113]
	v_mfma_f32_16x16x32_bf16 v[106:109], v[142:145], v[220:223], v[106:109]
	v_mfma_f32_16x16x32_bf16 v[94:97], v[134:137], v[228:231], v[94:97]
	v_mfma_f32_16x16x32_bf16 v[90:93], v[142:145], v[228:231], v[90:93]
	v_mfma_f32_16x16x32_bf16 v[78:81], v[134:137], v[236:239], v[78:81]
	v_mfma_f32_16x16x32_bf16 v[74:77], v[142:145], v[236:239], v[74:77]
	s_setprio 0
	s_setprio 1
	v_mfma_f32_16x16x32_bf16 v[118:121], v[174:177], v[208:211], v[118:121]
	v_mfma_f32_16x16x32_bf16 v[114:117], v[182:185], v[208:211], v[114:117]
	v_mfma_f32_16x16x32_bf16 v[102:105], v[174:177], v[216:219], v[102:105]
	v_mfma_f32_16x16x32_bf16 v[98:101], v[182:185], v[216:219], v[98:101]
	v_mfma_f32_16x16x32_bf16 v[86:89], v[174:177], v[224:227], v[86:89]
	v_mfma_f32_16x16x32_bf16 v[82:85], v[182:185], v[224:227], v[82:85]
	v_mfma_f32_16x16x32_bf16 v[70:73], v[174:177], v[232:235], v[70:73]
	v_mfma_f32_16x16x32_bf16 v[66:69], v[182:185], v[232:235], v[66:69]
	v_mfma_f32_16x16x32_bf16 v[118:121], v[178:181], v[212:215], v[118:121]
	v_mfma_f32_16x16x32_bf16 v[114:117], v[186:189], v[212:215], v[114:117]
	v_mfma_f32_16x16x32_bf16 v[102:105], v[178:181], v[220:223], v[102:105]
	v_mfma_f32_16x16x32_bf16 v[98:101], v[186:189], v[220:223], v[98:101]
	v_mfma_f32_16x16x32_bf16 v[86:89], v[178:181], v[228:231], v[86:89]
	v_mfma_f32_16x16x32_bf16 v[82:85], v[186:189], v[228:231], v[82:85]
	v_mfma_f32_16x16x32_bf16 v[70:73], v[178:181], v[236:239], v[70:73]
	v_mfma_f32_16x16x32_bf16 v[66:69], v[186:189], v[236:239], v[66:69]
	s_setprio 0
	s_barrier
; #define PG8_STAGE(bufoff, gbase, voff) do { _Pragma("unroll") for (int _i = 0; _i < 2; ++_i) \
;         __builtin_amdgcn_global_load_lds((const unsigned*)((const char*)(gbase) + (voff)[_i]), (LAS unsigned*)(lds + (bufoff) + ldsw + _i * 8192), 16, 0, 0); } while (0)
; #define PG8_LDA(dst, b, h) do { _Pragma("unroll") for (int m = 0; m < 4; ++m) _Pragma("unroll") for (int k = 0; k < 2; ++k) dst[m][k] = *(const LAS bf16x8*)(lds + PG8_SA(b, h) + aoff + m * 2048 + k * 1024); } while (0)
; #define PG8_MMA(ai, bj, At, Bt) do { __builtin_amdgcn_s_setprio(1); _Pragma("unroll") for (int m = 0; m < 4; ++m) _Pragma("unroll") for (int n = 0; n < 2; ++n) _Pragma("unroll") for (int k = 0; k < 2; ++k) \
;         acc[ai][bj][m][n] = __builtin_amdgcn_mfma_f32_16x16x32_bf16(Bt[n][k], At[m][k], acc[ai][bj][m][n], 0, 0, 0); __builtin_amdgcn_s_setprio(0); } while (0)
; #define PG8_WAIT_V(n) asm volatile("s_waitcnt vmcnt(" #n ")" ::: "memory")
; #define PG8_WAIT_L(n) asm volatile("s_waitcnt lgkmcnt(" #n ")" ::: "memory")
; #define PG8_BAR __builtin_amdgcn_s_barrier()
; #define PG8_SCHED __builtin_amdgcn_sched_barrier(0)
; template <class Epi, class Sched>
; __device__ __forceinline__ void gemm_phase(LAS unsigned char* lds, const Gemm g, const Sched& S, const Epi& E) {
;     ...
;             PG8_LDA(At, 1, 1); PG8_STAGE(PG8_SB(1, 0), b3, voffB); PG8_STAGE(PG8_SB(1, 1), b3 + hstepB, voffB); PG8_STAGE(PG8_SA(1, 0), a3, voffA);
;             PG8_WAIT_V(8); PG8_WAIT_L(0); PG8_BAR; PG8_MMA(1, 0, At, B0); PG8_MMA(1, 1, At, B1); PG8_BAR; PG8_SCHED;
;         }
;         if (wr == 0) PG8_BAR;
	s_add_i32 s26, s50, s33
	v_lshl_add_u64 v[192:193], v[192:193], 0, s[56:57]
	s_mov_b32 m0, s26
	ds_read_b128 v[208:211], v190 offset:49152
	ds_read_b128 v[212:215], v190 offset:50176
	ds_read_b128 v[216:219], v190 offset:51200
	ds_read_b128 v[220:223], v190 offset:52224
	ds_read_b128 v[224:227], v190 offset:53248
	ds_read_b128 v[228:231], v190 offset:54272
	ds_read_b128 v[232:235], v190 offset:55296
	ds_read_b128 v[236:239], v190 offset:56320
	global_load_lds_dwordx4 v[192:193], off
	s_add_i32 m0, s26, 0x2000
	s_add_u32 s24, s24, 0x80080
	v_lshl_add_u64 v[192:193], v[240:241], 0, s[56:57]
	s_addc_u32 s25, s25, 0
	s_add_i32 s26, s51, s33
	global_load_lds_dwordx4 v[192:193], off
	v_lshl_add_u64 v[192:193], s[24:25], 0, v[164:165]
	s_mov_b32 m0, s26
	s_nop 0
	global_load_lds_dwordx4 v[192:193], off
	v_lshl_add_u64 v[192:193], s[24:25], 0, v[168:169]
	s_add_i32 m0, s26, 0x2000
	s_nop 0
	global_load_lds_dwordx4 v[192:193], off
	v_lshl_add_u64 v[192:193], v[242:243], 0, s[56:57]
	s_mov_b32 m0, s41
	s_nop 0
	global_load_lds_dwordx4 v[192:193], off
	v_lshl_add_u64 v[192:193], v[244:245], 0, s[56:57]
	s_mov_b32 m0, s42
	s_nop 0
	global_load_lds_dwordx4 v[192:193], off
	s_nop 0
	s_nop 0
	s_waitcnt vmcnt(8)
	s_waitcnt lgkmcnt(0)
	v_mfma_f32_16x16x32_bf16 v[62:65], v[130:133], v[208:211], v[62:65]
	v_mfma_f32_16x16x32_bf16 v[58:61], v[138:141], v[208:211], v[58:61]
	s_barrier
	s_setprio 1
	s_waitcnt lgkmcnt(0)
	v_mfma_f32_16x16x32_bf16 v[46:49], v[130:133], v[216:219], v[46:49]
	v_mfma_f32_16x16x32_bf16 v[42:45], v[138:141], v[216:219], v[42:45]
	v_mfma_f32_16x16x32_bf16 v[30:33], v[130:133], v[224:227], v[30:33]
	v_mfma_f32_16x16x32_bf16 v[26:29], v[138:141], v[224:227], v[26:29]
	v_mfma_f32_16x16x32_bf16 v[14:17], v[130:133], v[232:235], v[14:17]
	v_mfma_f32_16x16x32_bf16 v[10:13], v[138:141], v[232:235], v[10:13]
	v_mfma_f32_16x16x32_bf16 v[62:65], v[134:137], v[212:215], v[62:65]
	v_mfma_f32_16x16x32_bf16 v[58:61], v[142:145], v[212:215], v[58:61]
	v_mfma_f32_16x16x32_bf16 v[46:49], v[134:137], v[220:223], v[46:49]
	v_mfma_f32_16x16x32_bf16 v[42:45], v[142:145], v[220:223], v[42:45]
	v_mfma_f32_16x16x32_bf16 v[30:33], v[134:137], v[228:231], v[30:33]
	v_mfma_f32_16x16x32_bf16 v[26:29], v[142:145], v[228:231], v[26:29]
	v_mfma_f32_16x16x32_bf16 v[14:17], v[134:137], v[236:239], v[14:17]
	v_mfma_f32_16x16x32_bf16 v[10:13], v[142:145], v[236:239], v[10:13]
	s_setprio 0
	s_setprio 1
	v_mfma_f32_16x16x32_bf16 v[54:57], v[174:177], v[208:211], v[54:57]
	v_mfma_f32_16x16x32_bf16 v[50:53], v[182:185], v[208:211], v[50:53]
	v_mfma_f32_16x16x32_bf16 v[38:41], v[174:177], v[216:219], v[38:41]
	v_mfma_f32_16x16x32_bf16 v[34:37], v[182:185], v[216:219], v[34:37]
	v_mfma_f32_16x16x32_bf16 v[22:25], v[174:177], v[224:227], v[22:25]
	v_mfma_f32_16x16x32_bf16 v[18:21], v[182:185], v[224:227], v[18:21]
	v_mfma_f32_16x16x32_bf16 v[6:9], v[174:177], v[232:235], v[6:9]
	v_mfma_f32_16x16x32_bf16 v[2:5], v[182:185], v[232:235], v[2:5]
	v_mfma_f32_16x16x32_bf16 v[54:57], v[178:181], v[212:215], v[54:57]
	v_mfma_f32_16x16x32_bf16 v[50:53], v[186:189], v[212:215], v[50:53]
	v_mfma_f32_16x16x32_bf16 v[38:41], v[178:181], v[220:223], v[38:41]
	v_mfma_f32_16x16x32_bf16 v[34:37], v[186:189], v[220:223], v[34:37]
	v_mfma_f32_16x16x32_bf16 v[22:25], v[178:181], v[228:231], v[22:25]
	v_mfma_f32_16x16x32_bf16 v[18:21], v[186:189], v[228:231], v[18:21]
	v_mfma_f32_16x16x32_bf16 v[6:9], v[178:181], v[236:239], v[6:9]
	v_mfma_f32_16x16x32_bf16 v[2:5], v[186:189], v[236:239], v[2:5]
	s_setprio 0
	s_barrier
	s_add_i32 s49, s49, 2
	s_add_u32 s22, s22, 0x100
	s_addc_u32 s23, s23, 0
	s_add_u32 s46, s46, 0x100
	s_addc_u32 s47, s47, 0
	s_cmp_gt_u32 s49, 29
	s_cbranch_scc0 .LBB0_4423
	s_and_b64 vcc, exec, s[6:7]
	s_cbranch_vccz .LBB0_4426
	s_barrier
